# GEMM MMA segments as pure MFMA runs (setprio before the barrier, no-op lgkmcnt waits and mid-segment priority flips removed) + attention compare above the barrier
# speedup vs baseline: 1.0043x; 1.0024x over previous
; #define PG8_LDA(dst, b, h) do { _Pragma("unroll") for (int m = 0; m < 4; ++m) _Pragma("unroll") for (int k = 0; k < 2; ++k) dst[m][k] = *(const LAS bf16x8*)(lds + PG8_SA(b, h) + aoff + m * 2048 + k * 1024); } while (0)
; #define PG8_LDB(dst, b, h) do { _Pragma("unroll") for (int n = 0; n < 2; ++n) _Pragma("unroll") for (int k = 0; k < 2; ++k) dst[n][k] = *(const LAS bf16x8*)(lds + PG8_SB(b, h) + boff + n * 2048 + k * 1024); } while (0)
; #define PG8_MMA(ai, bj, At, Bt) do { __builtin_amdgcn_s_setprio(1); _Pragma("unroll") for (int m = 0; m < 4; ++m) _Pragma("unroll") for (int n = 0; n < 2; ++n) _Pragma("unroll") for (int k = 0; k < 2; ++k) \
;         acc[ai][bj][m][n] = __builtin_amdgcn_mfma_f32_16x16x32_bf16(Bt[n][k], At[m][k], acc[ai][bj][m][n], 0, 0, 0); __builtin_amdgcn_s_setprio(0); } while (0)
; template <class Epi, class Addr, bool ALIGN_EPI = true, class Order = StaticOrder>
; __device__ __forceinline__ void gemm_phase(LAS unsigned char* lds, const Gemm g, const Order& S, const Epi& E, const int wid) {
;     ...
;             const bool last = (t == nt - 2);
;             const char* a1 = cA + (size_t)(t + 1) * kstep;
;             const char* a2 = last ? nA : cA + (size_t)(t + 2) * kstep; const char* b2 = last ? nB : cB + (size_t)(t + 2) * kstep;
;             const char* a3 = a2 + kstep; const char* b3 = b2 + kstep;
;             PG8_LDB(B0, 0, 0); PG8_LDB(B1, 0, 1); PG8_SCHED; PG8_LDA(At, 0, 0); PG8_STAGE(PG8_SA(1, 1), a1 + hstepA, voffA);
;             PG8_WAIT_V(8); PG8_WAIT_L(0); PG8_BAR; PG8_MMA(0, 0, At, B0); PG8_MMA(0, 1, At, B1); PG8_BAR; PG8_SCHED;
;             PG8_LDA(At, 0, 1); PG8_STAGE(PG8_SB(0, 0), b2, voffB); PG8_STAGE(PG8_SB(0, 1), b2 + hstepB, voffB); PG8_STAGE(PG8_SA(0, 0), a2, voffA);
;             PG8_WAIT_V(8); PG8_WAIT_L(0); PG8_BAR; PG8_MMA(1, 0, At, B0); PG8_MMA(1, 1, At, B1); PG8_BAR; PG8_SCHED;
;             PG8_LDB(B0, 1, 0); PG8_LDB(B1, 1, 1); PG8_SCHED; PG8_LDA(At, 1, 0); PG8_STAGE(PG8_SA(0, 1), a2 + hstepA, voffA);
;             PG8_WAIT_V(8); PG8_WAIT_L(0); PG8_BAR; PG8_MMA(0, 0, At, B0); PG8_MMA(0, 1, At, B1); PG8_BAR; PG8_SCHED;
;             PG8_LDA(At, 1, 1); PG8_STAGE(PG8_SB(1, 0), b3, voffB); PG8_STAGE(PG8_SB(1, 1), b3 + hstepB, voffB); PG8_STAGE(PG8_SA(1, 0), a3, voffA);
;             PG8_WAIT_V(8); PG8_WAIT_L(0); PG8_BAR; PG8_MMA(1, 0, At, B0); PG8_MMA(1, 1, At, B1); PG8_BAR; PG8_SCHED;
.LBB0_123:
	ds_read_b128 v[128:131], v169
	ds_read_b128 v[132:135], v169 offset:1024
	ds_read_b128 v[152:155], v169 offset:2048
	ds_read_b128 v[156:159], v169 offset:3072
	ds_read_b128 v[160:163], v170
	ds_read_b128 v[176:179], v170 offset:1024
	ds_read_b128 v[180:183], v170 offset:2048
	ds_read_b128 v[184:187], v170 offset:3072
	s_add_u32 s46, s8, 0x100
	s_addc_u32 s47, s9, 0
	s_cmp_eq_u32 s80, 60
	s_cselect_b32 s52, s27, s46
	s_cselect_b32 s53, s21, s47
	s_cselect_b32 s50, s39, s78
	s_cselect_b32 s51, s17, s79
	s_add_u32 s48, s52, 0x80
	s_addc_u32 s49, s53, 0
	ds_read_b128 v[188:191], v171
	ds_read_b128 v[192:195], v171 offset:1024
	ds_read_b128 v[196:199], v171 offset:2048
	ds_read_b128 v[200:203], v171 offset:3072
	ds_read_b128 v[204:207], v171 offset:4096
	ds_read_b128 v[208:211], v171 offset:5120
	ds_read_b128 v[212:215], v171 offset:6144
	ds_read_b128 v[216:219], v171 offset:7168
	s_add_u32 s8, s8, 0x100080
	s_addc_u32 s9, s9, 0
	s_mov_b32 s18, m0
	s_mov_b32 m0, s66
	s_nop 0
	global_load_lds_dwordx4 v164, s[8:9]
	s_mov_b32 m0, s67
	s_nop 0
	global_load_lds_dwordx4 v166, s[8:9]
	s_mov_b32 m0, s18
	s_waitcnt vmcnt(8)
	s_waitcnt lgkmcnt(0)
	s_setprio 1
	s_barrier
	v_mfma_f32_16x16x32_bf16 v[124:127], v[128:131], v[188:191], v[124:127]
	v_mfma_f32_16x16x32_bf16 v[120:123], v[152:155], v[188:191], v[120:123]
	v_mfma_f32_16x16x32_bf16 v[108:111], v[128:131], v[196:199], v[108:111]
	v_mfma_f32_16x16x32_bf16 v[104:107], v[152:155], v[196:199], v[104:107]
	v_mfma_f32_16x16x32_bf16 v[92:95], v[128:131], v[204:207], v[92:95]
	v_mfma_f32_16x16x32_bf16 v[88:91], v[152:155], v[204:207], v[88:91]
	v_mfma_f32_16x16x32_bf16 v[76:79], v[128:131], v[212:215], v[76:79]
	v_mfma_f32_16x16x32_bf16 v[72:75], v[152:155], v[212:215], v[72:75]
	v_mfma_f32_16x16x32_bf16 v[124:127], v[132:135], v[192:195], v[124:127]
	v_mfma_f32_16x16x32_bf16 v[120:123], v[156:159], v[192:195], v[120:123]
	v_mfma_f32_16x16x32_bf16 v[108:111], v[132:135], v[200:203], v[108:111]
	v_mfma_f32_16x16x32_bf16 v[104:107], v[156:159], v[200:203], v[104:107]
	v_mfma_f32_16x16x32_bf16 v[92:95], v[132:135], v[208:211], v[92:95]
	v_mfma_f32_16x16x32_bf16 v[88:91], v[156:159], v[208:211], v[88:91]
	v_mfma_f32_16x16x32_bf16 v[76:79], v[132:135], v[216:219], v[76:79]
	v_mfma_f32_16x16x32_bf16 v[72:75], v[156:159], v[216:219], v[72:75]
	v_mfma_f32_16x16x32_bf16 v[116:119], v[160:163], v[188:191], v[116:119]
	v_mfma_f32_16x16x32_bf16 v[112:115], v[180:183], v[188:191], v[112:115]
	v_mfma_f32_16x16x32_bf16 v[100:103], v[160:163], v[196:199], v[100:103]
	v_mfma_f32_16x16x32_bf16 v[96:99], v[180:183], v[196:199], v[96:99]
	v_mfma_f32_16x16x32_bf16 v[84:87], v[160:163], v[204:207], v[84:87]
	v_mfma_f32_16x16x32_bf16 v[80:83], v[180:183], v[204:207], v[80:83]
	v_mfma_f32_16x16x32_bf16 v[68:71], v[160:163], v[212:215], v[68:71]
	v_mfma_f32_16x16x32_bf16 v[64:67], v[180:183], v[212:215], v[64:67]
	v_mfma_f32_16x16x32_bf16 v[116:119], v[176:179], v[192:195], v[116:119]
	v_mfma_f32_16x16x32_bf16 v[112:115], v[184:187], v[192:195], v[112:115]
	v_mfma_f32_16x16x32_bf16 v[100:103], v[176:179], v[200:203], v[100:103]
	v_mfma_f32_16x16x32_bf16 v[96:99], v[184:187], v[200:203], v[96:99]
	v_mfma_f32_16x16x32_bf16 v[84:87], v[176:179], v[208:211], v[84:87]
	v_mfma_f32_16x16x32_bf16 v[80:83], v[184:187], v[208:211], v[80:83]
	v_mfma_f32_16x16x32_bf16 v[68:71], v[176:179], v[216:219], v[68:71]
	v_mfma_f32_16x16x32_bf16 v[64:67], v[184:187], v[216:219], v[64:67]
	s_barrier
	s_setprio 0
	ds_read_b128 v[188:191], v171 offset:16384
	ds_read_b128 v[192:195], v171 offset:17408
	ds_read_b128 v[196:199], v171 offset:18432
	ds_read_b128 v[200:203], v171 offset:19456
	ds_read_b128 v[204:207], v171 offset:20480
	ds_read_b128 v[208:211], v171 offset:21504
	ds_read_b128 v[212:215], v171 offset:22528
	ds_read_b128 v[216:219], v171 offset:23552
	s_mov_b32 s8, m0
	s_mov_b32 m0, s43
	s_nop 0
	global_load_lds_dwordx4 v165, s[50:51]
	s_mov_b32 m0, s54
	s_nop 0
	global_load_lds_dwordx4 v167, s[50:51]
	s_mov_b32 m0, s8
	s_add_u32 s8, s50, 0x100000
	s_addc_u32 s9, s51, 0
	s_mov_b32 s18, m0
	s_mov_b32 m0, s55
	s_nop 0
	global_load_lds_dwordx4 v165, s[8:9]
	s_mov_b32 m0, s56
	s_nop 0
	global_load_lds_dwordx4 v167, s[8:9]
	s_mov_b32 m0, s18
	s_mov_b32 s8, m0
	s_mov_b32 m0, s41
	s_nop 0
	global_load_lds_dwordx4 v164, s[52:53]
	s_mov_b32 m0, s57
	s_nop 0
	global_load_lds_dwordx4 v166, s[52:53]
	s_mov_b32 m0, s8
	s_waitcnt vmcnt(8)
	s_waitcnt lgkmcnt(0)
	s_setprio 1
	s_barrier
	v_mfma_f32_16x16x32_bf16 v[60:63], v[128:131], v[188:191], v[60:63]
	v_mfma_f32_16x16x32_bf16 v[56:59], v[152:155], v[188:191], v[56:59]
	v_mfma_f32_16x16x32_bf16 v[44:47], v[128:131], v[196:199], v[44:47]
	v_mfma_f32_16x16x32_bf16 v[40:43], v[152:155], v[196:199], v[40:43]
	v_mfma_f32_16x16x32_bf16 v[28:31], v[128:131], v[204:207], v[28:31]
	v_mfma_f32_16x16x32_bf16 v[24:27], v[152:155], v[204:207], v[24:27]
	v_mfma_f32_16x16x32_bf16 v[12:15], v[128:131], v[212:215], v[12:15]
	v_mfma_f32_16x16x32_bf16 v[8:11], v[152:155], v[212:215], v[8:11]
	v_mfma_f32_16x16x32_bf16 v[60:63], v[132:135], v[192:195], v[60:63]
	v_mfma_f32_16x16x32_bf16 v[56:59], v[156:159], v[192:195], v[56:59]
	v_mfma_f32_16x16x32_bf16 v[44:47], v[132:135], v[200:203], v[44:47]
	v_mfma_f32_16x16x32_bf16 v[40:43], v[156:159], v[200:203], v[40:43]
	v_mfma_f32_16x16x32_bf16 v[28:31], v[132:135], v[208:211], v[28:31]
	v_mfma_f32_16x16x32_bf16 v[24:27], v[156:159], v[208:211], v[24:27]
	v_mfma_f32_16x16x32_bf16 v[12:15], v[132:135], v[216:219], v[12:15]
	v_mfma_f32_16x16x32_bf16 v[8:11], v[156:159], v[216:219], v[8:11]
	v_mfma_f32_16x16x32_bf16 v[52:55], v[160:163], v[188:191], v[52:55]
	v_mfma_f32_16x16x32_bf16 v[48:51], v[180:183], v[188:191], v[48:51]
	v_mfma_f32_16x16x32_bf16 v[36:39], v[160:163], v[196:199], v[36:39]
	v_mfma_f32_16x16x32_bf16 v[32:35], v[180:183], v[196:199], v[32:35]
	v_mfma_f32_16x16x32_bf16 v[20:23], v[160:163], v[204:207], v[20:23]
	v_mfma_f32_16x16x32_bf16 v[16:19], v[180:183], v[204:207], v[16:19]
	v_mfma_f32_16x16x32_bf16 v[4:7], v[160:163], v[212:215], v[4:7]
	v_mfma_f32_16x16x32_bf16 v[0:3], v[180:183], v[212:215], v[0:3]
	v_mfma_f32_16x16x32_bf16 v[52:55], v[176:179], v[192:195], v[52:55]
	v_mfma_f32_16x16x32_bf16 v[48:51], v[184:187], v[192:195], v[48:51]
	v_mfma_f32_16x16x32_bf16 v[36:39], v[176:179], v[200:203], v[36:39]
	v_mfma_f32_16x16x32_bf16 v[32:35], v[184:187], v[200:203], v[32:35]
	v_mfma_f32_16x16x32_bf16 v[20:23], v[176:179], v[208:211], v[20:23]
	v_mfma_f32_16x16x32_bf16 v[16:19], v[184:187], v[208:211], v[16:19]
	v_mfma_f32_16x16x32_bf16 v[4:7], v[176:179], v[216:219], v[4:7]
	v_mfma_f32_16x16x32_bf16 v[0:3], v[184:187], v[216:219], v[0:3]
	s_barrier
; #define PG8_LDA(dst, b, h) do { _Pragma("unroll") for (int m = 0; m < 4; ++m) _Pragma("unroll") for (int k = 0; k < 2; ++k) dst[m][k] = *(const LAS bf16x8*)(lds + PG8_SA(b, h) + aoff + m * 2048 + k * 1024); } while (0)
; #define PG8_LDB(dst, b, h) do { _Pragma("unroll") for (int n = 0; n < 2; ++n) _Pragma("unroll") for (int k = 0; k < 2; ++k) dst[n][k] = *(const LAS bf16x8*)(lds + PG8_SB(b, h) + boff + n * 2048 + k * 1024); } while (0)
; #define PG8_MMA(ai, bj, At, Bt) do { __builtin_amdgcn_s_setprio(1); _Pragma("unroll") for (int m = 0; m < 4; ++m) _Pragma("unroll") for (int n = 0; n < 2; ++n) _Pragma("unroll") for (int k = 0; k < 2; ++k) \
;         acc[ai][bj][m][n] = __builtin_amdgcn_mfma_f32_16x16x32_bf16(Bt[n][k], At[m][k], acc[ai][bj][m][n], 0, 0, 0); __builtin_amdgcn_s_setprio(0); } while (0)
; #define PG8_WAIT_V(n) asm volatile("s_waitcnt vmcnt(" #n ")" ::: "memory")
; #define PG8_WAIT_L(n) asm volatile("s_waitcnt lgkmcnt(" #n ")" ::: "memory")
; #define PG8_BAR __builtin_amdgcn_s_barrier()
; #define PG8_SCHED __builtin_amdgcn_sched_barrier(0)
; template <class Epi, class Addr, bool ALIGN_EPI = true, class Order = StaticOrder>
; __device__ __forceinline__ void gemm_phase(LAS unsigned char* lds, const Gemm g, const Order& S, const Epi& E, const int wid) {
;     ...
;             PG8_LDB(B0, 1, 0); PG8_LDB(B1, 1, 1); PG8_SCHED; PG8_LDA(At, 1, 0); PG8_STAGE(PG8_SA(0, 1), a2 + hstepA, voffA);
;             PG8_WAIT_V(8); PG8_WAIT_L(0); PG8_BAR; PG8_MMA(0, 0, At, B0); PG8_MMA(0, 1, At, B1); PG8_BAR; PG8_SCHED;
;             PG8_LDA(At, 1, 1); PG8_STAGE(PG8_SB(1, 0), b3, voffB); PG8_STAGE(PG8_SB(1, 1), b3 + hstepB, voffB); PG8_STAGE(PG8_SA(1, 0), a3, voffA);
;             PG8_WAIT_V(8); PG8_WAIT_L(0); PG8_BAR; PG8_MMA(1, 0, At, B0); PG8_MMA(1, 1, At, B1); PG8_BAR; PG8_SCHED;
;         }
;         if constexpr (ALIGN_EPI) { if (wr == 0) PG8_BAR; }
	s_setprio 0
	ds_read_b128 v[128:131], v172
	ds_read_b128 v[132:135], v172 offset:1024
	ds_read_b128 v[152:155], v172 offset:2048
	ds_read_b128 v[156:159], v172 offset:3072
	ds_read_b128 v[160:163], v173
	ds_read_b128 v[176:179], v173 offset:1024
	ds_read_b128 v[180:183], v173 offset:2048
	ds_read_b128 v[184:187], v173 offset:3072
	ds_read_b128 v[188:191], v171 offset:32768
	ds_read_b128 v[192:195], v171 offset:33792
	ds_read_b128 v[196:199], v171 offset:34816
	ds_read_b128 v[200:203], v171 offset:35840
	ds_read_b128 v[204:207], v171 offset:36864
	ds_read_b128 v[208:211], v171 offset:37888
	ds_read_b128 v[212:215], v171 offset:38912
	ds_read_b128 v[216:219], v171 offset:39936
	s_add_u32 s8, s52, 0x100000
	s_addc_u32 s9, s53, 0
	s_mov_b32 s18, m0
	s_mov_b32 m0, s58
	s_nop 0
	global_load_lds_dwordx4 v164, s[8:9]
	s_mov_b32 m0, s59
	s_nop 0
	global_load_lds_dwordx4 v166, s[8:9]
	s_mov_b32 m0, s18
	s_waitcnt vmcnt(8)
	s_waitcnt lgkmcnt(0)
	s_setprio 1
	s_barrier
	v_mfma_f32_16x16x32_bf16 v[124:127], v[128:131], v[188:191], v[124:127]
	v_mfma_f32_16x16x32_bf16 v[120:123], v[152:155], v[188:191], v[120:123]
	v_mfma_f32_16x16x32_bf16 v[108:111], v[128:131], v[196:199], v[108:111]
	v_mfma_f32_16x16x32_bf16 v[104:107], v[152:155], v[196:199], v[104:107]
	v_mfma_f32_16x16x32_bf16 v[92:95], v[128:131], v[204:207], v[92:95]
	v_mfma_f32_16x16x32_bf16 v[88:91], v[152:155], v[204:207], v[88:91]
	v_mfma_f32_16x16x32_bf16 v[76:79], v[128:131], v[212:215], v[76:79]
	v_mfma_f32_16x16x32_bf16 v[72:75], v[152:155], v[212:215], v[72:75]
	v_mfma_f32_16x16x32_bf16 v[124:127], v[132:135], v[192:195], v[124:127]
	v_mfma_f32_16x16x32_bf16 v[120:123], v[156:159], v[192:195], v[120:123]
	v_mfma_f32_16x16x32_bf16 v[108:111], v[132:135], v[200:203], v[108:111]
	v_mfma_f32_16x16x32_bf16 v[104:107], v[156:159], v[200:203], v[104:107]
	v_mfma_f32_16x16x32_bf16 v[92:95], v[132:135], v[208:211], v[92:95]
	v_mfma_f32_16x16x32_bf16 v[88:91], v[156:159], v[208:211], v[88:91]
	v_mfma_f32_16x16x32_bf16 v[76:79], v[132:135], v[216:219], v[76:79]
	v_mfma_f32_16x16x32_bf16 v[72:75], v[156:159], v[216:219], v[72:75]
	v_mfma_f32_16x16x32_bf16 v[116:119], v[160:163], v[188:191], v[116:119]
	v_mfma_f32_16x16x32_bf16 v[112:115], v[180:183], v[188:191], v[112:115]
	v_mfma_f32_16x16x32_bf16 v[100:103], v[160:163], v[196:199], v[100:103]
	v_mfma_f32_16x16x32_bf16 v[96:99], v[180:183], v[196:199], v[96:99]
	v_mfma_f32_16x16x32_bf16 v[84:87], v[160:163], v[204:207], v[84:87]
	v_mfma_f32_16x16x32_bf16 v[80:83], v[180:183], v[204:207], v[80:83]
	v_mfma_f32_16x16x32_bf16 v[68:71], v[160:163], v[212:215], v[68:71]
	v_mfma_f32_16x16x32_bf16 v[64:67], v[180:183], v[212:215], v[64:67]
	v_mfma_f32_16x16x32_bf16 v[116:119], v[176:179], v[192:195], v[116:119]
	v_mfma_f32_16x16x32_bf16 v[112:115], v[184:187], v[192:195], v[112:115]
	v_mfma_f32_16x16x32_bf16 v[100:103], v[176:179], v[200:203], v[100:103]
	v_mfma_f32_16x16x32_bf16 v[96:99], v[184:187], v[200:203], v[96:99]
	v_mfma_f32_16x16x32_bf16 v[84:87], v[176:179], v[208:211], v[84:87]
	v_mfma_f32_16x16x32_bf16 v[80:83], v[184:187], v[208:211], v[80:83]
	v_mfma_f32_16x16x32_bf16 v[68:71], v[176:179], v[216:219], v[68:71]
	v_mfma_f32_16x16x32_bf16 v[64:67], v[184:187], v[216:219], v[64:67]
	s_barrier
	s_setprio 0
	ds_read_b128 v[188:191], v171 offset:49152
	ds_read_b128 v[192:195], v171 offset:50176
	ds_read_b128 v[196:199], v171 offset:51200
	ds_read_b128 v[200:203], v171 offset:52224
	ds_read_b128 v[204:207], v171 offset:53248
	ds_read_b128 v[208:211], v171 offset:54272
	ds_read_b128 v[212:215], v171 offset:55296
	ds_read_b128 v[216:219], v171 offset:56320
	s_add_u32 s8, s50, 0x80
	s_addc_u32 s9, s51, 0
	s_mov_b32 s18, m0
	s_mov_b32 m0, s60
	s_nop 0
	global_load_lds_dwordx4 v165, s[8:9]
	s_mov_b32 m0, s61
	s_nop 0
	global_load_lds_dwordx4 v167, s[8:9]
	s_mov_b32 m0, s18
	s_add_u32 s8, s50, 0x100080
	s_addc_u32 s9, s51, 0
	s_mov_b32 s18, m0
	s_mov_b32 m0, s64
	s_nop 0
	global_load_lds_dwordx4 v165, s[8:9]
	s_mov_b32 m0, s65
	s_nop 0
	global_load_lds_dwordx4 v167, s[8:9]
	s_mov_b32 m0, s18
	s_mov_b32 s8, m0
	s_mov_b32 m0, s62
	s_nop 0
	global_load_lds_dwordx4 v164, s[48:49]
	s_mov_b32 m0, s63
	s_nop 0
	global_load_lds_dwordx4 v166, s[48:49]
	s_mov_b32 m0, s8
	s_waitcnt vmcnt(8)
	s_waitcnt lgkmcnt(0)
	s_setprio 1
	s_barrier
	v_mfma_f32_16x16x32_bf16 v[60:63], v[128:131], v[188:191], v[60:63]
	v_mfma_f32_16x16x32_bf16 v[56:59], v[152:155], v[188:191], v[56:59]
	v_mfma_f32_16x16x32_bf16 v[44:47], v[128:131], v[196:199], v[44:47]
	v_mfma_f32_16x16x32_bf16 v[40:43], v[152:155], v[196:199], v[40:43]
	v_mfma_f32_16x16x32_bf16 v[28:31], v[128:131], v[204:207], v[28:31]
	v_mfma_f32_16x16x32_bf16 v[24:27], v[152:155], v[204:207], v[24:27]
	v_mfma_f32_16x16x32_bf16 v[12:15], v[128:131], v[212:215], v[12:15]
	v_mfma_f32_16x16x32_bf16 v[8:11], v[152:155], v[212:215], v[8:11]
	v_mfma_f32_16x16x32_bf16 v[60:63], v[132:135], v[192:195], v[60:63]
	v_mfma_f32_16x16x32_bf16 v[56:59], v[156:159], v[192:195], v[56:59]
	v_mfma_f32_16x16x32_bf16 v[44:47], v[132:135], v[200:203], v[44:47]
	v_mfma_f32_16x16x32_bf16 v[40:43], v[156:159], v[200:203], v[40:43]
	v_mfma_f32_16x16x32_bf16 v[28:31], v[132:135], v[208:211], v[28:31]
	v_mfma_f32_16x16x32_bf16 v[24:27], v[156:159], v[208:211], v[24:27]
	v_mfma_f32_16x16x32_bf16 v[12:15], v[132:135], v[216:219], v[12:15]
	v_mfma_f32_16x16x32_bf16 v[8:11], v[156:159], v[216:219], v[8:11]
	v_mfma_f32_16x16x32_bf16 v[52:55], v[160:163], v[188:191], v[52:55]
	v_mfma_f32_16x16x32_bf16 v[48:51], v[180:183], v[188:191], v[48:51]
	v_mfma_f32_16x16x32_bf16 v[36:39], v[160:163], v[196:199], v[36:39]
	v_mfma_f32_16x16x32_bf16 v[32:35], v[180:183], v[196:199], v[32:35]
	v_mfma_f32_16x16x32_bf16 v[20:23], v[160:163], v[204:207], v[20:23]
	v_mfma_f32_16x16x32_bf16 v[16:19], v[180:183], v[204:207], v[16:19]
	v_mfma_f32_16x16x32_bf16 v[4:7], v[160:163], v[212:215], v[4:7]
	v_mfma_f32_16x16x32_bf16 v[0:3], v[180:183], v[212:215], v[0:3]
	v_mfma_f32_16x16x32_bf16 v[52:55], v[176:179], v[192:195], v[52:55]
	v_mfma_f32_16x16x32_bf16 v[48:51], v[184:187], v[192:195], v[48:51]
	v_mfma_f32_16x16x32_bf16 v[36:39], v[176:179], v[200:203], v[36:39]
	v_mfma_f32_16x16x32_bf16 v[32:35], v[184:187], v[200:203], v[32:35]
	v_mfma_f32_16x16x32_bf16 v[20:23], v[176:179], v[208:211], v[20:23]
	v_mfma_f32_16x16x32_bf16 v[16:19], v[184:187], v[208:211], v[16:19]
	v_mfma_f32_16x16x32_bf16 v[4:7], v[176:179], v[216:219], v[4:7]
	v_mfma_f32_16x16x32_bf16 v[0:3], v[184:187], v[216:219], v[0:3]
	s_barrier
	s_setprio 0
	s_add_i32 s80, s80, 2
	s_add_u32 s78, s78, 0x100
	s_addc_u32 s79, s79, 0
	s_cmp_gt_u32 s80, 61
	s_mov_b64 s[8:9], s[46:47]
	s_cbranch_scc0 .LBB0_123
	s_and_b64 vcc, exec, s[10:11]
	s_cbranch_vccz .LBB0_126
	s_barrier

; #define PG8_LDA(dst, b, h) do { _Pragma("unroll") for (int m = 0; m < 4; ++m) _Pragma("unroll") for (int k = 0; k < 2; ++k) dst[m][k] = *(const LAS bf16x8*)(lds + PG8_SA(b, h) + aoff + m * 2048 + k * 1024); } while (0)
; #define PG8_LDB(dst, b, h) do { _Pragma("unroll") for (int n = 0; n < 2; ++n) _Pragma("unroll") for (int k = 0; k < 2; ++k) dst[n][k] = *(const LAS bf16x8*)(lds + PG8_SB(b, h) + boff + n * 2048 + k * 1024); } while (0)
; #define PG8_MMA(ai, bj, At, Bt) do { __builtin_amdgcn_s_setprio(1); _Pragma("unroll") for (int m = 0; m < 4; ++m) _Pragma("unroll") for (int n = 0; n < 2; ++n) _Pragma("unroll") for (int k = 0; k < 2; ++k) \
;         acc[ai][bj][m][n] = __builtin_amdgcn_mfma_f32_16x16x32_bf16(Bt[n][k], At[m][k], acc[ai][bj][m][n], 0, 0, 0); __builtin_amdgcn_s_setprio(0); } while (0)
; template <class Epi, class Addr, bool ALIGN_EPI = true, class Order = StaticOrder>
; __device__ __forceinline__ void gemm_phase(LAS unsigned char* lds, const Gemm g, const Order& S, const Epi& E, const int wid) {
;     ...
;             const bool last = (t == nt - 2);
;             const char* a1 = cA + (size_t)(t + 1) * kstep;
;             const char* a2 = last ? nA : cA + (size_t)(t + 2) * kstep; const char* b2 = last ? nB : cB + (size_t)(t + 2) * kstep;
;             const char* a3 = a2 + kstep; const char* b3 = b2 + kstep;
;             PG8_LDB(B0, 0, 0); PG8_LDB(B1, 0, 1); PG8_SCHED; PG8_LDA(At, 0, 0); PG8_STAGE(PG8_SA(1, 1), a1 + hstepA, voffA);
;             PG8_WAIT_V(8); PG8_WAIT_L(0); PG8_BAR; PG8_MMA(0, 0, At, B0); PG8_MMA(0, 1, At, B1); PG8_BAR; PG8_SCHED;
;             PG8_LDA(At, 0, 1); PG8_STAGE(PG8_SB(0, 0), b2, voffB); PG8_STAGE(PG8_SB(0, 1), b2 + hstepB, voffB); PG8_STAGE(PG8_SA(0, 0), a2, voffA);
;             PG8_WAIT_V(8); PG8_WAIT_L(0); PG8_BAR; PG8_MMA(1, 0, At, B0); PG8_MMA(1, 1, At, B1); PG8_BAR; PG8_SCHED;
;             PG8_LDB(B0, 1, 0); PG8_LDB(B1, 1, 1); PG8_SCHED; PG8_LDA(At, 1, 0); PG8_STAGE(PG8_SA(0, 1), a2 + hstepA, voffA);
;             PG8_WAIT_V(8); PG8_WAIT_L(0); PG8_BAR; PG8_MMA(0, 0, At, B0); PG8_MMA(0, 1, At, B1); PG8_BAR; PG8_SCHED;
;             PG8_LDA(At, 1, 1); PG8_STAGE(PG8_SB(1, 0), b3, voffB); PG8_STAGE(PG8_SB(1, 1), b3 + hstepB, voffB); PG8_STAGE(PG8_SA(1, 0), a3, voffA);
;             PG8_WAIT_V(8); PG8_WAIT_L(0); PG8_BAR; PG8_MMA(1, 0, At, B0); PG8_MMA(1, 1, At, B1); PG8_BAR; PG8_SCHED;
.LBB0_191:
	ds_read_b128 v[146:149], v140
	ds_read_b128 v[150:153], v140 offset:1024
	ds_read_b128 v[154:157], v140 offset:2048
	ds_read_b128 v[158:161], v140 offset:3072
	ds_read_b128 v[162:165], v141
	ds_read_b128 v[166:169], v141 offset:1024
	ds_read_b128 v[170:173], v141 offset:2048
	ds_read_b128 v[174:177], v141 offset:3072
	s_add_u32 s24, s22, 0x100
	s_addc_u32 s25, s23, 0
	s_cmp_eq_u32 s77, 60
	s_cselect_b32 s46, s17, s24
	s_cselect_b32 s47, s9, s25
	s_cselect_b32 s44, s74, s75
	s_cselect_b32 s45, s21, s76
	s_add_u32 s26, s46, 0x80
	s_addc_u32 s27, s47, 0
	ds_read_b128 v[178:181], v142
	ds_read_b128 v[182:185], v142 offset:1024
	ds_read_b128 v[186:189], v142 offset:2048
	ds_read_b128 v[190:193], v142 offset:3072
	ds_read_b128 v[194:197], v142 offset:4096
	ds_read_b128 v[198:201], v142 offset:5120
	ds_read_b128 v[202:205], v142 offset:6144
	ds_read_b128 v[206:209], v142 offset:7168
	s_add_u32 s18, s22, 0x100080
	s_addc_u32 s19, s23, 0
	s_mov_b32 s22, m0
	s_mov_b32 m0, s66
	s_nop 0
	global_load_lds_dwordx4 v136, s[18:19]
	s_mov_b32 m0, s67
	s_nop 0
	global_load_lds_dwordx4 v138, s[18:19]
	s_mov_b32 m0, s22
	s_waitcnt vmcnt(8)
	s_waitcnt lgkmcnt(0)
	s_setprio 1
	s_barrier
	v_mfma_f32_16x16x32_bf16 v[124:127], v[146:149], v[178:181], v[124:127]
	v_mfma_f32_16x16x32_bf16 v[120:123], v[154:157], v[178:181], v[120:123]
	v_mfma_f32_16x16x32_bf16 v[116:119], v[146:149], v[186:189], v[116:119]
	v_mfma_f32_16x16x32_bf16 v[108:111], v[154:157], v[186:189], v[108:111]
	v_mfma_f32_16x16x32_bf16 v[100:103], v[146:149], v[194:197], v[100:103]
	v_mfma_f32_16x16x32_bf16 v[92:95], v[154:157], v[194:197], v[92:95]
	v_mfma_f32_16x16x32_bf16 v[84:87], v[146:149], v[202:205], v[84:87]
	v_mfma_f32_16x16x32_bf16 v[76:79], v[154:157], v[202:205], v[76:79]
	v_mfma_f32_16x16x32_bf16 v[124:127], v[150:153], v[182:185], v[124:127]
	v_mfma_f32_16x16x32_bf16 v[120:123], v[158:161], v[182:185], v[120:123]
	v_mfma_f32_16x16x32_bf16 v[116:119], v[150:153], v[190:193], v[116:119]
	v_mfma_f32_16x16x32_bf16 v[108:111], v[158:161], v[190:193], v[108:111]
	v_mfma_f32_16x16x32_bf16 v[100:103], v[150:153], v[198:201], v[100:103]
	v_mfma_f32_16x16x32_bf16 v[92:95], v[158:161], v[198:201], v[92:95]
	v_mfma_f32_16x16x32_bf16 v[84:87], v[150:153], v[206:209], v[84:87]
	v_mfma_f32_16x16x32_bf16 v[76:79], v[158:161], v[206:209], v[76:79]
	v_mfma_f32_16x16x32_bf16 v[112:115], v[162:165], v[178:181], v[112:115]
	v_mfma_f32_16x16x32_bf16 v[104:107], v[170:173], v[178:181], v[104:107]
	v_mfma_f32_16x16x32_bf16 v[96:99], v[162:165], v[186:189], v[96:99]
	v_mfma_f32_16x16x32_bf16 v[88:91], v[170:173], v[186:189], v[88:91]
	v_mfma_f32_16x16x32_bf16 v[80:83], v[162:165], v[194:197], v[80:83]
	v_mfma_f32_16x16x32_bf16 v[72:75], v[170:173], v[194:197], v[72:75]
	v_mfma_f32_16x16x32_bf16 v[68:71], v[162:165], v[202:205], v[68:71]
	v_mfma_f32_16x16x32_bf16 v[64:67], v[170:173], v[202:205], v[64:67]
	v_mfma_f32_16x16x32_bf16 v[112:115], v[166:169], v[182:185], v[112:115]
	v_mfma_f32_16x16x32_bf16 v[104:107], v[174:177], v[182:185], v[104:107]
	v_mfma_f32_16x16x32_bf16 v[96:99], v[166:169], v[190:193], v[96:99]
	v_mfma_f32_16x16x32_bf16 v[88:91], v[174:177], v[190:193], v[88:91]
	v_mfma_f32_16x16x32_bf16 v[80:83], v[166:169], v[198:201], v[80:83]
	v_mfma_f32_16x16x32_bf16 v[72:75], v[174:177], v[198:201], v[72:75]
	v_mfma_f32_16x16x32_bf16 v[68:71], v[166:169], v[206:209], v[68:71]
	v_mfma_f32_16x16x32_bf16 v[64:67], v[174:177], v[206:209], v[64:67]
	s_barrier
	s_setprio 0
	ds_read_b128 v[178:181], v142 offset:16384
	ds_read_b128 v[182:185], v142 offset:17408
	ds_read_b128 v[186:189], v142 offset:18432
	ds_read_b128 v[190:193], v142 offset:19456
	ds_read_b128 v[194:197], v142 offset:20480
	ds_read_b128 v[198:201], v142 offset:21504
	ds_read_b128 v[202:205], v142 offset:22528
	ds_read_b128 v[206:209], v142 offset:23552
	s_mov_b32 s18, m0
	s_mov_b32 m0, s43
	s_nop 0
	global_load_lds_dwordx4 v137, s[44:45]
	s_mov_b32 m0, s54
	s_nop 0
	global_load_lds_dwordx4 v139, s[44:45]
	s_mov_b32 m0, s18
	s_add_u32 s18, s44, 0x2000000
	s_addc_u32 s19, s45, 0
	s_mov_b32 s22, m0
	s_mov_b32 m0, s55
	s_nop 0
	global_load_lds_dwordx4 v137, s[18:19]
	s_mov_b32 m0, s56
	s_nop 0
	global_load_lds_dwordx4 v139, s[18:19]
	s_mov_b32 m0, s22
	s_mov_b32 s18, m0
	s_mov_b32 m0, s41
	s_nop 0
	global_load_lds_dwordx4 v136, s[46:47]
	s_mov_b32 m0, s57
	s_nop 0
	global_load_lds_dwordx4 v138, s[46:47]
	s_mov_b32 m0, s18
	s_waitcnt vmcnt(8)
	s_waitcnt lgkmcnt(0)
	s_setprio 1
	s_barrier
	v_mfma_f32_16x16x32_bf16 v[60:63], v[146:149], v[178:181], v[60:63]
	v_mfma_f32_16x16x32_bf16 v[56:59], v[154:157], v[178:181], v[56:59]
	v_mfma_f32_16x16x32_bf16 v[52:55], v[146:149], v[186:189], v[52:55]
	v_mfma_f32_16x16x32_bf16 v[44:47], v[154:157], v[186:189], v[44:47]
	v_mfma_f32_16x16x32_bf16 v[36:39], v[146:149], v[194:197], v[36:39]
	v_mfma_f32_16x16x32_bf16 v[28:31], v[154:157], v[194:197], v[28:31]
	v_mfma_f32_16x16x32_bf16 v[20:23], v[146:149], v[202:205], v[20:23]
	v_mfma_f32_16x16x32_bf16 v[12:15], v[154:157], v[202:205], v[12:15]
	v_mfma_f32_16x16x32_bf16 v[60:63], v[150:153], v[182:185], v[60:63]
	v_mfma_f32_16x16x32_bf16 v[56:59], v[158:161], v[182:185], v[56:59]
	v_mfma_f32_16x16x32_bf16 v[52:55], v[150:153], v[190:193], v[52:55]
	v_mfma_f32_16x16x32_bf16 v[44:47], v[158:161], v[190:193], v[44:47]
	v_mfma_f32_16x16x32_bf16 v[36:39], v[150:153], v[198:201], v[36:39]
	v_mfma_f32_16x16x32_bf16 v[28:31], v[158:161], v[198:201], v[28:31]
	v_mfma_f32_16x16x32_bf16 v[20:23], v[150:153], v[206:209], v[20:23]
	v_mfma_f32_16x16x32_bf16 v[12:15], v[158:161], v[206:209], v[12:15]
	v_mfma_f32_16x16x32_bf16 v[48:51], v[162:165], v[178:181], v[48:51]
	v_mfma_f32_16x16x32_bf16 v[40:43], v[170:173], v[178:181], v[40:43]
	v_mfma_f32_16x16x32_bf16 v[32:35], v[162:165], v[186:189], v[32:35]
	v_mfma_f32_16x16x32_bf16 v[24:27], v[170:173], v[186:189], v[24:27]
	v_mfma_f32_16x16x32_bf16 v[16:19], v[162:165], v[194:197], v[16:19]
	v_mfma_f32_16x16x32_bf16 v[8:11], v[170:173], v[194:197], v[8:11]
	v_mfma_f32_16x16x32_bf16 v[4:7], v[162:165], v[202:205], v[4:7]
	v_mfma_f32_16x16x32_bf16 v[0:3], v[170:173], v[202:205], v[0:3]
	v_mfma_f32_16x16x32_bf16 v[48:51], v[166:169], v[182:185], v[48:51]
	v_mfma_f32_16x16x32_bf16 v[40:43], v[174:177], v[182:185], v[40:43]
	v_mfma_f32_16x16x32_bf16 v[32:35], v[166:169], v[190:193], v[32:35]
	v_mfma_f32_16x16x32_bf16 v[24:27], v[174:177], v[190:193], v[24:27]
	v_mfma_f32_16x16x32_bf16 v[16:19], v[166:169], v[198:201], v[16:19]
	v_mfma_f32_16x16x32_bf16 v[8:11], v[174:177], v[198:201], v[8:11]
	v_mfma_f32_16x16x32_bf16 v[4:7], v[166:169], v[206:209], v[4:7]
	v_mfma_f32_16x16x32_bf16 v[0:3], v[174:177], v[206:209], v[0:3]
	s_barrier
; #define PG8_LDA(dst, b, h) do { _Pragma("unroll") for (int m = 0; m < 4; ++m) _Pragma("unroll") for (int k = 0; k < 2; ++k) dst[m][k] = *(const LAS bf16x8*)(lds + PG8_SA(b, h) + aoff + m * 2048 + k * 1024); } while (0)
; #define PG8_LDB(dst, b, h) do { _Pragma("unroll") for (int n = 0; n < 2; ++n) _Pragma("unroll") for (int k = 0; k < 2; ++k) dst[n][k] = *(const LAS bf16x8*)(lds + PG8_SB(b, h) + boff + n * 2048 + k * 1024); } while (0)
; #define PG8_MMA(ai, bj, At, Bt) do { __builtin_amdgcn_s_setprio(1); _Pragma("unroll") for (int m = 0; m < 4; ++m) _Pragma("unroll") for (int n = 0; n < 2; ++n) _Pragma("unroll") for (int k = 0; k < 2; ++k) \
;         acc[ai][bj][m][n] = __builtin_amdgcn_mfma_f32_16x16x32_bf16(Bt[n][k], At[m][k], acc[ai][bj][m][n], 0, 0, 0); __builtin_amdgcn_s_setprio(0); } while (0)
; #define PG8_WAIT_V(n) asm volatile("s_waitcnt vmcnt(" #n ")" ::: "memory")
; #define PG8_WAIT_L(n) asm volatile("s_waitcnt lgkmcnt(" #n ")" ::: "memory")
; #define PG8_BAR __builtin_amdgcn_s_barrier()
; #define PG8_SCHED __builtin_amdgcn_sched_barrier(0)
; template <class Epi, class Addr, bool ALIGN_EPI = true, class Order = StaticOrder>
; __device__ __forceinline__ void gemm_phase(LAS unsigned char* lds, const Gemm g, const Order& S, const Epi& E, const int wid) {
;     ...
;             PG8_LDB(B0, 1, 0); PG8_LDB(B1, 1, 1); PG8_SCHED; PG8_LDA(At, 1, 0); PG8_STAGE(PG8_SA(0, 1), a2 + hstepA, voffA);
;             PG8_WAIT_V(8); PG8_WAIT_L(0); PG8_BAR; PG8_MMA(0, 0, At, B0); PG8_MMA(0, 1, At, B1); PG8_BAR; PG8_SCHED;
;             PG8_LDA(At, 1, 1); PG8_STAGE(PG8_SB(1, 0), b3, voffB); PG8_STAGE(PG8_SB(1, 1), b3 + hstepB, voffB); PG8_STAGE(PG8_SA(1, 0), a3, voffA);
;             PG8_WAIT_V(8); PG8_WAIT_L(0); PG8_BAR; PG8_MMA(1, 0, At, B0); PG8_MMA(1, 1, At, B1); PG8_BAR; PG8_SCHED;
;         }
;         if constexpr (ALIGN_EPI) { if (wr == 0) PG8_BAR; }
	s_setprio 0
	ds_read_b128 v[146:149], v143
	ds_read_b128 v[150:153], v143 offset:1024
	ds_read_b128 v[154:157], v143 offset:2048
	ds_read_b128 v[158:161], v143 offset:3072
	ds_read_b128 v[162:165], v144
	ds_read_b128 v[166:169], v144 offset:1024
	ds_read_b128 v[170:173], v144 offset:2048
	ds_read_b128 v[174:177], v144 offset:3072
	ds_read_b128 v[178:181], v142 offset:32768
	ds_read_b128 v[182:185], v142 offset:33792
	ds_read_b128 v[186:189], v142 offset:34816
	ds_read_b128 v[190:193], v142 offset:35840
	ds_read_b128 v[194:197], v142 offset:36864
	ds_read_b128 v[198:201], v142 offset:37888
	ds_read_b128 v[202:205], v142 offset:38912
	ds_read_b128 v[206:209], v142 offset:39936
	s_add_u32 s18, s46, 0x100000
	s_addc_u32 s19, s47, 0
	s_mov_b32 s22, m0
	s_mov_b32 m0, s58
	s_nop 0
	global_load_lds_dwordx4 v136, s[18:19]
	s_mov_b32 m0, s59
	s_nop 0
	global_load_lds_dwordx4 v138, s[18:19]
	s_mov_b32 m0, s22
	s_waitcnt vmcnt(8)
	s_waitcnt lgkmcnt(0)
	s_setprio 1
	s_barrier
	v_mfma_f32_16x16x32_bf16 v[124:127], v[146:149], v[178:181], v[124:127]
	v_mfma_f32_16x16x32_bf16 v[120:123], v[154:157], v[178:181], v[120:123]
	v_mfma_f32_16x16x32_bf16 v[116:119], v[146:149], v[186:189], v[116:119]
	v_mfma_f32_16x16x32_bf16 v[108:111], v[154:157], v[186:189], v[108:111]
	v_mfma_f32_16x16x32_bf16 v[100:103], v[146:149], v[194:197], v[100:103]
	v_mfma_f32_16x16x32_bf16 v[92:95], v[154:157], v[194:197], v[92:95]
	v_mfma_f32_16x16x32_bf16 v[84:87], v[146:149], v[202:205], v[84:87]
	v_mfma_f32_16x16x32_bf16 v[76:79], v[154:157], v[202:205], v[76:79]
	v_mfma_f32_16x16x32_bf16 v[124:127], v[150:153], v[182:185], v[124:127]
	v_mfma_f32_16x16x32_bf16 v[120:123], v[158:161], v[182:185], v[120:123]
	v_mfma_f32_16x16x32_bf16 v[116:119], v[150:153], v[190:193], v[116:119]
	v_mfma_f32_16x16x32_bf16 v[108:111], v[158:161], v[190:193], v[108:111]
	v_mfma_f32_16x16x32_bf16 v[100:103], v[150:153], v[198:201], v[100:103]
	v_mfma_f32_16x16x32_bf16 v[92:95], v[158:161], v[198:201], v[92:95]
	v_mfma_f32_16x16x32_bf16 v[84:87], v[150:153], v[206:209], v[84:87]
	v_mfma_f32_16x16x32_bf16 v[76:79], v[158:161], v[206:209], v[76:79]
	v_mfma_f32_16x16x32_bf16 v[112:115], v[162:165], v[178:181], v[112:115]
	v_mfma_f32_16x16x32_bf16 v[104:107], v[170:173], v[178:181], v[104:107]
	v_mfma_f32_16x16x32_bf16 v[96:99], v[162:165], v[186:189], v[96:99]
	v_mfma_f32_16x16x32_bf16 v[88:91], v[170:173], v[186:189], v[88:91]
	v_mfma_f32_16x16x32_bf16 v[80:83], v[162:165], v[194:197], v[80:83]
	v_mfma_f32_16x16x32_bf16 v[72:75], v[170:173], v[194:197], v[72:75]
	v_mfma_f32_16x16x32_bf16 v[68:71], v[162:165], v[202:205], v[68:71]
	v_mfma_f32_16x16x32_bf16 v[64:67], v[170:173], v[202:205], v[64:67]
	v_mfma_f32_16x16x32_bf16 v[112:115], v[166:169], v[182:185], v[112:115]
	v_mfma_f32_16x16x32_bf16 v[104:107], v[174:177], v[182:185], v[104:107]
	v_mfma_f32_16x16x32_bf16 v[96:99], v[166:169], v[190:193], v[96:99]
	v_mfma_f32_16x16x32_bf16 v[88:91], v[174:177], v[190:193], v[88:91]
	v_mfma_f32_16x16x32_bf16 v[80:83], v[166:169], v[198:201], v[80:83]
	v_mfma_f32_16x16x32_bf16 v[72:75], v[174:177], v[198:201], v[72:75]
	v_mfma_f32_16x16x32_bf16 v[68:71], v[166:169], v[206:209], v[68:71]
	v_mfma_f32_16x16x32_bf16 v[64:67], v[174:177], v[206:209], v[64:67]
	s_barrier
	s_setprio 0
	ds_read_b128 v[178:181], v142 offset:49152
	ds_read_b128 v[182:185], v142 offset:50176
	ds_read_b128 v[186:189], v142 offset:51200
	ds_read_b128 v[190:193], v142 offset:52224
	ds_read_b128 v[194:197], v142 offset:53248
	ds_read_b128 v[198:201], v142 offset:54272
	ds_read_b128 v[202:205], v142 offset:55296
	ds_read_b128 v[206:209], v142 offset:56320
	s_add_u32 s18, s44, 0x80
	s_addc_u32 s19, s45, 0
	s_mov_b32 s22, m0
	s_mov_b32 m0, s60
	s_nop 0
	global_load_lds_dwordx4 v137, s[18:19]
	s_mov_b32 m0, s61
	s_nop 0
	global_load_lds_dwordx4 v139, s[18:19]
	s_mov_b32 m0, s22
	s_add_u32 s18, s44, 0x2000080
	s_addc_u32 s19, s45, 0
	s_mov_b32 s22, m0
	s_mov_b32 m0, s64
	s_nop 0
	global_load_lds_dwordx4 v137, s[18:19]
	s_mov_b32 m0, s65
	s_nop 0
	global_load_lds_dwordx4 v139, s[18:19]
	s_mov_b32 m0, s22
	s_mov_b32 s18, m0
	s_mov_b32 m0, s62
	s_nop 0
	global_load_lds_dwordx4 v136, s[26:27]
	s_mov_b32 m0, s63
	s_nop 0
	global_load_lds_dwordx4 v138, s[26:27]
	s_mov_b32 m0, s18
	s_waitcnt vmcnt(8)
	s_waitcnt lgkmcnt(0)
	s_setprio 1
	s_barrier
	v_mfma_f32_16x16x32_bf16 v[60:63], v[146:149], v[178:181], v[60:63]
	v_mfma_f32_16x16x32_bf16 v[56:59], v[154:157], v[178:181], v[56:59]
	v_mfma_f32_16x16x32_bf16 v[52:55], v[146:149], v[186:189], v[52:55]
	v_mfma_f32_16x16x32_bf16 v[44:47], v[154:157], v[186:189], v[44:47]
	v_mfma_f32_16x16x32_bf16 v[36:39], v[146:149], v[194:197], v[36:39]
	v_mfma_f32_16x16x32_bf16 v[28:31], v[154:157], v[194:197], v[28:31]
	v_mfma_f32_16x16x32_bf16 v[20:23], v[146:149], v[202:205], v[20:23]
	v_mfma_f32_16x16x32_bf16 v[12:15], v[154:157], v[202:205], v[12:15]
	v_mfma_f32_16x16x32_bf16 v[60:63], v[150:153], v[182:185], v[60:63]
	v_mfma_f32_16x16x32_bf16 v[56:59], v[158:161], v[182:185], v[56:59]
	v_mfma_f32_16x16x32_bf16 v[52:55], v[150:153], v[190:193], v[52:55]
	v_mfma_f32_16x16x32_bf16 v[44:47], v[158:161], v[190:193], v[44:47]
	v_mfma_f32_16x16x32_bf16 v[36:39], v[150:153], v[198:201], v[36:39]
	v_mfma_f32_16x16x32_bf16 v[28:31], v[158:161], v[198:201], v[28:31]
	v_mfma_f32_16x16x32_bf16 v[20:23], v[150:153], v[206:209], v[20:23]
	v_mfma_f32_16x16x32_bf16 v[12:15], v[158:161], v[206:209], v[12:15]
	v_mfma_f32_16x16x32_bf16 v[48:51], v[162:165], v[178:181], v[48:51]
	v_mfma_f32_16x16x32_bf16 v[40:43], v[170:173], v[178:181], v[40:43]
	v_mfma_f32_16x16x32_bf16 v[32:35], v[162:165], v[186:189], v[32:35]
	v_mfma_f32_16x16x32_bf16 v[24:27], v[170:173], v[186:189], v[24:27]
	v_mfma_f32_16x16x32_bf16 v[16:19], v[162:165], v[194:197], v[16:19]
	v_mfma_f32_16x16x32_bf16 v[8:11], v[170:173], v[194:197], v[8:11]
	v_mfma_f32_16x16x32_bf16 v[4:7], v[162:165], v[202:205], v[4:7]
	v_mfma_f32_16x16x32_bf16 v[0:3], v[170:173], v[202:205], v[0:3]
	v_mfma_f32_16x16x32_bf16 v[48:51], v[166:169], v[182:185], v[48:51]
	v_mfma_f32_16x16x32_bf16 v[40:43], v[174:177], v[182:185], v[40:43]
	v_mfma_f32_16x16x32_bf16 v[32:35], v[166:169], v[190:193], v[32:35]
	v_mfma_f32_16x16x32_bf16 v[24:27], v[174:177], v[190:193], v[24:27]
	v_mfma_f32_16x16x32_bf16 v[16:19], v[166:169], v[198:201], v[16:19]
	v_mfma_f32_16x16x32_bf16 v[8:11], v[174:177], v[198:201], v[8:11]
	v_mfma_f32_16x16x32_bf16 v[4:7], v[166:169], v[206:209], v[4:7]
	v_mfma_f32_16x16x32_bf16 v[0:3], v[174:177], v[206:209], v[0:3]
	s_barrier
	s_setprio 0
	s_add_i32 s77, s77, 2
	s_add_u32 s75, s75, 0x100
	s_addc_u32 s76, s76, 0
	s_cmp_gt_u32 s77, 61
	s_mov_b64 s[22:23], s[24:25]
	s_cbranch_scc0 .LBB0_191
	s_and_b64 vcc, exec, s[10:11]
	s_cbranch_vccz .LBB0_194
	s_barrier

; #define PG8_LDA(dst, b, h) do { _Pragma("unroll") for (int m = 0; m < 4; ++m) _Pragma("unroll") for (int k = 0; k < 2; ++k) dst[m][k] = *(const LAS bf16x8*)(lds + PG8_SA(b, h) + aoff + m * 2048 + k * 1024); } while (0)
; #define PG8_LDB(dst, b, h) do { _Pragma("unroll") for (int n = 0; n < 2; ++n) _Pragma("unroll") for (int k = 0; k < 2; ++k) dst[n][k] = *(const LAS bf16x8*)(lds + PG8_SB(b, h) + boff + n * 2048 + k * 1024); } while (0)
; #define PG8_MMA(ai, bj, At, Bt) do { __builtin_amdgcn_s_setprio(1); _Pragma("unroll") for (int m = 0; m < 4; ++m) _Pragma("unroll") for (int n = 0; n < 2; ++n) _Pragma("unroll") for (int k = 0; k < 2; ++k) \
;         acc[ai][bj][m][n] = __builtin_amdgcn_mfma_f32_16x16x32_bf16(Bt[n][k], At[m][k], acc[ai][bj][m][n], 0, 0, 0); __builtin_amdgcn_s_setprio(0); } while (0)
; #define PG8_WAIT_V(n) asm volatile("s_waitcnt vmcnt(" #n ")" ::: "memory")
; #define PG8_WAIT_L(n) asm volatile("s_waitcnt lgkmcnt(" #n ")" ::: "memory")
; #define PG8_BAR __builtin_amdgcn_s_barrier()
; #define PG8_SCHED __builtin_amdgcn_sched_barrier(0)
; template <class Epi, class Addr, bool ALIGN_EPI = true, class Order = StaticOrder>
; __device__ __forceinline__ void gemm_phase(LAS unsigned char* lds, const Gemm g, const Order& S, const Epi& E, const int wid) {
;     ...
;         const char* nA = has_next ? (const char*)g.A + Addr::offA(nxt, g) : cA; const char* nB = has_next ? (const char*)g.Bt + Addr::offB(nxt, g) : cB;
;         for (int t = 0; t < nt; t += 2) {
;             const bool last = (t == nt - 2);
;             const char* a1 = cA + (size_t)(t + 1) * kstep;
;             const char* a2 = last ? nA : cA + (size_t)(t + 2) * kstep; const char* b2 = last ? nB : cB + (size_t)(t + 2) * kstep;
;             const char* a3 = a2 + kstep; const char* b3 = b2 + kstep;
;             PG8_LDB(B0, 0, 0); PG8_LDB(B1, 0, 1); PG8_SCHED; PG8_LDA(At, 0, 0); PG8_STAGE(PG8_SA(1, 1), a1 + hstepA, voffA);
;             PG8_WAIT_V(8); PG8_WAIT_L(0); PG8_BAR; PG8_MMA(0, 0, At, B0); PG8_MMA(0, 1, At, B1); PG8_BAR; PG8_SCHED;
;             PG8_LDA(At, 0, 1); PG8_STAGE(PG8_SB(0, 0), b2, voffB); PG8_STAGE(PG8_SB(0, 1), b2 + hstepB, voffB); PG8_STAGE(PG8_SA(0, 0), a2, voffA);
;             PG8_WAIT_V(8); PG8_WAIT_L(0); PG8_BAR; PG8_MMA(1, 0, At, B0); PG8_MMA(1, 1, At, B1); PG8_BAR; PG8_SCHED;
.LBB0_267:
	s_ashr_i32 s13, s12, 31
	s_lshl_b64 s[14:15], s[12:13], 17
	s_add_u32 s14, s29, s14
	s_addc_u32 s15, s31, s15
	s_and_b64 s[18:19], s[4:5], exec
	s_cselect_b32 s47, s15, s25
	s_cselect_b32 s46, s14, s24
	s_ashr_i32 s18, s75, 6
	s_ashr_i32 s19, s18, 31
	s_lshl_b32 s13, s75, 9
	s_and_b32 s13, s13, 0x7e00
	s_lshl_b64 s[18:19], s[18:19], 23
	ds_read_b128 v[0:3], v140
	ds_read_b128 v[4:7], v140 offset:1024
	ds_read_b128 v[8:11], v140 offset:2048
	ds_read_b128 v[12:15], v140 offset:3072
	ds_read_b128 v[16:19], v141
	ds_read_b128 v[20:23], v141 offset:1024
	ds_read_b128 v[24:27], v141 offset:2048
	ds_read_b128 v[28:31], v141 offset:3072
	s_add_u32 s17, s38, s18
	s_addc_u32 s18, s39, s19
	s_add_u32 s22, s17, s13
	s_addc_u32 s23, s18, 0
	s_and_b64 s[18:19], s[4:5], exec
	s_cselect_b32 s45, s23, s27
	s_cselect_b32 s44, s22, s26
	s_add_u32 s50, s24, 0x100
	s_addc_u32 s51, s25, 0
	s_add_u32 s18, s26, 0x100
	s_addc_u32 s19, s27, 0
	s_add_u32 s48, s24, 0x180
	s_addc_u32 s49, s25, 0
	ds_read_b128 v[32:35], v142
	ds_read_b128 v[36:39], v142 offset:1024
	ds_read_b128 v[40:43], v142 offset:2048
	ds_read_b128 v[44:47], v142 offset:3072
	ds_read_b128 v[48:51], v142 offset:4096
	ds_read_b128 v[52:55], v142 offset:5120
	ds_read_b128 v[56:59], v142 offset:6144
	ds_read_b128 v[60:63], v142 offset:7168
	s_add_u32 s76, s24, 0x10080
	s_addc_u32 s77, s25, 0
	s_mov_b32 s13, m0
	s_mov_b32 m0, s65
	s_nop 0
	global_load_lds_dwordx4 v136, s[76:77]
	s_mov_b32 m0, s66
	s_nop 0
	global_load_lds_dwordx4 v138, s[76:77]
	s_mov_b32 m0, s13
	s_waitcnt vmcnt(8)
	s_waitcnt lgkmcnt(0)
	s_setprio 1
	s_barrier
	v_mfma_f32_16x16x32_bf16 v[64:67], v[0:3], v[32:35], 0
	v_mfma_f32_16x16x32_bf16 v[68:71], v[8:11], v[32:35], 0
	v_mfma_f32_16x16x32_bf16 v[72:75], v[0:3], v[40:43], 0
	v_mfma_f32_16x16x32_bf16 v[76:79], v[8:11], v[40:43], 0
	v_mfma_f32_16x16x32_bf16 v[80:83], v[0:3], v[48:51], 0
	v_mfma_f32_16x16x32_bf16 v[84:87], v[8:11], v[48:51], 0
	v_mfma_f32_16x16x32_bf16 v[88:91], v[0:3], v[56:59], 0
	v_mfma_f32_16x16x32_bf16 v[92:95], v[8:11], v[56:59], 0
	v_mfma_f32_16x16x32_bf16 v[64:67], v[4:7], v[36:39], v[64:67]
	v_mfma_f32_16x16x32_bf16 v[68:71], v[12:15], v[36:39], v[68:71]
	v_mfma_f32_16x16x32_bf16 v[72:75], v[4:7], v[44:47], v[72:75]
	v_mfma_f32_16x16x32_bf16 v[76:79], v[12:15], v[44:47], v[76:79]
	v_mfma_f32_16x16x32_bf16 v[80:83], v[4:7], v[52:55], v[80:83]
	v_mfma_f32_16x16x32_bf16 v[84:87], v[12:15], v[52:55], v[84:87]
	v_mfma_f32_16x16x32_bf16 v[88:91], v[4:7], v[60:63], v[88:91]
	v_mfma_f32_16x16x32_bf16 v[92:95], v[12:15], v[60:63], v[92:95]
	v_mfma_f32_16x16x32_bf16 v[96:99], v[16:19], v[32:35], 0
	v_mfma_f32_16x16x32_bf16 v[32:35], v[24:27], v[32:35], 0
	v_mfma_f32_16x16x32_bf16 v[96:99], v[20:23], v[36:39], v[96:99]
	v_mfma_f32_16x16x32_bf16 v[32:35], v[28:31], v[36:39], v[32:35]
	v_mfma_f32_16x16x32_bf16 v[36:39], v[16:19], v[40:43], 0
	v_mfma_f32_16x16x32_bf16 v[40:43], v[24:27], v[40:43], 0
	v_mfma_f32_16x16x32_bf16 v[36:39], v[20:23], v[44:47], v[36:39]
	v_mfma_f32_16x16x32_bf16 v[40:43], v[28:31], v[44:47], v[40:43]
	v_mfma_f32_16x16x32_bf16 v[44:47], v[16:19], v[48:51], 0
	v_mfma_f32_16x16x32_bf16 v[48:51], v[24:27], v[48:51], 0
	v_mfma_f32_16x16x32_bf16 v[44:47], v[20:23], v[52:55], v[44:47]
	v_mfma_f32_16x16x32_bf16 v[48:51], v[28:31], v[52:55], v[48:51]
	v_mfma_f32_16x16x32_bf16 v[52:55], v[16:19], v[56:59], 0
	v_mfma_f32_16x16x32_bf16 v[56:59], v[24:27], v[56:59], 0
	v_mfma_f32_16x16x32_bf16 v[52:55], v[20:23], v[60:63], v[52:55]
	v_mfma_f32_16x16x32_bf16 v[56:59], v[28:31], v[60:63], v[56:59]
	s_barrier
	s_setprio 0
	ds_read_b128 v[60:63], v142 offset:16384
	ds_read_b128 v[100:103], v142 offset:17408
	ds_read_b128 v[104:107], v142 offset:18432
	ds_read_b128 v[108:111], v142 offset:19456
	ds_read_b128 v[112:115], v142 offset:20480
	ds_read_b128 v[116:119], v142 offset:21504
	ds_read_b128 v[120:123], v142 offset:22528
	ds_read_b128 v[124:127], v142 offset:23552
	s_mov_b32 s13, m0
	s_mov_b32 m0, s41
	s_nop 0
	global_load_lds_dwordx4 v137, s[18:19]
	s_mov_b32 m0, s43
	s_nop 0
	global_load_lds_dwordx4 v139, s[18:19]
	s_mov_b32 m0, s13
	s_add_u32 s18, s26, 0x400100
	s_addc_u32 s19, s27, 0
	s_mov_b32 s13, m0
	s_mov_b32 m0, s52
	s_nop 0
	global_load_lds_dwordx4 v137, s[18:19]
	s_mov_b32 m0, s53
	s_nop 0
	global_load_lds_dwordx4 v139, s[18:19]
	s_mov_b32 m0, s13
	s_nop 0
	s_mov_b32 s13, m0
	s_mov_b32 m0, s40
	s_nop 0
	global_load_lds_dwordx4 v136, s[50:51]
	s_mov_b32 m0, s54
	s_nop 0
	global_load_lds_dwordx4 v138, s[50:51]
	s_mov_b32 m0, s13
	s_waitcnt vmcnt(8)
	s_waitcnt lgkmcnt(0)
	s_setprio 1
	s_barrier
	v_mfma_f32_16x16x32_bf16 v[146:149], v[0:3], v[60:63], 0
	v_mfma_f32_16x16x32_bf16 v[154:157], v[0:3], v[104:107], 0
	v_mfma_f32_16x16x32_bf16 v[162:165], v[0:3], v[112:115], 0
	v_mfma_f32_16x16x32_bf16 v[0:3], v[0:3], v[120:123], 0
	v_mfma_f32_16x16x32_bf16 v[146:149], v[4:7], v[100:103], v[146:149]
	v_mfma_f32_16x16x32_bf16 v[154:157], v[4:7], v[108:111], v[154:157]
	v_mfma_f32_16x16x32_bf16 v[162:165], v[4:7], v[116:119], v[162:165]
	v_mfma_f32_16x16x32_bf16 v[0:3], v[4:7], v[124:127], v[0:3]
	v_mfma_f32_16x16x32_bf16 v[4:7], v[8:11], v[120:123], 0
	v_mfma_f32_16x16x32_bf16 v[150:153], v[8:11], v[60:63], 0
	v_mfma_f32_16x16x32_bf16 v[158:161], v[8:11], v[104:107], 0
	v_mfma_f32_16x16x32_bf16 v[166:169], v[8:11], v[112:115], 0
	v_mfma_f32_16x16x32_bf16 v[4:7], v[12:15], v[124:127], v[4:7]
	v_mfma_f32_16x16x32_bf16 v[150:153], v[12:15], v[100:103], v[150:153]
	v_mfma_f32_16x16x32_bf16 v[158:161], v[12:15], v[108:111], v[158:161]
	v_mfma_f32_16x16x32_bf16 v[166:169], v[12:15], v[116:119], v[166:169]
	v_mfma_f32_16x16x32_bf16 v[8:11], v[16:19], v[60:63], 0
	v_mfma_f32_16x16x32_bf16 v[12:15], v[24:27], v[60:63], 0
	v_mfma_f32_16x16x32_bf16 v[8:11], v[20:23], v[100:103], v[8:11]
	v_mfma_f32_16x16x32_bf16 v[12:15], v[28:31], v[100:103], v[12:15]
	v_mfma_f32_16x16x32_bf16 v[60:63], v[16:19], v[104:107], 0
	v_mfma_f32_16x16x32_bf16 v[100:103], v[24:27], v[104:107], 0
	v_mfma_f32_16x16x32_bf16 v[104:107], v[16:19], v[112:115], 0
	v_mfma_f32_16x16x32_bf16 v[16:19], v[16:19], v[120:123], 0
	v_mfma_f32_16x16x32_bf16 v[60:63], v[20:23], v[108:111], v[60:63]
	v_mfma_f32_16x16x32_bf16 v[100:103], v[28:31], v[108:111], v[100:103]
	v_mfma_f32_16x16x32_bf16 v[104:107], v[20:23], v[116:119], v[104:107]
	v_mfma_f32_16x16x32_bf16 v[108:111], v[24:27], v[112:115], 0
	v_mfma_f32_16x16x32_bf16 v[16:19], v[20:23], v[124:127], v[16:19]
	v_mfma_f32_16x16x32_bf16 v[20:23], v[24:27], v[120:123], 0
	v_mfma_f32_16x16x32_bf16 v[108:111], v[28:31], v[116:119], v[108:111]
	v_mfma_f32_16x16x32_bf16 v[20:23], v[28:31], v[124:127], v[20:23]
	s_barrier
; #define PG8_LDA(dst, b, h) do { _Pragma("unroll") for (int m = 0; m < 4; ++m) _Pragma("unroll") for (int k = 0; k < 2; ++k) dst[m][k] = *(const LAS bf16x8*)(lds + PG8_SA(b, h) + aoff + m * 2048 + k * 1024); } while (0)
; #define PG8_LDB(dst, b, h) do { _Pragma("unroll") for (int n = 0; n < 2; ++n) _Pragma("unroll") for (int k = 0; k < 2; ++k) dst[n][k] = *(const LAS bf16x8*)(lds + PG8_SB(b, h) + boff + n * 2048 + k * 1024); } while (0)
; #define PG8_MMA(ai, bj, At, Bt) do { __builtin_amdgcn_s_setprio(1); _Pragma("unroll") for (int m = 0; m < 4; ++m) _Pragma("unroll") for (int n = 0; n < 2; ++n) _Pragma("unroll") for (int k = 0; k < 2; ++k) \
;         acc[ai][bj][m][n] = __builtin_amdgcn_mfma_f32_16x16x32_bf16(Bt[n][k], At[m][k], acc[ai][bj][m][n], 0, 0, 0); __builtin_amdgcn_s_setprio(0); } while (0)
; #define PG8_WAIT_V(n) asm volatile("s_waitcnt vmcnt(" #n ")" ::: "memory")
; #define PG8_WAIT_L(n) asm volatile("s_waitcnt lgkmcnt(" #n ")" ::: "memory")
; #define PG8_BAR __builtin_amdgcn_s_barrier()
; #define PG8_SCHED __builtin_amdgcn_sched_barrier(0)
; template <class Epi, class Addr, bool ALIGN_EPI = true, class Order = StaticOrder>
; __device__ __forceinline__ void gemm_phase(LAS unsigned char* lds, const Gemm g, const Order& S, const Epi& E, const int wid) {
;     ...
;             PG8_WAIT_V(8); PG8_WAIT_L(0); PG8_BAR; PG8_MMA(1, 0, At, B0); PG8_MMA(1, 1, At, B1); PG8_BAR; PG8_SCHED;
;             PG8_LDB(B0, 1, 0); PG8_LDB(B1, 1, 1); PG8_SCHED; PG8_LDA(At, 1, 0); PG8_STAGE(PG8_SA(0, 1), a2 + hstepA, voffA);
;             PG8_WAIT_V(8); PG8_WAIT_L(0); PG8_BAR; PG8_MMA(0, 0, At, B0); PG8_MMA(0, 1, At, B1); PG8_BAR; PG8_SCHED;
;             PG8_LDA(At, 1, 1); PG8_STAGE(PG8_SB(1, 0), b3, voffB); PG8_STAGE(PG8_SB(1, 1), b3 + hstepB, voffB); PG8_STAGE(PG8_SA(1, 0), a3, voffA);
;             PG8_WAIT_V(8); PG8_WAIT_L(0); PG8_BAR; PG8_MMA(1, 0, At, B0); PG8_MMA(1, 1, At, B1); PG8_BAR; PG8_SCHED;
	s_setprio 0
	ds_read_b128 v[24:27], v143
	ds_read_b128 v[28:31], v143 offset:1024
	ds_read_b128 v[112:115], v143 offset:2048
	ds_read_b128 v[116:119], v143 offset:3072
	ds_read_b128 v[120:123], v144
	ds_read_b128 v[124:127], v144 offset:1024
	ds_read_b128 v[170:173], v144 offset:2048
	ds_read_b128 v[174:177], v144 offset:3072
	ds_read_b128 v[178:181], v142 offset:32768
	ds_read_b128 v[182:185], v142 offset:33792
	ds_read_b128 v[186:189], v142 offset:34816
	ds_read_b128 v[190:193], v142 offset:35840
	ds_read_b128 v[194:197], v142 offset:36864
	ds_read_b128 v[198:201], v142 offset:37888
	ds_read_b128 v[202:205], v142 offset:38912
	ds_read_b128 v[206:209], v142 offset:39936
	s_add_u32 s18, s24, 0x10100
	s_addc_u32 s19, s25, 0
	s_mov_b32 s13, m0
	s_mov_b32 m0, s55
	s_nop 0
	global_load_lds_dwordx4 v136, s[18:19]
	s_mov_b32 m0, s56
	s_nop 0
	global_load_lds_dwordx4 v138, s[18:19]
	s_mov_b32 m0, s13
	s_waitcnt vmcnt(8)
	s_waitcnt lgkmcnt(0)
	s_setprio 1
	s_barrier
	v_mfma_f32_16x16x32_bf16 v[64:67], v[24:27], v[178:181], v[64:67]
	v_mfma_f32_16x16x32_bf16 v[68:71], v[112:115], v[178:181], v[68:71]
	v_mfma_f32_16x16x32_bf16 v[72:75], v[24:27], v[186:189], v[72:75]
	v_mfma_f32_16x16x32_bf16 v[76:79], v[112:115], v[186:189], v[76:79]
	v_mfma_f32_16x16x32_bf16 v[80:83], v[24:27], v[194:197], v[80:83]
	v_mfma_f32_16x16x32_bf16 v[84:87], v[112:115], v[194:197], v[84:87]
	v_mfma_f32_16x16x32_bf16 v[88:91], v[24:27], v[202:205], v[88:91]
	v_mfma_f32_16x16x32_bf16 v[92:95], v[112:115], v[202:205], v[92:95]
	v_mfma_f32_16x16x32_bf16 v[64:67], v[28:31], v[182:185], v[64:67]
	v_mfma_f32_16x16x32_bf16 v[68:71], v[116:119], v[182:185], v[68:71]
	v_mfma_f32_16x16x32_bf16 v[72:75], v[28:31], v[190:193], v[72:75]
	v_mfma_f32_16x16x32_bf16 v[76:79], v[116:119], v[190:193], v[76:79]
	v_mfma_f32_16x16x32_bf16 v[80:83], v[28:31], v[198:201], v[80:83]
	v_mfma_f32_16x16x32_bf16 v[84:87], v[116:119], v[198:201], v[84:87]
	v_mfma_f32_16x16x32_bf16 v[88:91], v[28:31], v[206:209], v[88:91]
	v_mfma_f32_16x16x32_bf16 v[92:95], v[116:119], v[206:209], v[92:95]
	v_mfma_f32_16x16x32_bf16 v[96:99], v[120:123], v[178:181], v[96:99]
	v_mfma_f32_16x16x32_bf16 v[32:35], v[170:173], v[178:181], v[32:35]
	v_mfma_f32_16x16x32_bf16 v[36:39], v[120:123], v[186:189], v[36:39]
	v_mfma_f32_16x16x32_bf16 v[40:43], v[170:173], v[186:189], v[40:43]
	v_mfma_f32_16x16x32_bf16 v[44:47], v[120:123], v[194:197], v[44:47]
	v_mfma_f32_16x16x32_bf16 v[48:51], v[170:173], v[194:197], v[48:51]
	v_mfma_f32_16x16x32_bf16 v[52:55], v[120:123], v[202:205], v[52:55]
	v_mfma_f32_16x16x32_bf16 v[56:59], v[170:173], v[202:205], v[56:59]
	v_mfma_f32_16x16x32_bf16 v[96:99], v[124:127], v[182:185], v[96:99]
	v_mfma_f32_16x16x32_bf16 v[32:35], v[174:177], v[182:185], v[32:35]
	v_mfma_f32_16x16x32_bf16 v[36:39], v[124:127], v[190:193], v[36:39]
	v_mfma_f32_16x16x32_bf16 v[40:43], v[174:177], v[190:193], v[40:43]
	v_mfma_f32_16x16x32_bf16 v[44:47], v[124:127], v[198:201], v[44:47]
	v_mfma_f32_16x16x32_bf16 v[48:51], v[174:177], v[198:201], v[48:51]
	v_mfma_f32_16x16x32_bf16 v[52:55], v[124:127], v[206:209], v[52:55]
	v_mfma_f32_16x16x32_bf16 v[56:59], v[174:177], v[206:209], v[56:59]
	s_barrier
	s_setprio 0
	ds_read_b128 v[178:181], v142 offset:49152
	ds_read_b128 v[182:185], v142 offset:50176
	ds_read_b128 v[186:189], v142 offset:51200
	ds_read_b128 v[190:193], v142 offset:52224
	ds_read_b128 v[194:197], v142 offset:53248
	ds_read_b128 v[198:201], v142 offset:54272
	ds_read_b128 v[202:205], v142 offset:55296
	ds_read_b128 v[206:209], v142 offset:56320
	s_add_u32 s18, s26, 0x180
	s_addc_u32 s19, s27, 0
	s_mov_b32 s13, m0
	s_mov_b32 m0, s59
	s_nop 0
	global_load_lds_dwordx4 v137, s[18:19]
	s_mov_b32 m0, s60
	s_nop 0
	global_load_lds_dwordx4 v139, s[18:19]
	s_mov_b32 m0, s13
	s_add_u32 s18, s26, 0x400180
	s_addc_u32 s19, s27, 0
	s_mov_b32 s13, m0
	s_mov_b32 m0, s63
	s_nop 0
	global_load_lds_dwordx4 v137, s[18:19]
	s_mov_b32 m0, s64
	s_nop 0
	global_load_lds_dwordx4 v139, s[18:19]
	s_mov_b32 m0, s13
	s_nop 0
	s_mov_b32 s13, m0
	s_mov_b32 m0, s61
	s_nop 0
	global_load_lds_dwordx4 v136, s[48:49]
	s_mov_b32 m0, s62
	s_nop 0
	global_load_lds_dwordx4 v138, s[48:49]
	s_mov_b32 m0, s13
	s_waitcnt vmcnt(8)
	s_waitcnt lgkmcnt(0)
	s_setprio 1
	s_barrier
	v_mfma_f32_16x16x32_bf16 v[0:3], v[24:27], v[202:205], v[0:3]
	v_mfma_f32_16x16x32_bf16 v[4:7], v[112:115], v[202:205], v[4:7]
	v_mfma_f32_16x16x32_bf16 v[146:149], v[24:27], v[178:181], v[146:149]
	v_mfma_f32_16x16x32_bf16 v[150:153], v[112:115], v[178:181], v[150:153]
	v_mfma_f32_16x16x32_bf16 v[154:157], v[24:27], v[186:189], v[154:157]
	v_mfma_f32_16x16x32_bf16 v[158:161], v[112:115], v[186:189], v[158:161]
	v_mfma_f32_16x16x32_bf16 v[162:165], v[24:27], v[194:197], v[162:165]
	v_mfma_f32_16x16x32_bf16 v[166:169], v[112:115], v[194:197], v[166:169]
	v_mfma_f32_16x16x32_bf16 v[0:3], v[28:31], v[206:209], v[0:3]
	v_mfma_f32_16x16x32_bf16 v[4:7], v[116:119], v[206:209], v[4:7]
	v_mfma_f32_16x16x32_bf16 v[146:149], v[28:31], v[182:185], v[146:149]
	v_mfma_f32_16x16x32_bf16 v[150:153], v[116:119], v[182:185], v[150:153]
	v_mfma_f32_16x16x32_bf16 v[154:157], v[28:31], v[190:193], v[154:157]
	v_mfma_f32_16x16x32_bf16 v[158:161], v[116:119], v[190:193], v[158:161]
	v_mfma_f32_16x16x32_bf16 v[162:165], v[28:31], v[198:201], v[162:165]
	v_mfma_f32_16x16x32_bf16 v[166:169], v[116:119], v[198:201], v[166:169]
	v_mfma_f32_16x16x32_bf16 v[8:11], v[120:123], v[178:181], v[8:11]
	v_mfma_f32_16x16x32_bf16 v[12:15], v[170:173], v[178:181], v[12:15]
	v_mfma_f32_16x16x32_bf16 v[24:27], v[120:123], v[186:189], v[60:63]
	v_mfma_f32_16x16x32_bf16 v[28:31], v[170:173], v[186:189], v[100:103]
	v_mfma_f32_16x16x32_bf16 v[60:63], v[120:123], v[194:197], v[104:107]
	v_mfma_f32_16x16x32_bf16 v[100:103], v[170:173], v[194:197], v[108:111]
	v_mfma_f32_16x16x32_bf16 v[16:19], v[120:123], v[202:205], v[16:19]
	v_mfma_f32_16x16x32_bf16 v[20:23], v[170:173], v[202:205], v[20:23]
	v_mfma_f32_16x16x32_bf16 v[8:11], v[124:127], v[182:185], v[8:11]
	v_mfma_f32_16x16x32_bf16 v[12:15], v[174:177], v[182:185], v[12:15]
	v_mfma_f32_16x16x32_bf16 v[24:27], v[124:127], v[190:193], v[24:27]
	v_mfma_f32_16x16x32_bf16 v[28:31], v[174:177], v[190:193], v[28:31]
	v_mfma_f32_16x16x32_bf16 v[60:63], v[124:127], v[198:201], v[60:63]
	v_mfma_f32_16x16x32_bf16 v[100:103], v[174:177], v[198:201], v[100:103]
	v_mfma_f32_16x16x32_bf16 v[16:19], v[124:127], v[206:209], v[16:19]
	v_mfma_f32_16x16x32_bf16 v[20:23], v[174:177], v[206:209], v[20:23]
	s_barrier
; #define PG8_LDA(dst, b, h) do { _Pragma("unroll") for (int m = 0; m < 4; ++m) _Pragma("unroll") for (int k = 0; k < 2; ++k) dst[m][k] = *(const LAS bf16x8*)(lds + PG8_SA(b, h) + aoff + m * 2048 + k * 1024); } while (0)
; #define PG8_LDB(dst, b, h) do { _Pragma("unroll") for (int n = 0; n < 2; ++n) _Pragma("unroll") for (int k = 0; k < 2; ++k) dst[n][k] = *(const LAS bf16x8*)(lds + PG8_SB(b, h) + boff + n * 2048 + k * 1024); } while (0)
; #define PG8_MMA(ai, bj, At, Bt) do { __builtin_amdgcn_s_setprio(1); _Pragma("unroll") for (int m = 0; m < 4; ++m) _Pragma("unroll") for (int n = 0; n < 2; ++n) _Pragma("unroll") for (int k = 0; k < 2; ++k) \
;         acc[ai][bj][m][n] = __builtin_amdgcn_mfma_f32_16x16x32_bf16(Bt[n][k], At[m][k], acc[ai][bj][m][n], 0, 0, 0); __builtin_amdgcn_s_setprio(0); } while (0)
; #define PG8_WAIT_V(n) asm volatile("s_waitcnt vmcnt(" #n ")" ::: "memory")
; #define PG8_WAIT_L(n) asm volatile("s_waitcnt lgkmcnt(" #n ")" ::: "memory")
; #define PG8_BAR __builtin_amdgcn_s_barrier()
; #define PG8_SCHED __builtin_amdgcn_sched_barrier(0)
; template <class Epi, class Addr, bool ALIGN_EPI = true, class Order = StaticOrder>
; __device__ __forceinline__ void gemm_phase(LAS unsigned char* lds, const Gemm g, const Order& S, const Epi& E, const int wid) {
;     ...
;             PG8_LDB(B0, 0, 0); PG8_LDB(B1, 0, 1); PG8_SCHED; PG8_LDA(At, 0, 0); PG8_STAGE(PG8_SA(1, 1), a1 + hstepA, voffA);
;             PG8_WAIT_V(8); PG8_WAIT_L(0); PG8_BAR; PG8_MMA(0, 0, At, B0); PG8_MMA(0, 1, At, B1); PG8_BAR; PG8_SCHED;
;             PG8_LDA(At, 0, 1); PG8_STAGE(PG8_SB(0, 0), b2, voffB); PG8_STAGE(PG8_SB(0, 1), b2 + hstepB, voffB); PG8_STAGE(PG8_SA(0, 0), a2, voffA);
;             PG8_WAIT_V(8); PG8_WAIT_L(0); PG8_BAR; PG8_MMA(1, 0, At, B0); PG8_MMA(1, 1, At, B1); PG8_BAR; PG8_SCHED;
	s_setprio 0
	ds_read_b128 v[104:107], v140
	ds_read_b128 v[108:111], v140 offset:1024
	ds_read_b128 v[112:115], v140 offset:2048
	ds_read_b128 v[116:119], v140 offset:3072
	ds_read_b128 v[120:123], v141
	ds_read_b128 v[124:127], v141 offset:1024
	ds_read_b128 v[170:173], v141 offset:2048
	ds_read_b128 v[174:177], v141 offset:3072
	s_add_u32 s26, s46, 0x80
	s_addc_u32 s27, s47, 0
	ds_read_b128 v[178:181], v142
	ds_read_b128 v[182:185], v142 offset:1024
	ds_read_b128 v[186:189], v142 offset:2048
	ds_read_b128 v[190:193], v142 offset:3072
	ds_read_b128 v[194:197], v142 offset:4096
	ds_read_b128 v[198:201], v142 offset:5120
	ds_read_b128 v[202:205], v142 offset:6144
	ds_read_b128 v[206:209], v142 offset:7168
	s_add_u32 s18, s24, 0x10180
	s_addc_u32 s19, s25, 0
	s_mov_b32 s13, m0
	s_mov_b32 m0, s65
	s_nop 0
	global_load_lds_dwordx4 v136, s[18:19]
	s_mov_b32 m0, s66
	s_nop 0
	global_load_lds_dwordx4 v138, s[18:19]
	s_mov_b32 m0, s13
	s_waitcnt vmcnt(8)
	s_waitcnt lgkmcnt(0)
	s_setprio 1
	s_barrier
	v_mfma_f32_16x16x32_bf16 v[64:67], v[104:107], v[178:181], v[64:67]
	v_mfma_f32_16x16x32_bf16 v[68:71], v[112:115], v[178:181], v[68:71]
	v_mfma_f32_16x16x32_bf16 v[72:75], v[104:107], v[186:189], v[72:75]
	v_mfma_f32_16x16x32_bf16 v[76:79], v[112:115], v[186:189], v[76:79]
	v_mfma_f32_16x16x32_bf16 v[80:83], v[104:107], v[194:197], v[80:83]
	v_mfma_f32_16x16x32_bf16 v[84:87], v[112:115], v[194:197], v[84:87]
	v_mfma_f32_16x16x32_bf16 v[88:91], v[104:107], v[202:205], v[88:91]
	v_mfma_f32_16x16x32_bf16 v[64:67], v[108:111], v[182:185], v[64:67]
	v_mfma_f32_16x16x32_bf16 v[68:71], v[116:119], v[182:185], v[68:71]
	v_mfma_f32_16x16x32_bf16 v[72:75], v[108:111], v[190:193], v[72:75]
	v_mfma_f32_16x16x32_bf16 v[76:79], v[116:119], v[190:193], v[76:79]
	v_mfma_f32_16x16x32_bf16 v[80:83], v[108:111], v[198:201], v[80:83]
	v_mfma_f32_16x16x32_bf16 v[84:87], v[116:119], v[198:201], v[84:87]
	v_mfma_f32_16x16x32_bf16 v[88:91], v[108:111], v[206:209], v[88:91]
	v_mfma_f32_16x16x32_bf16 v[92:95], v[112:115], v[202:205], v[92:95]
	v_mfma_f32_16x16x32_bf16 v[210:213], v[116:119], v[206:209], v[92:95]
	v_mfma_f32_16x16x32_bf16 v[92:95], v[120:123], v[178:181], v[96:99]
	v_mfma_f32_16x16x32_bf16 v[32:35], v[170:173], v[178:181], v[32:35]
	v_mfma_f32_16x16x32_bf16 v[36:39], v[120:123], v[186:189], v[36:39]
	v_mfma_f32_16x16x32_bf16 v[40:43], v[170:173], v[186:189], v[40:43]
	v_mfma_f32_16x16x32_bf16 v[44:47], v[120:123], v[194:197], v[44:47]
	v_mfma_f32_16x16x32_bf16 v[48:51], v[170:173], v[194:197], v[48:51]
	v_mfma_f32_16x16x32_bf16 v[52:55], v[120:123], v[202:205], v[52:55]
	v_mfma_f32_16x16x32_bf16 v[96:99], v[124:127], v[182:185], v[92:95]
	v_mfma_f32_16x16x32_bf16 v[32:35], v[174:177], v[182:185], v[32:35]
	v_mfma_f32_16x16x32_bf16 v[36:39], v[124:127], v[190:193], v[36:39]
	v_mfma_f32_16x16x32_bf16 v[40:43], v[174:177], v[190:193], v[40:43]
	v_mfma_f32_16x16x32_bf16 v[44:47], v[124:127], v[198:201], v[44:47]
	v_mfma_f32_16x16x32_bf16 v[48:51], v[174:177], v[198:201], v[48:51]
	v_mfma_f32_16x16x32_bf16 v[178:181], v[124:127], v[206:209], v[52:55]
	v_mfma_f32_16x16x32_bf16 v[52:55], v[170:173], v[202:205], v[56:59]
	v_mfma_f32_16x16x32_bf16 v[182:185], v[174:177], v[206:209], v[52:55]
	s_barrier
	s_setprio 0
	s_nop 4
	ds_read_b128 v[52:55], v142 offset:16384
	ds_read_b128 v[56:59], v142 offset:17408
	ds_read_b128 v[92:95], v142 offset:18432
	ds_read_b128 v[186:189], v142 offset:19456
	ds_read_b128 v[190:193], v142 offset:20480
	ds_read_b128 v[194:197], v142 offset:21504
	ds_read_b128 v[198:201], v142 offset:22528
	ds_read_b128 v[202:205], v142 offset:23552
	s_mov_b32 s13, m0
	s_mov_b32 m0, s41
	s_nop 0
	global_load_lds_dwordx4 v137, s[44:45]
	s_mov_b32 m0, s43
	s_nop 0
	global_load_lds_dwordx4 v139, s[44:45]
	s_mov_b32 m0, s13
	s_add_u32 s18, s44, 0x400000
	s_addc_u32 s19, s45, 0
	s_mov_b32 s13, m0
	s_mov_b32 m0, s52
	s_nop 0
	global_load_lds_dwordx4 v137, s[18:19]
	s_mov_b32 m0, s53
	s_nop 0
	global_load_lds_dwordx4 v139, s[18:19]
	s_mov_b32 m0, s13
	s_nop 0
	s_mov_b32 s13, m0
	s_mov_b32 m0, s40
	s_nop 0
	global_load_lds_dwordx4 v136, s[46:47]
	s_mov_b32 m0, s54
	s_nop 0
	global_load_lds_dwordx4 v138, s[46:47]
	s_mov_b32 m0, s13
	s_waitcnt vmcnt(8)
	s_waitcnt lgkmcnt(0)
	s_setprio 1
	s_barrier
	v_mfma_f32_16x16x32_bf16 v[0:3], v[104:107], v[198:201], v[0:3]
	v_mfma_f32_16x16x32_bf16 v[4:7], v[112:115], v[198:201], v[4:7]
	v_mfma_f32_16x16x32_bf16 v[146:149], v[104:107], v[52:55], v[146:149]
	v_mfma_f32_16x16x32_bf16 v[150:153], v[112:115], v[52:55], v[150:153]
	v_mfma_f32_16x16x32_bf16 v[154:157], v[104:107], v[92:95], v[154:157]
	v_mfma_f32_16x16x32_bf16 v[158:161], v[112:115], v[92:95], v[158:161]
	v_mfma_f32_16x16x32_bf16 v[162:165], v[104:107], v[190:193], v[162:165]
	v_mfma_f32_16x16x32_bf16 v[166:169], v[112:115], v[190:193], v[166:169]
	v_mfma_f32_16x16x32_bf16 v[0:3], v[108:111], v[202:205], v[0:3]
	v_mfma_f32_16x16x32_bf16 v[4:7], v[116:119], v[202:205], v[4:7]
	v_mfma_f32_16x16x32_bf16 v[146:149], v[108:111], v[56:59], v[146:149]
	v_mfma_f32_16x16x32_bf16 v[150:153], v[116:119], v[56:59], v[150:153]
	v_mfma_f32_16x16x32_bf16 v[154:157], v[108:111], v[186:189], v[154:157]
	v_mfma_f32_16x16x32_bf16 v[158:161], v[116:119], v[186:189], v[158:161]
	v_mfma_f32_16x16x32_bf16 v[162:165], v[108:111], v[194:197], v[162:165]
	v_mfma_f32_16x16x32_bf16 v[166:169], v[116:119], v[194:197], v[166:169]
	v_mfma_f32_16x16x32_bf16 v[12:15], v[170:173], v[52:55], v[12:15]
	v_mfma_f32_16x16x32_bf16 v[206:209], v[174:177], v[56:59], v[12:15]
	v_mfma_f32_16x16x32_bf16 v[12:15], v[120:123], v[92:95], v[24:27]
	v_mfma_f32_16x16x32_bf16 v[24:27], v[124:127], v[186:189], v[12:15]
	v_mfma_f32_16x16x32_bf16 v[12:15], v[170:173], v[92:95], v[28:31]
	v_mfma_f32_16x16x32_bf16 v[186:189], v[174:177], v[186:189], v[12:15]
	v_mfma_f32_16x16x32_bf16 v[12:15], v[120:123], v[190:193], v[60:63]
	v_mfma_f32_16x16x32_bf16 v[214:217], v[124:127], v[194:197], v[12:15]
	v_mfma_f32_16x16x32_bf16 v[12:15], v[170:173], v[190:193], v[100:103]
	v_mfma_f32_16x16x32_bf16 v[8:11], v[120:123], v[52:55], v[8:11]
	v_mfma_f32_16x16x32_bf16 v[190:193], v[174:177], v[194:197], v[12:15]
	v_mfma_f32_16x16x32_bf16 v[12:15], v[120:123], v[198:201], v[16:19]
	v_mfma_f32_16x16x32_bf16 v[8:11], v[124:127], v[56:59], v[8:11]
	v_mfma_f32_16x16x32_bf16 v[194:197], v[124:127], v[202:205], v[12:15]
	v_mfma_f32_16x16x32_bf16 v[12:15], v[170:173], v[198:201], v[20:23]
	v_mfma_f32_16x16x32_bf16 v[170:173], v[174:177], v[202:205], v[12:15]
	s_barrier
; #define PG8_LDA(dst, b, h) do { _Pragma("unroll") for (int m = 0; m < 4; ++m) _Pragma("unroll") for (int k = 0; k < 2; ++k) dst[m][k] = *(const LAS bf16x8*)(lds + PG8_SA(b, h) + aoff + m * 2048 + k * 1024); } while (0)
; #define PG8_LDB(dst, b, h) do { _Pragma("unroll") for (int n = 0; n < 2; ++n) _Pragma("unroll") for (int k = 0; k < 2; ++k) dst[n][k] = *(const LAS bf16x8*)(lds + PG8_SB(b, h) + boff + n * 2048 + k * 1024); } while (0)
; #define PG8_MMA(ai, bj, At, Bt) do { __builtin_amdgcn_s_setprio(1); _Pragma("unroll") for (int m = 0; m < 4; ++m) _Pragma("unroll") for (int n = 0; n < 2; ++n) _Pragma("unroll") for (int k = 0; k < 2; ++k) \
;         acc[ai][bj][m][n] = __builtin_amdgcn_mfma_f32_16x16x32_bf16(Bt[n][k], At[m][k], acc[ai][bj][m][n], 0, 0, 0); __builtin_amdgcn_s_setprio(0); } while (0)
; #define PG8_WAIT_V(n) asm volatile("s_waitcnt vmcnt(" #n ")" ::: "memory")
; #define PG8_WAIT_L(n) asm volatile("s_waitcnt lgkmcnt(" #n ")" ::: "memory")
; #define PG8_BAR __builtin_amdgcn_s_barrier()
; #define PG8_SCHED __builtin_amdgcn_sched_barrier(0)
; template <class Epi, class Addr, bool ALIGN_EPI = true, class Order = StaticOrder>
; __device__ __forceinline__ void gemm_phase(LAS unsigned char* lds, const Gemm g, const Order& S, const Epi& E, const int wid) {
;     ...
;             PG8_WAIT_V(8); PG8_WAIT_L(0); PG8_BAR; PG8_MMA(1, 0, At, B0); PG8_MMA(1, 1, At, B1); PG8_BAR; PG8_SCHED;
;             PG8_LDB(B0, 1, 0); PG8_LDB(B1, 1, 1); PG8_SCHED; PG8_LDA(At, 1, 0); PG8_STAGE(PG8_SA(0, 1), a2 + hstepA, voffA);
;             PG8_WAIT_V(8); PG8_WAIT_L(0); PG8_BAR; PG8_MMA(0, 0, At, B0); PG8_MMA(0, 1, At, B1); PG8_BAR; PG8_SCHED;
;             PG8_LDA(At, 1, 1); PG8_STAGE(PG8_SB(1, 0), b3, voffB); PG8_STAGE(PG8_SB(1, 1), b3 + hstepB, voffB); PG8_STAGE(PG8_SA(1, 0), a3, voffA);
;             PG8_WAIT_V(8); PG8_WAIT_L(0); PG8_BAR; PG8_MMA(1, 0, At, B0); PG8_MMA(1, 1, At, B1); PG8_BAR; PG8_SCHED;
;         }
;         if constexpr (ALIGN_EPI) { if (wr == 0) PG8_BAR; }
	s_setprio 0
	s_nop 4
	ds_read_b128 v[12:15], v143
	ds_read_b128 v[16:19], v143 offset:1024
	ds_read_b128 v[174:177], v143 offset:2048
	ds_read_b128 v[198:201], v143 offset:3072
	ds_read_b128 v[202:205], v144
	ds_read_b128 v[218:221], v144 offset:1024
	ds_read_b128 v[222:225], v144 offset:2048
	ds_read_b128 v[226:229], v144 offset:3072
	ds_read_b128 v[20:23], v142 offset:32768
	ds_read_b128 v[28:31], v142 offset:33792
	ds_read_b128 v[56:59], v142 offset:34816
	ds_read_b128 v[230:233], v142 offset:35840
	ds_read_b128 v[234:237], v142 offset:36864
	ds_read_b128 v[238:241], v142 offset:37888
	ds_read_b128 v[242:245], v142 offset:38912
	ds_read_b128 v[246:249], v142 offset:39936
	s_add_u32 s18, s46, 0x10000
	s_addc_u32 s19, s47, 0
	s_mov_b32 s13, m0
	s_mov_b32 m0, s55
	s_nop 0
	global_load_lds_dwordx4 v136, s[18:19]
	s_mov_b32 m0, s56
	s_nop 0
	global_load_lds_dwordx4 v138, s[18:19]
	s_mov_b32 m0, s13
	s_waitcnt vmcnt(8)
	s_waitcnt lgkmcnt(0)
	s_setprio 1
	s_barrier
	v_mfma_f32_16x16x32_bf16 v[52:55], v[12:15], v[20:23], v[64:67]
	v_mfma_f32_16x16x32_bf16 v[120:123], v[16:19], v[28:31], v[52:55]
	v_mfma_f32_16x16x32_bf16 v[52:55], v[174:177], v[20:23], v[68:71]
	v_mfma_f32_16x16x32_bf16 v[112:115], v[198:201], v[28:31], v[52:55]
	v_mfma_f32_16x16x32_bf16 v[52:55], v[12:15], v[56:59], v[72:75]
	v_mfma_f32_16x16x32_bf16 v[108:111], v[16:19], v[230:233], v[52:55]
	v_mfma_f32_16x16x32_bf16 v[52:55], v[174:177], v[56:59], v[76:79]
	v_mfma_f32_16x16x32_bf16 v[100:103], v[198:201], v[230:233], v[52:55]
	v_mfma_f32_16x16x32_bf16 v[52:55], v[12:15], v[234:237], v[80:83]
	v_mfma_f32_16x16x32_bf16 v[92:95], v[16:19], v[238:241], v[52:55]
	v_mfma_f32_16x16x32_bf16 v[52:55], v[174:177], v[234:237], v[84:87]
	v_mfma_f32_16x16x32_bf16 v[84:87], v[198:201], v[238:241], v[52:55]
	v_mfma_f32_16x16x32_bf16 v[52:55], v[12:15], v[242:245], v[88:91]
	v_mfma_f32_16x16x32_bf16 v[60:63], v[16:19], v[246:249], v[52:55]
	v_mfma_f32_16x16x32_bf16 v[52:55], v[174:177], v[242:245], v[210:213]
	v_mfma_f32_16x16x32_bf16 v[52:55], v[198:201], v[246:249], v[52:55]
	v_mfma_f32_16x16x32_bf16 v[64:67], v[202:205], v[20:23], v[96:99]
	v_mfma_f32_16x16x32_bf16 v[20:23], v[222:225], v[20:23], v[32:35]
	v_mfma_f32_16x16x32_bf16 v[116:119], v[226:229], v[28:31], v[20:23]
	v_mfma_f32_16x16x32_bf16 v[20:23], v[202:205], v[56:59], v[36:39]
	v_mfma_f32_16x16x32_bf16 v[104:107], v[218:221], v[230:233], v[20:23]
	v_mfma_f32_16x16x32_bf16 v[20:23], v[222:225], v[56:59], v[40:43]
	v_mfma_f32_16x16x32_bf16 v[96:99], v[226:229], v[230:233], v[20:23]
	v_mfma_f32_16x16x32_bf16 v[20:23], v[202:205], v[234:237], v[44:47]
	v_mfma_f32_16x16x32_bf16 v[88:91], v[218:221], v[238:241], v[20:23]
	v_mfma_f32_16x16x32_bf16 v[20:23], v[222:225], v[234:237], v[48:51]
	v_mfma_f32_16x16x32_bf16 v[80:83], v[226:229], v[238:241], v[20:23]
	v_mfma_f32_16x16x32_bf16 v[20:23], v[202:205], v[242:245], v[178:181]
	v_mfma_f32_16x16x32_bf16 v[56:59], v[218:221], v[246:249], v[20:23]
	v_mfma_f32_16x16x32_bf16 v[20:23], v[222:225], v[242:245], v[182:185]
	v_mfma_f32_16x16x32_bf16 v[124:127], v[218:221], v[28:31], v[64:67]
	v_mfma_f32_16x16x32_bf16 v[48:51], v[226:229], v[246:249], v[20:23]
	s_barrier
	s_setprio 0
	ds_read_b128 v[32:35], v142 offset:49152
	ds_read_b128 v[40:43], v142 offset:50176
	ds_read_b128 v[178:181], v142 offset:51200
	ds_read_b128 v[182:185], v142 offset:52224
	ds_read_b128 v[210:213], v142 offset:53248
	ds_read_b128 v[230:233], v142 offset:54272
	ds_read_b128 v[234:237], v142 offset:55296
	ds_read_b128 v[238:241], v142 offset:56320
	s_add_u32 s18, s44, 0x80
	s_addc_u32 s19, s45, 0
	s_mov_b32 s13, m0
	s_mov_b32 m0, s59
	s_nop 0
	global_load_lds_dwordx4 v137, s[18:19]
	s_mov_b32 m0, s60
	s_nop 0
	global_load_lds_dwordx4 v139, s[18:19]
	s_mov_b32 m0, s13
	s_add_u32 s18, s44, 0x400080
	s_addc_u32 s19, s45, 0
	s_mov_b32 s13, m0
	s_mov_b32 m0, s63
	s_nop 0
	global_load_lds_dwordx4 v137, s[18:19]
	s_mov_b32 m0, s64
	s_nop 0
	global_load_lds_dwordx4 v139, s[18:19]
	s_mov_b32 m0, s13
	s_nop 0
	s_mov_b32 s13, m0
	s_mov_b32 m0, s61
	s_nop 0
	global_load_lds_dwordx4 v136, s[26:27]
	s_mov_b32 m0, s62
	s_nop 0
	global_load_lds_dwordx4 v138, s[26:27]
	s_mov_b32 m0, s13
	s_waitcnt vmcnt(8)
	s_waitcnt lgkmcnt(0)
	s_setprio 1
	s_barrier
	v_mfma_f32_16x16x32_bf16 v[20:23], v[12:15], v[32:35], v[146:149]
	v_mfma_f32_16x16x32_bf16 v[76:79], v[16:19], v[40:43], v[20:23]
	v_mfma_f32_16x16x32_bf16 v[20:23], v[174:177], v[32:35], v[150:153]
	v_mfma_f32_16x16x32_bf16 v[68:71], v[198:201], v[40:43], v[20:23]
	v_mfma_f32_16x16x32_bf16 v[20:23], v[12:15], v[178:181], v[154:157]
	v_mfma_f32_16x16x32_bf16 v[44:47], v[16:19], v[182:185], v[20:23]
	v_mfma_f32_16x16x32_bf16 v[20:23], v[174:177], v[178:181], v[158:161]
	v_mfma_f32_16x16x32_bf16 v[36:39], v[198:201], v[182:185], v[20:23]
	v_mfma_f32_16x16x32_bf16 v[20:23], v[12:15], v[210:213], v[162:165]
	v_mfma_f32_16x16x32_bf16 v[0:3], v[12:15], v[234:237], v[0:3]
	v_mfma_f32_16x16x32_bf16 v[28:31], v[16:19], v[230:233], v[20:23]
	v_mfma_f32_16x16x32_bf16 v[20:23], v[174:177], v[210:213], v[166:169]
	v_mfma_f32_16x16x32_bf16 v[12:15], v[16:19], v[238:241], v[0:3]
	v_mfma_f32_16x16x32_bf16 v[0:3], v[174:177], v[234:237], v[4:7]
	v_mfma_f32_16x16x32_bf16 v[20:23], v[198:201], v[230:233], v[20:23]
	v_mfma_f32_16x16x32_bf16 v[4:7], v[198:201], v[238:241], v[0:3]
	v_mfma_f32_16x16x32_bf16 v[0:3], v[202:205], v[32:35], v[8:11]
	v_mfma_f32_16x16x32_bf16 v[72:75], v[218:221], v[40:43], v[0:3]
	v_mfma_f32_16x16x32_bf16 v[0:3], v[222:225], v[32:35], v[206:209]
	v_mfma_f32_16x16x32_bf16 v[64:67], v[226:229], v[40:43], v[0:3]
	v_mfma_f32_16x16x32_bf16 v[0:3], v[202:205], v[178:181], v[24:27]
	v_mfma_f32_16x16x32_bf16 v[40:43], v[218:221], v[182:185], v[0:3]
	v_mfma_f32_16x16x32_bf16 v[0:3], v[222:225], v[178:181], v[186:189]
	v_mfma_f32_16x16x32_bf16 v[32:35], v[226:229], v[182:185], v[0:3]
	v_mfma_f32_16x16x32_bf16 v[0:3], v[202:205], v[210:213], v[214:217]
	v_mfma_f32_16x16x32_bf16 v[24:27], v[218:221], v[230:233], v[0:3]
	v_mfma_f32_16x16x32_bf16 v[0:3], v[222:225], v[210:213], v[190:193]
	v_mfma_f32_16x16x32_bf16 v[16:19], v[226:229], v[230:233], v[0:3]
	v_mfma_f32_16x16x32_bf16 v[0:3], v[202:205], v[234:237], v[194:197]
	v_mfma_f32_16x16x32_bf16 v[8:11], v[218:221], v[238:241], v[0:3]
	v_mfma_f32_16x16x32_bf16 v[0:3], v[222:225], v[234:237], v[170:173]
	v_mfma_f32_16x16x32_bf16 v[0:3], v[226:229], v[238:241], v[0:3]
	s_barrier
	s_setprio 0
	s_andn2_b64 vcc, exec, s[8:9]
	s_cbranch_vccnz .LBB0_269
	s_barrier

; #define PG8_LDA(dst, b, h) do { _Pragma("unroll") for (int m = 0; m < 4; ++m) _Pragma("unroll") for (int k = 0; k < 2; ++k) dst[m][k] = *(const LAS bf16x8*)(lds + PG8_SA(b, h) + aoff + m * 2048 + k * 1024); } while (0)
; #define PG8_LDB(dst, b, h) do { _Pragma("unroll") for (int n = 0; n < 2; ++n) _Pragma("unroll") for (int k = 0; k < 2; ++k) dst[n][k] = *(const LAS bf16x8*)(lds + PG8_SB(b, h) + boff + n * 2048 + k * 1024); } while (0)
; #define PG8_MMA(ai, bj, At, Bt) do { __builtin_amdgcn_s_setprio(1); _Pragma("unroll") for (int m = 0; m < 4; ++m) _Pragma("unroll") for (int n = 0; n < 2; ++n) _Pragma("unroll") for (int k = 0; k < 2; ++k) \
;         acc[ai][bj][m][n] = __builtin_amdgcn_mfma_f32_16x16x32_bf16(Bt[n][k], At[m][k], acc[ai][bj][m][n], 0, 0, 0); __builtin_amdgcn_s_setprio(0); } while (0)
; #define PG8_WAIT_V(n) asm volatile("s_waitcnt vmcnt(" #n ")" ::: "memory")
; #define PG8_WAIT_L(n) asm volatile("s_waitcnt lgkmcnt(" #n ")" ::: "memory")
; #define PG8_BAR __builtin_amdgcn_s_barrier()
; template <class Epi, class Addr, bool ALIGN_EPI = true, class Order = StaticOrder>
; __device__ __forceinline__ void gemm_phase(LAS unsigned char* lds, const Gemm g, const Order& S, const Epi& E, const int wid) {
;     ...
;         for (int t = 0; t < nt; t += 2) {
;             const bool last = (t == nt - 2);
;             const char* a1 = cA + (size_t)(t + 1) * kstep;
;             const char* a2 = last ? nA : cA + (size_t)(t + 2) * kstep; const char* b2 = last ? nB : cB + (size_t)(t + 2) * kstep;
;             const char* a3 = a2 + kstep; const char* b3 = b2 + kstep;
;             PG8_LDB(B0, 0, 0); PG8_LDB(B1, 0, 1); PG8_SCHED; PG8_LDA(At, 0, 0); PG8_STAGE(PG8_SA(1, 1), a1 + hstepA, voffA);
;             PG8_WAIT_V(8); PG8_WAIT_L(0); PG8_BAR; PG8_MMA(0, 0, At, B0); PG8_MMA(0, 1, At, B1); PG8_BAR; PG8_SCHED;
;             PG8_LDA(At, 0, 1); PG8_STAGE(PG8_SB(0, 0), b2, voffB); PG8_STAGE(PG8_SB(0, 1), b2 + hstepB, voffB); PG8_STAGE(PG8_SA(0, 0), a2, voffA);
;             PG8_WAIT_V(8); PG8_WAIT_L(0); PG8_BAR; PG8_MMA(1, 0, At, B0); PG8_MMA(1, 1, At, B1); PG8_BAR; PG8_SCHED;
;             PG8_LDB(B0, 1, 0); PG8_LDB(B1, 1, 1); PG8_SCHED; PG8_LDA(At, 1, 0); PG8_STAGE(PG8_SA(0, 1), a2 + hstepA, voffA);
;             PG8_WAIT_V(8); PG8_WAIT_L(0); PG8_BAR; PG8_MMA(0, 0, At, B0); PG8_MMA(0, 1, At, B1); PG8_BAR; PG8_SCHED;
.LBB0_559:
	s_add_u32 s44, s26, 0x100
	ds_read_b128 v[146:149], v140
	ds_read_b128 v[150:153], v140 offset:1024
	ds_read_b128 v[154:157], v140 offset:2048
	ds_read_b128 v[158:161], v140 offset:3072
	ds_read_b128 v[162:165], v141
	ds_read_b128 v[166:169], v141 offset:1024
	ds_read_b128 v[170:173], v141 offset:2048
	ds_read_b128 v[174:177], v141 offset:3072
	s_addc_u32 s45, s27, 0
	s_add_u32 s18, s22, s26
	s_addc_u32 s19, s23, s27
	s_add_u32 s25, s18, 0x100
	s_addc_u32 s26, s19, 0
	s_cmp_eq_u32 s17, 4
	s_cselect_b32 s48, s15, s25
	s_cselect_b32 s49, s13, s26
	s_cselect_b32 s25, 0, s45
	s_cselect_b32 s36, 0, s44
	s_add_u32 s26, s48, 0x80
	s_addc_u32 s27, s49, 0
	s_add_u32 s46, s6, s36
	s_addc_u32 s47, s7, s25
	ds_read_b128 v[178:181], v142
	ds_read_b128 v[182:185], v142 offset:1024
	ds_read_b128 v[186:189], v142 offset:2048
	ds_read_b128 v[190:193], v142 offset:3072
	ds_read_b128 v[194:197], v142 offset:4096
	ds_read_b128 v[198:201], v142 offset:5120
	ds_read_b128 v[202:205], v142 offset:6144
	ds_read_b128 v[206:209], v142 offset:7168
	s_add_u32 s18, s18, 0x100080
	s_addc_u32 s19, s19, 0
	s_mov_b32 s25, m0
	s_mov_b32 m0, s64
	s_nop 0
	global_load_lds_dwordx4 v136, s[18:19]
	s_mov_b32 m0, s65
	s_nop 0
	global_load_lds_dwordx4 v138, s[18:19]
	s_mov_b32 m0, s25
	s_waitcnt vmcnt(8)
	s_waitcnt lgkmcnt(0)
	s_setprio 1
	s_barrier
	v_mfma_f32_16x16x32_bf16 v[124:127], v[146:149], v[178:181], v[124:127]
	v_mfma_f32_16x16x32_bf16 v[120:123], v[154:157], v[178:181], v[120:123]
	v_mfma_f32_16x16x32_bf16 v[116:119], v[146:149], v[186:189], v[116:119]
	v_mfma_f32_16x16x32_bf16 v[108:111], v[154:157], v[186:189], v[108:111]
	v_mfma_f32_16x16x32_bf16 v[100:103], v[146:149], v[194:197], v[100:103]
	v_mfma_f32_16x16x32_bf16 v[92:95], v[154:157], v[194:197], v[92:95]
	v_mfma_f32_16x16x32_bf16 v[84:87], v[146:149], v[202:205], v[84:87]
	v_mfma_f32_16x16x32_bf16 v[76:79], v[154:157], v[202:205], v[76:79]
	v_mfma_f32_16x16x32_bf16 v[124:127], v[150:153], v[182:185], v[124:127]
	v_mfma_f32_16x16x32_bf16 v[120:123], v[158:161], v[182:185], v[120:123]
	v_mfma_f32_16x16x32_bf16 v[116:119], v[150:153], v[190:193], v[116:119]
	v_mfma_f32_16x16x32_bf16 v[108:111], v[158:161], v[190:193], v[108:111]
	v_mfma_f32_16x16x32_bf16 v[100:103], v[150:153], v[198:201], v[100:103]
	v_mfma_f32_16x16x32_bf16 v[92:95], v[158:161], v[198:201], v[92:95]
	v_mfma_f32_16x16x32_bf16 v[84:87], v[150:153], v[206:209], v[84:87]
	v_mfma_f32_16x16x32_bf16 v[76:79], v[158:161], v[206:209], v[76:79]
	v_mfma_f32_16x16x32_bf16 v[112:115], v[162:165], v[178:181], v[112:115]
	v_mfma_f32_16x16x32_bf16 v[104:107], v[170:173], v[178:181], v[104:107]
	v_mfma_f32_16x16x32_bf16 v[96:99], v[162:165], v[186:189], v[96:99]
	v_mfma_f32_16x16x32_bf16 v[88:91], v[170:173], v[186:189], v[88:91]
	v_mfma_f32_16x16x32_bf16 v[80:83], v[162:165], v[194:197], v[80:83]
	v_mfma_f32_16x16x32_bf16 v[72:75], v[170:173], v[194:197], v[72:75]
	v_mfma_f32_16x16x32_bf16 v[68:71], v[162:165], v[202:205], v[68:71]
	v_mfma_f32_16x16x32_bf16 v[64:67], v[170:173], v[202:205], v[64:67]
	v_mfma_f32_16x16x32_bf16 v[112:115], v[166:169], v[182:185], v[112:115]
	v_mfma_f32_16x16x32_bf16 v[104:107], v[174:177], v[182:185], v[104:107]
	v_mfma_f32_16x16x32_bf16 v[96:99], v[166:169], v[190:193], v[96:99]
	v_mfma_f32_16x16x32_bf16 v[88:91], v[174:177], v[190:193], v[88:91]
	v_mfma_f32_16x16x32_bf16 v[80:83], v[166:169], v[198:201], v[80:83]
	v_mfma_f32_16x16x32_bf16 v[72:75], v[174:177], v[198:201], v[72:75]
	v_mfma_f32_16x16x32_bf16 v[68:71], v[166:169], v[206:209], v[68:71]
	v_mfma_f32_16x16x32_bf16 v[64:67], v[174:177], v[206:209], v[64:67]
	s_barrier
	s_setprio 0
	ds_read_b128 v[178:181], v142 offset:16384
	ds_read_b128 v[182:185], v142 offset:17408
	ds_read_b128 v[186:189], v142 offset:18432
	ds_read_b128 v[190:193], v142 offset:19456
	ds_read_b128 v[194:197], v142 offset:20480
	ds_read_b128 v[198:201], v142 offset:21504
	ds_read_b128 v[202:205], v142 offset:22528
	ds_read_b128 v[206:209], v142 offset:23552
	s_mov_b32 s18, m0
	s_mov_b32 m0, s41
	s_nop 0
	global_load_lds_dwordx4 v137, s[46:47]
	s_mov_b32 m0, s43
	s_nop 0
	global_load_lds_dwordx4 v139, s[46:47]
	s_mov_b32 m0, s18
	s_add_u32 s18, s46, 0x20000
	s_addc_u32 s19, s47, 0
	s_mov_b32 s25, m0
	s_mov_b32 m0, s50
	s_nop 0
	global_load_lds_dwordx4 v137, s[18:19]
	s_mov_b32 m0, s51
	s_nop 0
	global_load_lds_dwordx4 v139, s[18:19]
	s_mov_b32 m0, s25
	s_mov_b32 s18, m0
	s_mov_b32 m0, s39
	s_nop 0
	global_load_lds_dwordx4 v136, s[48:49]
	s_mov_b32 m0, s52
	s_nop 0
	global_load_lds_dwordx4 v138, s[48:49]
	s_mov_b32 m0, s18
	s_waitcnt vmcnt(8)
	s_waitcnt lgkmcnt(0)
	s_setprio 1
	s_barrier
; #define PG8_LDA(dst, b, h) do { _Pragma("unroll") for (int m = 0; m < 4; ++m) _Pragma("unroll") for (int k = 0; k < 2; ++k) dst[m][k] = *(const LAS bf16x8*)(lds + PG8_SA(b, h) + aoff + m * 2048 + k * 1024); } while (0)
; #define PG8_MMA(ai, bj, At, Bt) do { __builtin_amdgcn_s_setprio(1); _Pragma("unroll") for (int m = 0; m < 4; ++m) _Pragma("unroll") for (int n = 0; n < 2; ++n) _Pragma("unroll") for (int k = 0; k < 2; ++k) \
;         acc[ai][bj][m][n] = __builtin_amdgcn_mfma_f32_16x16x32_bf16(Bt[n][k], At[m][k], acc[ai][bj][m][n], 0, 0, 0); __builtin_amdgcn_s_setprio(0); } while (0)
; #define PG8_WAIT_V(n) asm volatile("s_waitcnt vmcnt(" #n ")" ::: "memory")
; #define PG8_WAIT_L(n) asm volatile("s_waitcnt lgkmcnt(" #n ")" ::: "memory")
; #define PG8_BAR __builtin_amdgcn_s_barrier()
; #define PG8_SCHED __builtin_amdgcn_sched_barrier(0)
; template <class Epi, class Addr, bool ALIGN_EPI = true, class Order = StaticOrder>
; __device__ __forceinline__ void gemm_phase(LAS unsigned char* lds, const Gemm g, const Order& S, const Epi& E, const int wid) {
;     ...
;             PG8_WAIT_V(8); PG8_WAIT_L(0); PG8_BAR; PG8_MMA(0, 0, At, B0); PG8_MMA(0, 1, At, B1); PG8_BAR; PG8_SCHED;
;             PG8_LDA(At, 1, 1); PG8_STAGE(PG8_SB(1, 0), b3, voffB); PG8_STAGE(PG8_SB(1, 1), b3 + hstepB, voffB); PG8_STAGE(PG8_SA(1, 0), a3, voffA);
;             PG8_WAIT_V(8); PG8_WAIT_L(0); PG8_BAR; PG8_MMA(1, 0, At, B0); PG8_MMA(1, 1, At, B1); PG8_BAR; PG8_SCHED;
	v_mfma_f32_16x16x32_bf16 v[60:63], v[146:149], v[178:181], v[60:63]
	v_mfma_f32_16x16x32_bf16 v[56:59], v[154:157], v[178:181], v[56:59]
	v_mfma_f32_16x16x32_bf16 v[52:55], v[146:149], v[186:189], v[52:55]
	v_mfma_f32_16x16x32_bf16 v[44:47], v[154:157], v[186:189], v[44:47]
	v_mfma_f32_16x16x32_bf16 v[36:39], v[146:149], v[194:197], v[36:39]
	v_mfma_f32_16x16x32_bf16 v[28:31], v[154:157], v[194:197], v[28:31]
	v_mfma_f32_16x16x32_bf16 v[20:23], v[146:149], v[202:205], v[20:23]
	v_mfma_f32_16x16x32_bf16 v[12:15], v[154:157], v[202:205], v[12:15]
	v_mfma_f32_16x16x32_bf16 v[60:63], v[150:153], v[182:185], v[60:63]
	v_mfma_f32_16x16x32_bf16 v[56:59], v[158:161], v[182:185], v[56:59]
	v_mfma_f32_16x16x32_bf16 v[52:55], v[150:153], v[190:193], v[52:55]
	v_mfma_f32_16x16x32_bf16 v[44:47], v[158:161], v[190:193], v[44:47]
	v_mfma_f32_16x16x32_bf16 v[36:39], v[150:153], v[198:201], v[36:39]
	v_mfma_f32_16x16x32_bf16 v[28:31], v[158:161], v[198:201], v[28:31]
	v_mfma_f32_16x16x32_bf16 v[20:23], v[150:153], v[206:209], v[20:23]
	v_mfma_f32_16x16x32_bf16 v[12:15], v[158:161], v[206:209], v[12:15]
	v_mfma_f32_16x16x32_bf16 v[48:51], v[162:165], v[178:181], v[48:51]
	v_mfma_f32_16x16x32_bf16 v[40:43], v[170:173], v[178:181], v[40:43]
	v_mfma_f32_16x16x32_bf16 v[32:35], v[162:165], v[186:189], v[32:35]
	v_mfma_f32_16x16x32_bf16 v[24:27], v[170:173], v[186:189], v[24:27]
	v_mfma_f32_16x16x32_bf16 v[16:19], v[162:165], v[194:197], v[16:19]
	v_mfma_f32_16x16x32_bf16 v[8:11], v[170:173], v[194:197], v[8:11]
	v_mfma_f32_16x16x32_bf16 v[4:7], v[162:165], v[202:205], v[4:7]
	v_mfma_f32_16x16x32_bf16 v[0:3], v[170:173], v[202:205], v[0:3]
	v_mfma_f32_16x16x32_bf16 v[48:51], v[166:169], v[182:185], v[48:51]
	v_mfma_f32_16x16x32_bf16 v[40:43], v[174:177], v[182:185], v[40:43]
	v_mfma_f32_16x16x32_bf16 v[32:35], v[166:169], v[190:193], v[32:35]
	v_mfma_f32_16x16x32_bf16 v[24:27], v[174:177], v[190:193], v[24:27]
	v_mfma_f32_16x16x32_bf16 v[16:19], v[166:169], v[198:201], v[16:19]
	v_mfma_f32_16x16x32_bf16 v[8:11], v[174:177], v[198:201], v[8:11]
	v_mfma_f32_16x16x32_bf16 v[4:7], v[166:169], v[206:209], v[4:7]
	v_mfma_f32_16x16x32_bf16 v[0:3], v[174:177], v[206:209], v[0:3]
	s_barrier
	s_setprio 0
	ds_read_b128 v[146:149], v143
	ds_read_b128 v[150:153], v143 offset:1024
	ds_read_b128 v[154:157], v143 offset:2048
	ds_read_b128 v[158:161], v143 offset:3072
	ds_read_b128 v[162:165], v144
	ds_read_b128 v[166:169], v144 offset:1024
	ds_read_b128 v[170:173], v144 offset:2048
	ds_read_b128 v[174:177], v144 offset:3072
	ds_read_b128 v[178:181], v142 offset:32768
	ds_read_b128 v[182:185], v142 offset:33792
	ds_read_b128 v[186:189], v142 offset:34816
	ds_read_b128 v[190:193], v142 offset:35840
	ds_read_b128 v[194:197], v142 offset:36864
	ds_read_b128 v[198:201], v142 offset:37888
	ds_read_b128 v[202:205], v142 offset:38912
	ds_read_b128 v[206:209], v142 offset:39936
	s_add_u32 s18, s48, 0x100000
	s_addc_u32 s19, s49, 0
	s_mov_b32 s25, m0
	s_mov_b32 m0, s53
	s_nop 0
	global_load_lds_dwordx4 v136, s[18:19]
	s_mov_b32 m0, s54
	s_nop 0
	global_load_lds_dwordx4 v138, s[18:19]
	s_mov_b32 m0, s25
	s_waitcnt vmcnt(8)
	s_waitcnt lgkmcnt(0)
	s_setprio 1
	s_barrier
	v_mfma_f32_16x16x32_bf16 v[124:127], v[146:149], v[178:181], v[124:127]
	v_mfma_f32_16x16x32_bf16 v[120:123], v[154:157], v[178:181], v[120:123]
	v_mfma_f32_16x16x32_bf16 v[116:119], v[146:149], v[186:189], v[116:119]
	v_mfma_f32_16x16x32_bf16 v[108:111], v[154:157], v[186:189], v[108:111]
	v_mfma_f32_16x16x32_bf16 v[100:103], v[146:149], v[194:197], v[100:103]
	v_mfma_f32_16x16x32_bf16 v[92:95], v[154:157], v[194:197], v[92:95]
	v_mfma_f32_16x16x32_bf16 v[84:87], v[146:149], v[202:205], v[84:87]
	v_mfma_f32_16x16x32_bf16 v[76:79], v[154:157], v[202:205], v[76:79]
	v_mfma_f32_16x16x32_bf16 v[124:127], v[150:153], v[182:185], v[124:127]
	v_mfma_f32_16x16x32_bf16 v[120:123], v[158:161], v[182:185], v[120:123]
	v_mfma_f32_16x16x32_bf16 v[116:119], v[150:153], v[190:193], v[116:119]
	v_mfma_f32_16x16x32_bf16 v[108:111], v[158:161], v[190:193], v[108:111]
	v_mfma_f32_16x16x32_bf16 v[100:103], v[150:153], v[198:201], v[100:103]
	v_mfma_f32_16x16x32_bf16 v[92:95], v[158:161], v[198:201], v[92:95]
	v_mfma_f32_16x16x32_bf16 v[84:87], v[150:153], v[206:209], v[84:87]
	v_mfma_f32_16x16x32_bf16 v[76:79], v[158:161], v[206:209], v[76:79]
	v_mfma_f32_16x16x32_bf16 v[112:115], v[162:165], v[178:181], v[112:115]
	v_mfma_f32_16x16x32_bf16 v[104:107], v[170:173], v[178:181], v[104:107]
	v_mfma_f32_16x16x32_bf16 v[96:99], v[162:165], v[186:189], v[96:99]
	v_mfma_f32_16x16x32_bf16 v[88:91], v[170:173], v[186:189], v[88:91]
	v_mfma_f32_16x16x32_bf16 v[80:83], v[162:165], v[194:197], v[80:83]
	v_mfma_f32_16x16x32_bf16 v[72:75], v[170:173], v[194:197], v[72:75]
	v_mfma_f32_16x16x32_bf16 v[68:71], v[162:165], v[202:205], v[68:71]
	v_mfma_f32_16x16x32_bf16 v[64:67], v[170:173], v[202:205], v[64:67]
	v_mfma_f32_16x16x32_bf16 v[112:115], v[166:169], v[182:185], v[112:115]
	v_mfma_f32_16x16x32_bf16 v[104:107], v[174:177], v[182:185], v[104:107]
	v_mfma_f32_16x16x32_bf16 v[96:99], v[166:169], v[190:193], v[96:99]
	v_mfma_f32_16x16x32_bf16 v[88:91], v[174:177], v[190:193], v[88:91]
	v_mfma_f32_16x16x32_bf16 v[80:83], v[166:169], v[198:201], v[80:83]
	v_mfma_f32_16x16x32_bf16 v[72:75], v[174:177], v[198:201], v[72:75]
	v_mfma_f32_16x16x32_bf16 v[68:71], v[166:169], v[206:209], v[68:71]
	v_mfma_f32_16x16x32_bf16 v[64:67], v[174:177], v[206:209], v[64:67]
	s_barrier
; #define PG8_LDA(dst, b, h) do { _Pragma("unroll") for (int m = 0; m < 4; ++m) _Pragma("unroll") for (int k = 0; k < 2; ++k) dst[m][k] = *(const LAS bf16x8*)(lds + PG8_SA(b, h) + aoff + m * 2048 + k * 1024); } while (0)
; #define PG8_MMA(ai, bj, At, Bt) do { __builtin_amdgcn_s_setprio(1); _Pragma("unroll") for (int m = 0; m < 4; ++m) _Pragma("unroll") for (int n = 0; n < 2; ++n) _Pragma("unroll") for (int k = 0; k < 2; ++k) \
;         acc[ai][bj][m][n] = __builtin_amdgcn_mfma_f32_16x16x32_bf16(Bt[n][k], At[m][k], acc[ai][bj][m][n], 0, 0, 0); __builtin_amdgcn_s_setprio(0); } while (0)
; #define PG8_WAIT_V(n) asm volatile("s_waitcnt vmcnt(" #n ")" ::: "memory")
; #define PG8_WAIT_L(n) asm volatile("s_waitcnt lgkmcnt(" #n ")" ::: "memory")
; #define PG8_BAR __builtin_amdgcn_s_barrier()
; #define PG8_SCHED __builtin_amdgcn_sched_barrier(0)
; template <class Epi, class Addr, bool ALIGN_EPI = true, class Order = StaticOrder>
; __device__ __forceinline__ void gemm_phase(LAS unsigned char* lds, const Gemm g, const Order& S, const Epi& E, const int wid) {
;     ...
;         for (int t = 0; t < nt; t += 2) {
;     ...
;             PG8_LDA(At, 1, 1); PG8_STAGE(PG8_SB(1, 0), b3, voffB); PG8_STAGE(PG8_SB(1, 1), b3 + hstepB, voffB); PG8_STAGE(PG8_SA(1, 0), a3, voffA);
;             PG8_WAIT_V(8); PG8_WAIT_L(0); PG8_BAR; PG8_MMA(1, 0, At, B0); PG8_MMA(1, 1, At, B1); PG8_BAR; PG8_SCHED;
	s_setprio 0
	ds_read_b128 v[178:181], v142 offset:49152
	ds_read_b128 v[182:185], v142 offset:50176
	ds_read_b128 v[186:189], v142 offset:51200
	ds_read_b128 v[190:193], v142 offset:52224
	ds_read_b128 v[194:197], v142 offset:53248
	ds_read_b128 v[198:201], v142 offset:54272
	ds_read_b128 v[202:205], v142 offset:55296
	ds_read_b128 v[206:209], v142 offset:56320
	s_add_u32 s18, s46, 0x80
	s_addc_u32 s19, s47, 0
	s_mov_b32 s25, m0
	s_mov_b32 m0, s58
	s_nop 0
	global_load_lds_dwordx4 v137, s[18:19]
	s_mov_b32 m0, s59
	s_nop 0
	global_load_lds_dwordx4 v139, s[18:19]
	s_mov_b32 m0, s25
	s_add_u32 s18, s46, 0x20080
	s_addc_u32 s19, s47, 0
	s_mov_b32 s25, m0
	s_mov_b32 m0, s62
	s_nop 0
	global_load_lds_dwordx4 v137, s[18:19]
	s_mov_b32 m0, s63
	s_nop 0
	global_load_lds_dwordx4 v139, s[18:19]
	s_mov_b32 m0, s25
	s_mov_b32 s18, m0
	s_mov_b32 m0, s60
	s_nop 0
	global_load_lds_dwordx4 v136, s[26:27]
	s_mov_b32 m0, s61
	s_nop 0
	global_load_lds_dwordx4 v138, s[26:27]
	s_mov_b32 m0, s18
	s_waitcnt vmcnt(8)
	s_waitcnt lgkmcnt(0)
	s_setprio 1
	s_barrier
	v_mfma_f32_16x16x32_bf16 v[60:63], v[146:149], v[178:181], v[60:63]
	v_mfma_f32_16x16x32_bf16 v[56:59], v[154:157], v[178:181], v[56:59]
	v_mfma_f32_16x16x32_bf16 v[52:55], v[146:149], v[186:189], v[52:55]
	v_mfma_f32_16x16x32_bf16 v[44:47], v[154:157], v[186:189], v[44:47]
	v_mfma_f32_16x16x32_bf16 v[36:39], v[146:149], v[194:197], v[36:39]
	v_mfma_f32_16x16x32_bf16 v[28:31], v[154:157], v[194:197], v[28:31]
	v_mfma_f32_16x16x32_bf16 v[20:23], v[146:149], v[202:205], v[20:23]
	v_mfma_f32_16x16x32_bf16 v[12:15], v[154:157], v[202:205], v[12:15]
	v_mfma_f32_16x16x32_bf16 v[60:63], v[150:153], v[182:185], v[60:63]
	v_mfma_f32_16x16x32_bf16 v[56:59], v[158:161], v[182:185], v[56:59]
	v_mfma_f32_16x16x32_bf16 v[52:55], v[150:153], v[190:193], v[52:55]
	v_mfma_f32_16x16x32_bf16 v[44:47], v[158:161], v[190:193], v[44:47]
	v_mfma_f32_16x16x32_bf16 v[36:39], v[150:153], v[198:201], v[36:39]
	v_mfma_f32_16x16x32_bf16 v[28:31], v[158:161], v[198:201], v[28:31]
	v_mfma_f32_16x16x32_bf16 v[20:23], v[150:153], v[206:209], v[20:23]
	v_mfma_f32_16x16x32_bf16 v[12:15], v[158:161], v[206:209], v[12:15]
	v_mfma_f32_16x16x32_bf16 v[48:51], v[162:165], v[178:181], v[48:51]
	v_mfma_f32_16x16x32_bf16 v[40:43], v[170:173], v[178:181], v[40:43]
	v_mfma_f32_16x16x32_bf16 v[32:35], v[162:165], v[186:189], v[32:35]
	v_mfma_f32_16x16x32_bf16 v[24:27], v[170:173], v[186:189], v[24:27]
	v_mfma_f32_16x16x32_bf16 v[16:19], v[162:165], v[194:197], v[16:19]
	v_mfma_f32_16x16x32_bf16 v[8:11], v[170:173], v[194:197], v[8:11]
	v_mfma_f32_16x16x32_bf16 v[4:7], v[162:165], v[202:205], v[4:7]
	v_mfma_f32_16x16x32_bf16 v[0:3], v[170:173], v[202:205], v[0:3]
	v_mfma_f32_16x16x32_bf16 v[48:51], v[166:169], v[182:185], v[48:51]
	v_mfma_f32_16x16x32_bf16 v[40:43], v[174:177], v[182:185], v[40:43]
	v_mfma_f32_16x16x32_bf16 v[32:35], v[166:169], v[190:193], v[32:35]
	v_mfma_f32_16x16x32_bf16 v[24:27], v[174:177], v[190:193], v[24:27]
	v_mfma_f32_16x16x32_bf16 v[16:19], v[166:169], v[198:201], v[16:19]
	v_mfma_f32_16x16x32_bf16 v[8:11], v[174:177], v[198:201], v[8:11]
	v_mfma_f32_16x16x32_bf16 v[4:7], v[166:169], v[206:209], v[4:7]
	v_mfma_f32_16x16x32_bf16 v[0:3], v[174:177], v[206:209], v[0:3]
	s_barrier
	s_setprio 0
	s_add_i32 s17, s17, 2
	s_cmp_gt_u32 s17, 5
	s_mov_b64 s[26:27], s[44:45]
	s_cbranch_scc0 .LBB0_559
	s_and_b64 vcc, exec, s[10:11]
	s_cbranch_vccz .LBB0_562
	s_barrier

; #define PG8_LDA(dst, b, h) do { _Pragma("unroll") for (int m = 0; m < 4; ++m) _Pragma("unroll") for (int k = 0; k < 2; ++k) dst[m][k] = *(const LAS bf16x8*)(lds + PG8_SA(b, h) + aoff + m * 2048 + k * 1024); } while (0)
; #define PG8_LDB(dst, b, h) do { _Pragma("unroll") for (int n = 0; n < 2; ++n) _Pragma("unroll") for (int k = 0; k < 2; ++k) dst[n][k] = *(const LAS bf16x8*)(lds + PG8_SB(b, h) + boff + n * 2048 + k * 1024); } while (0)
; #define PG8_MMA(ai, bj, At, Bt) do { __builtin_amdgcn_s_setprio(1); _Pragma("unroll") for (int m = 0; m < 4; ++m) _Pragma("unroll") for (int n = 0; n < 2; ++n) _Pragma("unroll") for (int k = 0; k < 2; ++k) \
;         acc[ai][bj][m][n] = __builtin_amdgcn_mfma_f32_16x16x32_bf16(Bt[n][k], At[m][k], acc[ai][bj][m][n], 0, 0, 0); __builtin_amdgcn_s_setprio(0); } while (0)
; #define PG8_WAIT_V(n) asm volatile("s_waitcnt vmcnt(" #n ")" ::: "memory")
; #define PG8_WAIT_L(n) asm volatile("s_waitcnt lgkmcnt(" #n ")" ::: "memory")
; #define PG8_BAR __builtin_amdgcn_s_barrier()
; template <class Epi, class Addr, bool ALIGN_EPI = true, class Order = StaticOrder>
; __device__ __forceinline__ void gemm_phase(LAS unsigned char* lds, const Gemm g, const Order& S, const Epi& E, const int wid) {
;     ...
;         for (int t = 0; t < nt; t += 2) {
;             const bool last = (t == nt - 2);
;             const char* a1 = cA + (size_t)(t + 1) * kstep;
;             const char* a2 = last ? nA : cA + (size_t)(t + 2) * kstep; const char* b2 = last ? nB : cB + (size_t)(t + 2) * kstep;
;             const char* a3 = a2 + kstep; const char* b3 = b2 + kstep;
;             PG8_LDB(B0, 0, 0); PG8_LDB(B1, 0, 1); PG8_SCHED; PG8_LDA(At, 0, 0); PG8_STAGE(PG8_SA(1, 1), a1 + hstepA, voffA);
;             PG8_WAIT_V(8); PG8_WAIT_L(0); PG8_BAR; PG8_MMA(0, 0, At, B0); PG8_MMA(0, 1, At, B1); PG8_BAR; PG8_SCHED;
;             PG8_LDA(At, 0, 1); PG8_STAGE(PG8_SB(0, 0), b2, voffB); PG8_STAGE(PG8_SB(0, 1), b2 + hstepB, voffB); PG8_STAGE(PG8_SA(0, 0), a2, voffA);
;             PG8_WAIT_V(8); PG8_WAIT_L(0); PG8_BAR; PG8_MMA(1, 0, At, B0); PG8_MMA(1, 1, At, B1); PG8_BAR; PG8_SCHED;
;             PG8_LDB(B0, 1, 0); PG8_LDB(B1, 1, 1); PG8_SCHED; PG8_LDA(At, 1, 0); PG8_STAGE(PG8_SA(0, 1), a2 + hstepA, voffA);
;             PG8_WAIT_V(8); PG8_WAIT_L(0); PG8_BAR; PG8_MMA(0, 0, At, B0); PG8_MMA(0, 1, At, B1); PG8_BAR; PG8_SCHED;
.LBB0_636:
	ds_read_b128 v[146:149], v140
	ds_read_b128 v[150:153], v140 offset:1024
	ds_read_b128 v[154:157], v140 offset:2048
	ds_read_b128 v[158:161], v140 offset:3072
	ds_read_b128 v[162:165], v141
	ds_read_b128 v[166:169], v141 offset:1024
	ds_read_b128 v[170:173], v141 offset:2048
	ds_read_b128 v[174:177], v141 offset:3072
	s_add_u32 s46, s44, 0x100
	s_addc_u32 s47, s45, 0
	s_cmp_eq_u32 s89, 28
	s_cselect_b32 s52, s25, s46
	s_cselect_b32 s53, s17, s47
	s_cselect_b32 s50, s27, s87
	s_cselect_b32 s51, s15, s88
	s_add_u32 s48, s52, 0x80
	s_addc_u32 s49, s53, 0
	ds_read_b128 v[178:181], v142
	ds_read_b128 v[182:185], v142 offset:1024
	ds_read_b128 v[186:189], v142 offset:2048
	ds_read_b128 v[190:193], v142 offset:3072
	ds_read_b128 v[194:197], v142 offset:4096
	ds_read_b128 v[198:201], v142 offset:5120
	ds_read_b128 v[202:205], v142 offset:6144
	ds_read_b128 v[206:209], v142 offset:7168
	s_add_u32 s18, s44, 0x80080
	s_addc_u32 s19, s45, 0
	s_mov_b32 s36, m0
	s_mov_b32 m0, s61
	s_nop 0
	global_load_lds_dwordx4 v136, s[18:19]
	s_mov_b32 m0, s62
	s_nop 0
	global_load_lds_dwordx4 v138, s[18:19]
	s_mov_b32 m0, s36
	s_waitcnt vmcnt(8)
	s_waitcnt lgkmcnt(0)
	s_setprio 1
	s_barrier
	v_mfma_f32_16x16x32_bf16 v[124:127], v[146:149], v[178:181], v[124:127]
	v_mfma_f32_16x16x32_bf16 v[120:123], v[154:157], v[178:181], v[120:123]
	v_mfma_f32_16x16x32_bf16 v[116:119], v[146:149], v[186:189], v[116:119]
	v_mfma_f32_16x16x32_bf16 v[108:111], v[154:157], v[186:189], v[108:111]
	v_mfma_f32_16x16x32_bf16 v[100:103], v[146:149], v[194:197], v[100:103]
	v_mfma_f32_16x16x32_bf16 v[92:95], v[154:157], v[194:197], v[92:95]
	v_mfma_f32_16x16x32_bf16 v[84:87], v[146:149], v[202:205], v[84:87]
	v_mfma_f32_16x16x32_bf16 v[76:79], v[154:157], v[202:205], v[76:79]
	v_mfma_f32_16x16x32_bf16 v[124:127], v[150:153], v[182:185], v[124:127]
	v_mfma_f32_16x16x32_bf16 v[120:123], v[158:161], v[182:185], v[120:123]
	v_mfma_f32_16x16x32_bf16 v[116:119], v[150:153], v[190:193], v[116:119]
	v_mfma_f32_16x16x32_bf16 v[108:111], v[158:161], v[190:193], v[108:111]
	v_mfma_f32_16x16x32_bf16 v[100:103], v[150:153], v[198:201], v[100:103]
	v_mfma_f32_16x16x32_bf16 v[92:95], v[158:161], v[198:201], v[92:95]
	v_mfma_f32_16x16x32_bf16 v[84:87], v[150:153], v[206:209], v[84:87]
	v_mfma_f32_16x16x32_bf16 v[76:79], v[158:161], v[206:209], v[76:79]
	v_mfma_f32_16x16x32_bf16 v[112:115], v[162:165], v[178:181], v[112:115]
	v_mfma_f32_16x16x32_bf16 v[104:107], v[170:173], v[178:181], v[104:107]
	v_mfma_f32_16x16x32_bf16 v[96:99], v[162:165], v[186:189], v[96:99]
	v_mfma_f32_16x16x32_bf16 v[88:91], v[170:173], v[186:189], v[88:91]
	v_mfma_f32_16x16x32_bf16 v[80:83], v[162:165], v[194:197], v[80:83]
	v_mfma_f32_16x16x32_bf16 v[72:75], v[170:173], v[194:197], v[72:75]
	v_mfma_f32_16x16x32_bf16 v[68:71], v[162:165], v[202:205], v[68:71]
	v_mfma_f32_16x16x32_bf16 v[64:67], v[170:173], v[202:205], v[64:67]
	v_mfma_f32_16x16x32_bf16 v[112:115], v[166:169], v[182:185], v[112:115]
	v_mfma_f32_16x16x32_bf16 v[104:107], v[174:177], v[182:185], v[104:107]
	v_mfma_f32_16x16x32_bf16 v[96:99], v[166:169], v[190:193], v[96:99]
	v_mfma_f32_16x16x32_bf16 v[88:91], v[174:177], v[190:193], v[88:91]
	v_mfma_f32_16x16x32_bf16 v[80:83], v[166:169], v[198:201], v[80:83]
	v_mfma_f32_16x16x32_bf16 v[72:75], v[174:177], v[198:201], v[72:75]
	v_mfma_f32_16x16x32_bf16 v[68:71], v[166:169], v[206:209], v[68:71]
	v_mfma_f32_16x16x32_bf16 v[64:67], v[174:177], v[206:209], v[64:67]
	s_barrier
	s_setprio 0
	ds_read_b128 v[178:181], v142 offset:16384
	ds_read_b128 v[182:185], v142 offset:17408
	ds_read_b128 v[186:189], v142 offset:18432
	ds_read_b128 v[190:193], v142 offset:19456
	ds_read_b128 v[194:197], v142 offset:20480
	ds_read_b128 v[198:201], v142 offset:21504
	ds_read_b128 v[202:205], v142 offset:22528
	ds_read_b128 v[206:209], v142 offset:23552
	s_mov_b32 s18, m0
	s_mov_b32 m0, s31
	s_nop 0
	global_load_lds_dwordx4 v137, s[50:51]
	s_mov_b32 m0, s38
	s_nop 0
	global_load_lds_dwordx4 v139, s[50:51]
	s_mov_b32 m0, s18
	s_add_u32 s18, s50, 0x80000
	s_addc_u32 s19, s51, 0
	s_mov_b32 s36, m0
	s_mov_b32 m0, s39
	s_nop 0
	global_load_lds_dwordx4 v137, s[18:19]
	s_mov_b32 m0, s40
	s_nop 0
	global_load_lds_dwordx4 v139, s[18:19]
	s_mov_b32 m0, s36
	s_mov_b32 s18, m0
	s_mov_b32 m0, s29
	s_nop 0
	global_load_lds_dwordx4 v136, s[52:53]
	s_mov_b32 m0, s41
	s_nop 0
	global_load_lds_dwordx4 v138, s[52:53]
	s_mov_b32 m0, s18
	s_waitcnt vmcnt(8)
	s_waitcnt lgkmcnt(0)
	s_setprio 1
	s_barrier
	v_mfma_f32_16x16x32_bf16 v[60:63], v[146:149], v[178:181], v[60:63]
	v_mfma_f32_16x16x32_bf16 v[56:59], v[154:157], v[178:181], v[56:59]
	v_mfma_f32_16x16x32_bf16 v[52:55], v[146:149], v[186:189], v[52:55]
	v_mfma_f32_16x16x32_bf16 v[44:47], v[154:157], v[186:189], v[44:47]
	v_mfma_f32_16x16x32_bf16 v[36:39], v[146:149], v[194:197], v[36:39]
	v_mfma_f32_16x16x32_bf16 v[28:31], v[154:157], v[194:197], v[28:31]
	v_mfma_f32_16x16x32_bf16 v[20:23], v[146:149], v[202:205], v[20:23]
	v_mfma_f32_16x16x32_bf16 v[12:15], v[154:157], v[202:205], v[12:15]
	v_mfma_f32_16x16x32_bf16 v[60:63], v[150:153], v[182:185], v[60:63]
	v_mfma_f32_16x16x32_bf16 v[56:59], v[158:161], v[182:185], v[56:59]
	v_mfma_f32_16x16x32_bf16 v[52:55], v[150:153], v[190:193], v[52:55]
	v_mfma_f32_16x16x32_bf16 v[44:47], v[158:161], v[190:193], v[44:47]
	v_mfma_f32_16x16x32_bf16 v[36:39], v[150:153], v[198:201], v[36:39]
	v_mfma_f32_16x16x32_bf16 v[28:31], v[158:161], v[198:201], v[28:31]
	v_mfma_f32_16x16x32_bf16 v[20:23], v[150:153], v[206:209], v[20:23]
	v_mfma_f32_16x16x32_bf16 v[12:15], v[158:161], v[206:209], v[12:15]
	v_mfma_f32_16x16x32_bf16 v[48:51], v[162:165], v[178:181], v[48:51]
	v_mfma_f32_16x16x32_bf16 v[40:43], v[170:173], v[178:181], v[40:43]
	v_mfma_f32_16x16x32_bf16 v[32:35], v[162:165], v[186:189], v[32:35]
	v_mfma_f32_16x16x32_bf16 v[24:27], v[170:173], v[186:189], v[24:27]
	v_mfma_f32_16x16x32_bf16 v[16:19], v[162:165], v[194:197], v[16:19]
	v_mfma_f32_16x16x32_bf16 v[8:11], v[170:173], v[194:197], v[8:11]
	v_mfma_f32_16x16x32_bf16 v[4:7], v[162:165], v[202:205], v[4:7]
	v_mfma_f32_16x16x32_bf16 v[0:3], v[170:173], v[202:205], v[0:3]
	v_mfma_f32_16x16x32_bf16 v[48:51], v[166:169], v[182:185], v[48:51]
	v_mfma_f32_16x16x32_bf16 v[40:43], v[174:177], v[182:185], v[40:43]
	v_mfma_f32_16x16x32_bf16 v[32:35], v[166:169], v[190:193], v[32:35]
	v_mfma_f32_16x16x32_bf16 v[24:27], v[174:177], v[190:193], v[24:27]
	v_mfma_f32_16x16x32_bf16 v[16:19], v[166:169], v[198:201], v[16:19]
	v_mfma_f32_16x16x32_bf16 v[8:11], v[174:177], v[198:201], v[8:11]
	v_mfma_f32_16x16x32_bf16 v[4:7], v[166:169], v[206:209], v[4:7]
	v_mfma_f32_16x16x32_bf16 v[0:3], v[174:177], v[206:209], v[0:3]
	s_barrier
; #define PG8_LDA(dst, b, h) do { _Pragma("unroll") for (int m = 0; m < 4; ++m) _Pragma("unroll") for (int k = 0; k < 2; ++k) dst[m][k] = *(const LAS bf16x8*)(lds + PG8_SA(b, h) + aoff + m * 2048 + k * 1024); } while (0)
; #define PG8_LDB(dst, b, h) do { _Pragma("unroll") for (int n = 0; n < 2; ++n) _Pragma("unroll") for (int k = 0; k < 2; ++k) dst[n][k] = *(const LAS bf16x8*)(lds + PG8_SB(b, h) + boff + n * 2048 + k * 1024); } while (0)
; #define PG8_MMA(ai, bj, At, Bt) do { __builtin_amdgcn_s_setprio(1); _Pragma("unroll") for (int m = 0; m < 4; ++m) _Pragma("unroll") for (int n = 0; n < 2; ++n) _Pragma("unroll") for (int k = 0; k < 2; ++k) \
;         acc[ai][bj][m][n] = __builtin_amdgcn_mfma_f32_16x16x32_bf16(Bt[n][k], At[m][k], acc[ai][bj][m][n], 0, 0, 0); __builtin_amdgcn_s_setprio(0); } while (0)
; #define PG8_WAIT_V(n) asm volatile("s_waitcnt vmcnt(" #n ")" ::: "memory")
; #define PG8_WAIT_L(n) asm volatile("s_waitcnt lgkmcnt(" #n ")" ::: "memory")
; #define PG8_BAR __builtin_amdgcn_s_barrier()
; #define PG8_SCHED __builtin_amdgcn_sched_barrier(0)
; template <class Epi, class Addr, bool ALIGN_EPI = true, class Order = StaticOrder>
; __device__ __forceinline__ void gemm_phase(LAS unsigned char* lds, const Gemm g, const Order& S, const Epi& E, const int wid) {
;     ...
;             PG8_LDB(B0, 1, 0); PG8_LDB(B1, 1, 1); PG8_SCHED; PG8_LDA(At, 1, 0); PG8_STAGE(PG8_SA(0, 1), a2 + hstepA, voffA);
;             PG8_WAIT_V(8); PG8_WAIT_L(0); PG8_BAR; PG8_MMA(0, 0, At, B0); PG8_MMA(0, 1, At, B1); PG8_BAR; PG8_SCHED;
;             PG8_LDA(At, 1, 1); PG8_STAGE(PG8_SB(1, 0), b3, voffB); PG8_STAGE(PG8_SB(1, 1), b3 + hstepB, voffB); PG8_STAGE(PG8_SA(1, 0), a3, voffA);
;             PG8_WAIT_V(8); PG8_WAIT_L(0); PG8_BAR; PG8_MMA(1, 0, At, B0); PG8_MMA(1, 1, At, B1); PG8_BAR; PG8_SCHED;
;         }
	s_setprio 0
	ds_read_b128 v[146:149], v143
	ds_read_b128 v[150:153], v143 offset:1024
	ds_read_b128 v[154:157], v143 offset:2048
	ds_read_b128 v[158:161], v143 offset:3072
	ds_read_b128 v[162:165], v144
	ds_read_b128 v[166:169], v144 offset:1024
	ds_read_b128 v[170:173], v144 offset:2048
	ds_read_b128 v[174:177], v144 offset:3072
	ds_read_b128 v[178:181], v142 offset:32768
	ds_read_b128 v[182:185], v142 offset:33792
	ds_read_b128 v[186:189], v142 offset:34816
	ds_read_b128 v[190:193], v142 offset:35840
	ds_read_b128 v[194:197], v142 offset:36864
	ds_read_b128 v[198:201], v142 offset:37888
	ds_read_b128 v[202:205], v142 offset:38912
	ds_read_b128 v[206:209], v142 offset:39936
	s_add_u32 s18, s52, 0x80000
	s_addc_u32 s19, s53, 0
	s_mov_b32 s36, m0
	s_mov_b32 m0, s43
	s_nop 0
	global_load_lds_dwordx4 v136, s[18:19]
	s_mov_b32 m0, s54
	s_nop 0
	global_load_lds_dwordx4 v138, s[18:19]
	s_mov_b32 m0, s36
	s_waitcnt vmcnt(8)
	s_waitcnt lgkmcnt(0)
	s_setprio 1
	s_barrier
	v_mfma_f32_16x16x32_bf16 v[124:127], v[146:149], v[178:181], v[124:127]
	v_mfma_f32_16x16x32_bf16 v[120:123], v[154:157], v[178:181], v[120:123]
	v_mfma_f32_16x16x32_bf16 v[116:119], v[146:149], v[186:189], v[116:119]
	v_mfma_f32_16x16x32_bf16 v[108:111], v[154:157], v[186:189], v[108:111]
	v_mfma_f32_16x16x32_bf16 v[100:103], v[146:149], v[194:197], v[100:103]
	v_mfma_f32_16x16x32_bf16 v[92:95], v[154:157], v[194:197], v[92:95]
	v_mfma_f32_16x16x32_bf16 v[84:87], v[146:149], v[202:205], v[84:87]
	v_mfma_f32_16x16x32_bf16 v[76:79], v[154:157], v[202:205], v[76:79]
	v_mfma_f32_16x16x32_bf16 v[124:127], v[150:153], v[182:185], v[124:127]
	v_mfma_f32_16x16x32_bf16 v[120:123], v[158:161], v[182:185], v[120:123]
	v_mfma_f32_16x16x32_bf16 v[116:119], v[150:153], v[190:193], v[116:119]
	v_mfma_f32_16x16x32_bf16 v[108:111], v[158:161], v[190:193], v[108:111]
	v_mfma_f32_16x16x32_bf16 v[100:103], v[150:153], v[198:201], v[100:103]
	v_mfma_f32_16x16x32_bf16 v[92:95], v[158:161], v[198:201], v[92:95]
	v_mfma_f32_16x16x32_bf16 v[84:87], v[150:153], v[206:209], v[84:87]
	v_mfma_f32_16x16x32_bf16 v[76:79], v[158:161], v[206:209], v[76:79]
	v_mfma_f32_16x16x32_bf16 v[112:115], v[162:165], v[178:181], v[112:115]
	v_mfma_f32_16x16x32_bf16 v[104:107], v[170:173], v[178:181], v[104:107]
	v_mfma_f32_16x16x32_bf16 v[96:99], v[162:165], v[186:189], v[96:99]
	v_mfma_f32_16x16x32_bf16 v[88:91], v[170:173], v[186:189], v[88:91]
	v_mfma_f32_16x16x32_bf16 v[80:83], v[162:165], v[194:197], v[80:83]
	v_mfma_f32_16x16x32_bf16 v[72:75], v[170:173], v[194:197], v[72:75]
	v_mfma_f32_16x16x32_bf16 v[68:71], v[162:165], v[202:205], v[68:71]
	v_mfma_f32_16x16x32_bf16 v[64:67], v[170:173], v[202:205], v[64:67]
	v_mfma_f32_16x16x32_bf16 v[112:115], v[166:169], v[182:185], v[112:115]
	v_mfma_f32_16x16x32_bf16 v[104:107], v[174:177], v[182:185], v[104:107]
	v_mfma_f32_16x16x32_bf16 v[96:99], v[166:169], v[190:193], v[96:99]
	v_mfma_f32_16x16x32_bf16 v[88:91], v[174:177], v[190:193], v[88:91]
	v_mfma_f32_16x16x32_bf16 v[80:83], v[166:169], v[198:201], v[80:83]
	v_mfma_f32_16x16x32_bf16 v[72:75], v[174:177], v[198:201], v[72:75]
	v_mfma_f32_16x16x32_bf16 v[68:71], v[166:169], v[206:209], v[68:71]
	v_mfma_f32_16x16x32_bf16 v[64:67], v[174:177], v[206:209], v[64:67]
	s_barrier
	s_setprio 0
	ds_read_b128 v[178:181], v142 offset:49152
	ds_read_b128 v[182:185], v142 offset:50176
	ds_read_b128 v[186:189], v142 offset:51200
	ds_read_b128 v[190:193], v142 offset:52224
	ds_read_b128 v[194:197], v142 offset:53248
	ds_read_b128 v[198:201], v142 offset:54272
	ds_read_b128 v[202:205], v142 offset:55296
	ds_read_b128 v[206:209], v142 offset:56320
	s_add_u32 s18, s50, 0x80
	s_addc_u32 s19, s51, 0
	s_mov_b32 s36, m0
	s_mov_b32 m0, s55
	s_nop 0
	global_load_lds_dwordx4 v137, s[18:19]
	s_mov_b32 m0, s56
	s_nop 0
	global_load_lds_dwordx4 v139, s[18:19]
	s_mov_b32 m0, s36
	s_add_u32 s18, s50, 0x80080
	s_addc_u32 s19, s51, 0
	s_mov_b32 s36, m0
	s_mov_b32 m0, s59
	s_nop 0
	global_load_lds_dwordx4 v137, s[18:19]
	s_mov_b32 m0, s60
	s_nop 0
	global_load_lds_dwordx4 v139, s[18:19]
	s_mov_b32 m0, s36
	s_mov_b32 s18, m0
	s_mov_b32 m0, s57
	s_nop 0
	global_load_lds_dwordx4 v136, s[48:49]
	s_mov_b32 m0, s58
	s_nop 0
	global_load_lds_dwordx4 v138, s[48:49]
	s_mov_b32 m0, s18
	s_waitcnt vmcnt(8)
	s_waitcnt lgkmcnt(0)
	s_setprio 1
	s_barrier
	v_mfma_f32_16x16x32_bf16 v[60:63], v[146:149], v[178:181], v[60:63]
	v_mfma_f32_16x16x32_bf16 v[56:59], v[154:157], v[178:181], v[56:59]
	v_mfma_f32_16x16x32_bf16 v[52:55], v[146:149], v[186:189], v[52:55]
	v_mfma_f32_16x16x32_bf16 v[44:47], v[154:157], v[186:189], v[44:47]
	v_mfma_f32_16x16x32_bf16 v[36:39], v[146:149], v[194:197], v[36:39]
	v_mfma_f32_16x16x32_bf16 v[28:31], v[154:157], v[194:197], v[28:31]
	v_mfma_f32_16x16x32_bf16 v[20:23], v[146:149], v[202:205], v[20:23]
	v_mfma_f32_16x16x32_bf16 v[12:15], v[154:157], v[202:205], v[12:15]
	v_mfma_f32_16x16x32_bf16 v[60:63], v[150:153], v[182:185], v[60:63]
	v_mfma_f32_16x16x32_bf16 v[56:59], v[158:161], v[182:185], v[56:59]
	v_mfma_f32_16x16x32_bf16 v[52:55], v[150:153], v[190:193], v[52:55]
	v_mfma_f32_16x16x32_bf16 v[44:47], v[158:161], v[190:193], v[44:47]
	v_mfma_f32_16x16x32_bf16 v[36:39], v[150:153], v[198:201], v[36:39]
	v_mfma_f32_16x16x32_bf16 v[28:31], v[158:161], v[198:201], v[28:31]
	v_mfma_f32_16x16x32_bf16 v[20:23], v[150:153], v[206:209], v[20:23]
	v_mfma_f32_16x16x32_bf16 v[12:15], v[158:161], v[206:209], v[12:15]
	v_mfma_f32_16x16x32_bf16 v[48:51], v[162:165], v[178:181], v[48:51]
	v_mfma_f32_16x16x32_bf16 v[40:43], v[170:173], v[178:181], v[40:43]
	v_mfma_f32_16x16x32_bf16 v[32:35], v[162:165], v[186:189], v[32:35]
	v_mfma_f32_16x16x32_bf16 v[24:27], v[170:173], v[186:189], v[24:27]
	v_mfma_f32_16x16x32_bf16 v[16:19], v[162:165], v[194:197], v[16:19]
	v_mfma_f32_16x16x32_bf16 v[8:11], v[170:173], v[194:197], v[8:11]
	v_mfma_f32_16x16x32_bf16 v[4:7], v[162:165], v[202:205], v[4:7]
	v_mfma_f32_16x16x32_bf16 v[0:3], v[170:173], v[202:205], v[0:3]
	v_mfma_f32_16x16x32_bf16 v[48:51], v[166:169], v[182:185], v[48:51]
	v_mfma_f32_16x16x32_bf16 v[40:43], v[174:177], v[182:185], v[40:43]
	v_mfma_f32_16x16x32_bf16 v[32:35], v[166:169], v[190:193], v[32:35]
	v_mfma_f32_16x16x32_bf16 v[24:27], v[174:177], v[190:193], v[24:27]
	v_mfma_f32_16x16x32_bf16 v[16:19], v[166:169], v[198:201], v[16:19]
	v_mfma_f32_16x16x32_bf16 v[8:11], v[174:177], v[198:201], v[8:11]
	v_mfma_f32_16x16x32_bf16 v[4:7], v[166:169], v[206:209], v[4:7]
	v_mfma_f32_16x16x32_bf16 v[0:3], v[174:177], v[206:209], v[0:3]
	s_barrier
	s_setprio 0
	s_add_i32 s89, s89, 2
	s_add_u32 s87, s87, 0x100
	s_addc_u32 s88, s88, 0
	s_cmp_gt_u32 s89, 29
	s_mov_b64 s[44:45], s[46:47]
	s_cbranch_scc0 .LBB0_636
	s_and_b64 vcc, exec, s[8:9]
	s_cbranch_vccz .LBB0_639
	s_barrier

; #define PG8_LDA(dst, b, h) do { _Pragma("unroll") for (int m = 0; m < 4; ++m) _Pragma("unroll") for (int k = 0; k < 2; ++k) dst[m][k] = *(const LAS bf16x8*)(lds + PG8_SA(b, h) + aoff + m * 2048 + k * 1024); } while (0)
; #define PG8_LDB(dst, b, h) do { _Pragma("unroll") for (int n = 0; n < 2; ++n) _Pragma("unroll") for (int k = 0; k < 2; ++k) dst[n][k] = *(const LAS bf16x8*)(lds + PG8_SB(b, h) + boff + n * 2048 + k * 1024); } while (0)
; #define PG8_MMA(ai, bj, At, Bt) do { __builtin_amdgcn_s_setprio(1); _Pragma("unroll") for (int m = 0; m < 4; ++m) _Pragma("unroll") for (int n = 0; n < 2; ++n) _Pragma("unroll") for (int k = 0; k < 2; ++k) \
;         acc[ai][bj][m][n] = __builtin_amdgcn_mfma_f32_16x16x32_bf16(Bt[n][k], At[m][k], acc[ai][bj][m][n], 0, 0, 0); __builtin_amdgcn_s_setprio(0); } while (0)
; #define PG8_WAIT_V(n) asm volatile("s_waitcnt vmcnt(" #n ")" ::: "memory")
; #define PG8_WAIT_L(n) asm volatile("s_waitcnt lgkmcnt(" #n ")" ::: "memory")
; #define PG8_BAR __builtin_amdgcn_s_barrier()
; template <class Epi, class Addr, bool ALIGN_EPI = true, class Order = StaticOrder>
; __device__ __forceinline__ void gemm_phase(LAS unsigned char* lds, const Gemm g, const Order& S, const Epi& E, const int wid) {
;     ...
;         for (int t = 0; t < nt; t += 2) {
;             const bool last = (t == nt - 2);
;             const char* a1 = cA + (size_t)(t + 1) * kstep;
;             const char* a2 = last ? nA : cA + (size_t)(t + 2) * kstep; const char* b2 = last ? nB : cB + (size_t)(t + 2) * kstep;
;             const char* a3 = a2 + kstep; const char* b3 = b2 + kstep;
;             PG8_LDB(B0, 0, 0); PG8_LDB(B1, 0, 1); PG8_SCHED; PG8_LDA(At, 0, 0); PG8_STAGE(PG8_SA(1, 1), a1 + hstepA, voffA);
;             PG8_WAIT_V(8); PG8_WAIT_L(0); PG8_BAR; PG8_MMA(0, 0, At, B0); PG8_MMA(0, 1, At, B1); PG8_BAR; PG8_SCHED;
;             PG8_LDA(At, 0, 1); PG8_STAGE(PG8_SB(0, 0), b2, voffB); PG8_STAGE(PG8_SB(0, 1), b2 + hstepB, voffB); PG8_STAGE(PG8_SA(0, 0), a2, voffA);
;             PG8_WAIT_V(8); PG8_WAIT_L(0); PG8_BAR; PG8_MMA(1, 0, At, B0); PG8_MMA(1, 1, At, B1); PG8_BAR; PG8_SCHED;
;             PG8_LDB(B0, 1, 0); PG8_LDB(B1, 1, 1); PG8_SCHED; PG8_LDA(At, 1, 0); PG8_STAGE(PG8_SA(0, 1), a2 + hstepA, voffA);
;             PG8_WAIT_V(8); PG8_WAIT_L(0); PG8_BAR; PG8_MMA(0, 0, At, B0); PG8_MMA(0, 1, At, B1); PG8_BAR; PG8_SCHED;
.LBB0_656:
	ds_read_b128 v[146:149], v140
	ds_read_b128 v[150:153], v140 offset:1024
	ds_read_b128 v[154:157], v140 offset:2048
	ds_read_b128 v[158:161], v140 offset:3072
	ds_read_b128 v[162:165], v141
	ds_read_b128 v[166:169], v141 offset:1024
	ds_read_b128 v[170:173], v141 offset:2048
	ds_read_b128 v[174:177], v141 offset:3072
	s_add_u32 s26, s24, 0x100
	s_addc_u32 s27, s25, 0
	s_cmp_eq_u32 s77, 28
	s_cselect_b32 s48, s21, s26
	s_cselect_b32 s49, s13, s27
	s_cselect_b32 s46, s23, s75
	s_cselect_b32 s47, s11, s76
	s_add_u32 s44, s48, 0x80
	s_addc_u32 s45, s49, 0
	ds_read_b128 v[178:181], v142
	ds_read_b128 v[182:185], v142 offset:1024
	ds_read_b128 v[186:189], v142 offset:2048
	ds_read_b128 v[190:193], v142 offset:3072
	ds_read_b128 v[194:197], v142 offset:4096
	ds_read_b128 v[198:201], v142 offset:5120
	ds_read_b128 v[202:205], v142 offset:6144
	ds_read_b128 v[206:209], v142 offset:7168
	s_add_u32 s18, s24, 0x80080
	s_addc_u32 s19, s25, 0
	s_mov_b32 s24, m0
	s_mov_b32 m0, s61
	s_nop 0
	global_load_lds_dwordx4 v136, s[18:19]
	s_mov_b32 m0, s62
	s_nop 0
	global_load_lds_dwordx4 v138, s[18:19]
	s_mov_b32 m0, s24
	s_waitcnt vmcnt(8)
	s_waitcnt lgkmcnt(0)
	s_setprio 1
	s_barrier
	v_mfma_f32_16x16x32_bf16 v[124:127], v[146:149], v[178:181], v[124:127]
	v_mfma_f32_16x16x32_bf16 v[120:123], v[154:157], v[178:181], v[120:123]
	v_mfma_f32_16x16x32_bf16 v[116:119], v[146:149], v[186:189], v[116:119]
	v_mfma_f32_16x16x32_bf16 v[108:111], v[154:157], v[186:189], v[108:111]
	v_mfma_f32_16x16x32_bf16 v[100:103], v[146:149], v[194:197], v[100:103]
	v_mfma_f32_16x16x32_bf16 v[92:95], v[154:157], v[194:197], v[92:95]
	v_mfma_f32_16x16x32_bf16 v[84:87], v[146:149], v[202:205], v[84:87]
	v_mfma_f32_16x16x32_bf16 v[76:79], v[154:157], v[202:205], v[76:79]
	v_mfma_f32_16x16x32_bf16 v[124:127], v[150:153], v[182:185], v[124:127]
	v_mfma_f32_16x16x32_bf16 v[120:123], v[158:161], v[182:185], v[120:123]
	v_mfma_f32_16x16x32_bf16 v[116:119], v[150:153], v[190:193], v[116:119]
	v_mfma_f32_16x16x32_bf16 v[108:111], v[158:161], v[190:193], v[108:111]
	v_mfma_f32_16x16x32_bf16 v[100:103], v[150:153], v[198:201], v[100:103]
	v_mfma_f32_16x16x32_bf16 v[92:95], v[158:161], v[198:201], v[92:95]
	v_mfma_f32_16x16x32_bf16 v[84:87], v[150:153], v[206:209], v[84:87]
	v_mfma_f32_16x16x32_bf16 v[76:79], v[158:161], v[206:209], v[76:79]
	v_mfma_f32_16x16x32_bf16 v[112:115], v[162:165], v[178:181], v[112:115]
	v_mfma_f32_16x16x32_bf16 v[104:107], v[170:173], v[178:181], v[104:107]
	v_mfma_f32_16x16x32_bf16 v[96:99], v[162:165], v[186:189], v[96:99]
	v_mfma_f32_16x16x32_bf16 v[88:91], v[170:173], v[186:189], v[88:91]
	v_mfma_f32_16x16x32_bf16 v[80:83], v[162:165], v[194:197], v[80:83]
	v_mfma_f32_16x16x32_bf16 v[72:75], v[170:173], v[194:197], v[72:75]
	v_mfma_f32_16x16x32_bf16 v[68:71], v[162:165], v[202:205], v[68:71]
	v_mfma_f32_16x16x32_bf16 v[64:67], v[170:173], v[202:205], v[64:67]
	v_mfma_f32_16x16x32_bf16 v[112:115], v[166:169], v[182:185], v[112:115]
	v_mfma_f32_16x16x32_bf16 v[104:107], v[174:177], v[182:185], v[104:107]
	v_mfma_f32_16x16x32_bf16 v[96:99], v[166:169], v[190:193], v[96:99]
	v_mfma_f32_16x16x32_bf16 v[88:91], v[174:177], v[190:193], v[88:91]
	v_mfma_f32_16x16x32_bf16 v[80:83], v[166:169], v[198:201], v[80:83]
	v_mfma_f32_16x16x32_bf16 v[72:75], v[174:177], v[198:201], v[72:75]
	v_mfma_f32_16x16x32_bf16 v[68:71], v[166:169], v[206:209], v[68:71]
	v_mfma_f32_16x16x32_bf16 v[64:67], v[174:177], v[206:209], v[64:67]
	s_barrier
	s_setprio 0
	ds_read_b128 v[178:181], v142 offset:16384
	ds_read_b128 v[182:185], v142 offset:17408
	ds_read_b128 v[186:189], v142 offset:18432
	ds_read_b128 v[190:193], v142 offset:19456
	ds_read_b128 v[194:197], v142 offset:20480
	ds_read_b128 v[198:201], v142 offset:21504
	ds_read_b128 v[202:205], v142 offset:22528
	ds_read_b128 v[206:209], v142 offset:23552
	s_mov_b32 s18, m0
	s_mov_b32 m0, s31
	s_nop 0
	global_load_lds_dwordx4 v137, s[46:47]
	s_mov_b32 m0, s38
	s_nop 0
	global_load_lds_dwordx4 v139, s[46:47]
	s_mov_b32 m0, s18
	s_add_u32 s18, s46, 0x80000
	s_addc_u32 s19, s47, 0
	s_mov_b32 s24, m0
	s_mov_b32 m0, s39
	s_nop 0
	global_load_lds_dwordx4 v137, s[18:19]
	s_mov_b32 m0, s40
	s_nop 0
	global_load_lds_dwordx4 v139, s[18:19]
	s_mov_b32 m0, s24
	s_mov_b32 s18, m0
	s_mov_b32 m0, s29
	s_nop 0
	global_load_lds_dwordx4 v136, s[48:49]
	s_mov_b32 m0, s41
	s_nop 0
	global_load_lds_dwordx4 v138, s[48:49]
	s_mov_b32 m0, s18
	s_waitcnt vmcnt(8)
	s_waitcnt lgkmcnt(0)
	s_setprio 1
	s_barrier
	v_mfma_f32_16x16x32_bf16 v[60:63], v[146:149], v[178:181], v[60:63]
	v_mfma_f32_16x16x32_bf16 v[56:59], v[154:157], v[178:181], v[56:59]
	v_mfma_f32_16x16x32_bf16 v[52:55], v[146:149], v[186:189], v[52:55]
	v_mfma_f32_16x16x32_bf16 v[44:47], v[154:157], v[186:189], v[44:47]
	v_mfma_f32_16x16x32_bf16 v[36:39], v[146:149], v[194:197], v[36:39]
	v_mfma_f32_16x16x32_bf16 v[28:31], v[154:157], v[194:197], v[28:31]
	v_mfma_f32_16x16x32_bf16 v[20:23], v[146:149], v[202:205], v[20:23]
	v_mfma_f32_16x16x32_bf16 v[12:15], v[154:157], v[202:205], v[12:15]
	v_mfma_f32_16x16x32_bf16 v[60:63], v[150:153], v[182:185], v[60:63]
	v_mfma_f32_16x16x32_bf16 v[56:59], v[158:161], v[182:185], v[56:59]
	v_mfma_f32_16x16x32_bf16 v[52:55], v[150:153], v[190:193], v[52:55]
	v_mfma_f32_16x16x32_bf16 v[44:47], v[158:161], v[190:193], v[44:47]
	v_mfma_f32_16x16x32_bf16 v[36:39], v[150:153], v[198:201], v[36:39]
	v_mfma_f32_16x16x32_bf16 v[28:31], v[158:161], v[198:201], v[28:31]
	v_mfma_f32_16x16x32_bf16 v[20:23], v[150:153], v[206:209], v[20:23]
	v_mfma_f32_16x16x32_bf16 v[12:15], v[158:161], v[206:209], v[12:15]
	v_mfma_f32_16x16x32_bf16 v[48:51], v[162:165], v[178:181], v[48:51]
	v_mfma_f32_16x16x32_bf16 v[40:43], v[170:173], v[178:181], v[40:43]
	v_mfma_f32_16x16x32_bf16 v[32:35], v[162:165], v[186:189], v[32:35]
	v_mfma_f32_16x16x32_bf16 v[24:27], v[170:173], v[186:189], v[24:27]
	v_mfma_f32_16x16x32_bf16 v[16:19], v[162:165], v[194:197], v[16:19]
	v_mfma_f32_16x16x32_bf16 v[8:11], v[170:173], v[194:197], v[8:11]
	v_mfma_f32_16x16x32_bf16 v[4:7], v[162:165], v[202:205], v[4:7]
	v_mfma_f32_16x16x32_bf16 v[0:3], v[170:173], v[202:205], v[0:3]
	v_mfma_f32_16x16x32_bf16 v[48:51], v[166:169], v[182:185], v[48:51]
	v_mfma_f32_16x16x32_bf16 v[40:43], v[174:177], v[182:185], v[40:43]
	v_mfma_f32_16x16x32_bf16 v[32:35], v[166:169], v[190:193], v[32:35]
	v_mfma_f32_16x16x32_bf16 v[24:27], v[174:177], v[190:193], v[24:27]
	v_mfma_f32_16x16x32_bf16 v[16:19], v[166:169], v[198:201], v[16:19]
	v_mfma_f32_16x16x32_bf16 v[8:11], v[174:177], v[198:201], v[8:11]
	v_mfma_f32_16x16x32_bf16 v[4:7], v[166:169], v[206:209], v[4:7]
	v_mfma_f32_16x16x32_bf16 v[0:3], v[174:177], v[206:209], v[0:3]
	s_barrier
; #define PG8_LDA(dst, b, h) do { _Pragma("unroll") for (int m = 0; m < 4; ++m) _Pragma("unroll") for (int k = 0; k < 2; ++k) dst[m][k] = *(const LAS bf16x8*)(lds + PG8_SA(b, h) + aoff + m * 2048 + k * 1024); } while (0)
; #define PG8_LDB(dst, b, h) do { _Pragma("unroll") for (int n = 0; n < 2; ++n) _Pragma("unroll") for (int k = 0; k < 2; ++k) dst[n][k] = *(const LAS bf16x8*)(lds + PG8_SB(b, h) + boff + n * 2048 + k * 1024); } while (0)
; #define PG8_MMA(ai, bj, At, Bt) do { __builtin_amdgcn_s_setprio(1); _Pragma("unroll") for (int m = 0; m < 4; ++m) _Pragma("unroll") for (int n = 0; n < 2; ++n) _Pragma("unroll") for (int k = 0; k < 2; ++k) \
;         acc[ai][bj][m][n] = __builtin_amdgcn_mfma_f32_16x16x32_bf16(Bt[n][k], At[m][k], acc[ai][bj][m][n], 0, 0, 0); __builtin_amdgcn_s_setprio(0); } while (0)
; #define PG8_WAIT_V(n) asm volatile("s_waitcnt vmcnt(" #n ")" ::: "memory")
; #define PG8_WAIT_L(n) asm volatile("s_waitcnt lgkmcnt(" #n ")" ::: "memory")
; #define PG8_BAR __builtin_amdgcn_s_barrier()
; #define PG8_SCHED __builtin_amdgcn_sched_barrier(0)
; template <class Epi, class Addr, bool ALIGN_EPI = true, class Order = StaticOrder>
; __device__ __forceinline__ void gemm_phase(LAS unsigned char* lds, const Gemm g, const Order& S, const Epi& E, const int wid) {
;     ...
;             PG8_LDB(B0, 1, 0); PG8_LDB(B1, 1, 1); PG8_SCHED; PG8_LDA(At, 1, 0); PG8_STAGE(PG8_SA(0, 1), a2 + hstepA, voffA);
;             PG8_WAIT_V(8); PG8_WAIT_L(0); PG8_BAR; PG8_MMA(0, 0, At, B0); PG8_MMA(0, 1, At, B1); PG8_BAR; PG8_SCHED;
;             PG8_LDA(At, 1, 1); PG8_STAGE(PG8_SB(1, 0), b3, voffB); PG8_STAGE(PG8_SB(1, 1), b3 + hstepB, voffB); PG8_STAGE(PG8_SA(1, 0), a3, voffA);
;             PG8_WAIT_V(8); PG8_WAIT_L(0); PG8_BAR; PG8_MMA(1, 0, At, B0); PG8_MMA(1, 1, At, B1); PG8_BAR; PG8_SCHED;
;         }
	s_setprio 0
	ds_read_b128 v[146:149], v143
	ds_read_b128 v[150:153], v143 offset:1024
	ds_read_b128 v[154:157], v143 offset:2048
	ds_read_b128 v[158:161], v143 offset:3072
	ds_read_b128 v[162:165], v144
	ds_read_b128 v[166:169], v144 offset:1024
	ds_read_b128 v[170:173], v144 offset:2048
	ds_read_b128 v[174:177], v144 offset:3072
	ds_read_b128 v[178:181], v142 offset:32768
	ds_read_b128 v[182:185], v142 offset:33792
	ds_read_b128 v[186:189], v142 offset:34816
	ds_read_b128 v[190:193], v142 offset:35840
	ds_read_b128 v[194:197], v142 offset:36864
	ds_read_b128 v[198:201], v142 offset:37888
	ds_read_b128 v[202:205], v142 offset:38912
	ds_read_b128 v[206:209], v142 offset:39936
	s_add_u32 s18, s48, 0x80000
	s_addc_u32 s19, s49, 0
	s_mov_b32 s24, m0
	s_mov_b32 m0, s43
	s_nop 0
	global_load_lds_dwordx4 v136, s[18:19]
	s_mov_b32 m0, s54
	s_nop 0
	global_load_lds_dwordx4 v138, s[18:19]
	s_mov_b32 m0, s24
	s_waitcnt vmcnt(8)
	s_waitcnt lgkmcnt(0)
	s_setprio 1
	s_barrier
	v_mfma_f32_16x16x32_bf16 v[124:127], v[146:149], v[178:181], v[124:127]
	v_mfma_f32_16x16x32_bf16 v[120:123], v[154:157], v[178:181], v[120:123]
	v_mfma_f32_16x16x32_bf16 v[116:119], v[146:149], v[186:189], v[116:119]
	v_mfma_f32_16x16x32_bf16 v[108:111], v[154:157], v[186:189], v[108:111]
	v_mfma_f32_16x16x32_bf16 v[100:103], v[146:149], v[194:197], v[100:103]
	v_mfma_f32_16x16x32_bf16 v[92:95], v[154:157], v[194:197], v[92:95]
	v_mfma_f32_16x16x32_bf16 v[84:87], v[146:149], v[202:205], v[84:87]
	v_mfma_f32_16x16x32_bf16 v[76:79], v[154:157], v[202:205], v[76:79]
	v_mfma_f32_16x16x32_bf16 v[124:127], v[150:153], v[182:185], v[124:127]
	v_mfma_f32_16x16x32_bf16 v[120:123], v[158:161], v[182:185], v[120:123]
	v_mfma_f32_16x16x32_bf16 v[116:119], v[150:153], v[190:193], v[116:119]
	v_mfma_f32_16x16x32_bf16 v[108:111], v[158:161], v[190:193], v[108:111]
	v_mfma_f32_16x16x32_bf16 v[100:103], v[150:153], v[198:201], v[100:103]
	v_mfma_f32_16x16x32_bf16 v[92:95], v[158:161], v[198:201], v[92:95]
	v_mfma_f32_16x16x32_bf16 v[84:87], v[150:153], v[206:209], v[84:87]
	v_mfma_f32_16x16x32_bf16 v[76:79], v[158:161], v[206:209], v[76:79]
	v_mfma_f32_16x16x32_bf16 v[112:115], v[162:165], v[178:181], v[112:115]
	v_mfma_f32_16x16x32_bf16 v[104:107], v[170:173], v[178:181], v[104:107]
	v_mfma_f32_16x16x32_bf16 v[96:99], v[162:165], v[186:189], v[96:99]
	v_mfma_f32_16x16x32_bf16 v[88:91], v[170:173], v[186:189], v[88:91]
	v_mfma_f32_16x16x32_bf16 v[80:83], v[162:165], v[194:197], v[80:83]
	v_mfma_f32_16x16x32_bf16 v[72:75], v[170:173], v[194:197], v[72:75]
	v_mfma_f32_16x16x32_bf16 v[68:71], v[162:165], v[202:205], v[68:71]
	v_mfma_f32_16x16x32_bf16 v[64:67], v[170:173], v[202:205], v[64:67]
	v_mfma_f32_16x16x32_bf16 v[112:115], v[166:169], v[182:185], v[112:115]
	v_mfma_f32_16x16x32_bf16 v[104:107], v[174:177], v[182:185], v[104:107]
	v_mfma_f32_16x16x32_bf16 v[96:99], v[166:169], v[190:193], v[96:99]
	v_mfma_f32_16x16x32_bf16 v[88:91], v[174:177], v[190:193], v[88:91]
	v_mfma_f32_16x16x32_bf16 v[80:83], v[166:169], v[198:201], v[80:83]
	v_mfma_f32_16x16x32_bf16 v[72:75], v[174:177], v[198:201], v[72:75]
	v_mfma_f32_16x16x32_bf16 v[68:71], v[166:169], v[206:209], v[68:71]
	v_mfma_f32_16x16x32_bf16 v[64:67], v[174:177], v[206:209], v[64:67]
	s_barrier
	s_setprio 0
	ds_read_b128 v[178:181], v142 offset:49152
	ds_read_b128 v[182:185], v142 offset:50176
	ds_read_b128 v[186:189], v142 offset:51200
	ds_read_b128 v[190:193], v142 offset:52224
	ds_read_b128 v[194:197], v142 offset:53248
	ds_read_b128 v[198:201], v142 offset:54272
	ds_read_b128 v[202:205], v142 offset:55296
	ds_read_b128 v[206:209], v142 offset:56320
	s_add_u32 s18, s46, 0x80
	s_addc_u32 s19, s47, 0
	s_mov_b32 s24, m0
	s_mov_b32 m0, s55
	s_nop 0
	global_load_lds_dwordx4 v137, s[18:19]
	s_mov_b32 m0, s56
	s_nop 0
	global_load_lds_dwordx4 v139, s[18:19]
	s_mov_b32 m0, s24
	s_add_u32 s18, s46, 0x80080
	s_addc_u32 s19, s47, 0
	s_mov_b32 s24, m0
	s_mov_b32 m0, s59
	s_nop 0
	global_load_lds_dwordx4 v137, s[18:19]
	s_mov_b32 m0, s60
	s_nop 0
	global_load_lds_dwordx4 v139, s[18:19]
	s_mov_b32 m0, s24
	s_mov_b32 s18, m0
	s_mov_b32 m0, s57
	s_nop 0
	global_load_lds_dwordx4 v136, s[44:45]
	s_mov_b32 m0, s58
	s_nop 0
	global_load_lds_dwordx4 v138, s[44:45]
	s_mov_b32 m0, s18
	s_waitcnt vmcnt(8)
	s_waitcnt lgkmcnt(0)
	s_setprio 1
	s_barrier
	v_mfma_f32_16x16x32_bf16 v[60:63], v[146:149], v[178:181], v[60:63]
	v_mfma_f32_16x16x32_bf16 v[56:59], v[154:157], v[178:181], v[56:59]
	v_mfma_f32_16x16x32_bf16 v[52:55], v[146:149], v[186:189], v[52:55]
	v_mfma_f32_16x16x32_bf16 v[44:47], v[154:157], v[186:189], v[44:47]
	v_mfma_f32_16x16x32_bf16 v[36:39], v[146:149], v[194:197], v[36:39]
	v_mfma_f32_16x16x32_bf16 v[28:31], v[154:157], v[194:197], v[28:31]
	v_mfma_f32_16x16x32_bf16 v[20:23], v[146:149], v[202:205], v[20:23]
	v_mfma_f32_16x16x32_bf16 v[12:15], v[154:157], v[202:205], v[12:15]
	v_mfma_f32_16x16x32_bf16 v[60:63], v[150:153], v[182:185], v[60:63]
	v_mfma_f32_16x16x32_bf16 v[56:59], v[158:161], v[182:185], v[56:59]
	v_mfma_f32_16x16x32_bf16 v[52:55], v[150:153], v[190:193], v[52:55]
	v_mfma_f32_16x16x32_bf16 v[44:47], v[158:161], v[190:193], v[44:47]
	v_mfma_f32_16x16x32_bf16 v[36:39], v[150:153], v[198:201], v[36:39]
	v_mfma_f32_16x16x32_bf16 v[28:31], v[158:161], v[198:201], v[28:31]
	v_mfma_f32_16x16x32_bf16 v[20:23], v[150:153], v[206:209], v[20:23]
	v_mfma_f32_16x16x32_bf16 v[12:15], v[158:161], v[206:209], v[12:15]
	v_mfma_f32_16x16x32_bf16 v[48:51], v[162:165], v[178:181], v[48:51]
	v_mfma_f32_16x16x32_bf16 v[40:43], v[170:173], v[178:181], v[40:43]
	v_mfma_f32_16x16x32_bf16 v[32:35], v[162:165], v[186:189], v[32:35]
	v_mfma_f32_16x16x32_bf16 v[24:27], v[170:173], v[186:189], v[24:27]
	v_mfma_f32_16x16x32_bf16 v[16:19], v[162:165], v[194:197], v[16:19]
	v_mfma_f32_16x16x32_bf16 v[8:11], v[170:173], v[194:197], v[8:11]
	v_mfma_f32_16x16x32_bf16 v[4:7], v[162:165], v[202:205], v[4:7]
	v_mfma_f32_16x16x32_bf16 v[0:3], v[170:173], v[202:205], v[0:3]
	v_mfma_f32_16x16x32_bf16 v[48:51], v[166:169], v[182:185], v[48:51]
	v_mfma_f32_16x16x32_bf16 v[40:43], v[174:177], v[182:185], v[40:43]
	v_mfma_f32_16x16x32_bf16 v[32:35], v[166:169], v[190:193], v[32:35]
	v_mfma_f32_16x16x32_bf16 v[24:27], v[174:177], v[190:193], v[24:27]
	v_mfma_f32_16x16x32_bf16 v[16:19], v[166:169], v[198:201], v[16:19]
	v_mfma_f32_16x16x32_bf16 v[8:11], v[174:177], v[198:201], v[8:11]
	v_mfma_f32_16x16x32_bf16 v[4:7], v[166:169], v[206:209], v[4:7]
	v_mfma_f32_16x16x32_bf16 v[0:3], v[174:177], v[206:209], v[0:3]
	s_barrier
	s_setprio 0
	s_add_i32 s77, s77, 2
	s_add_u32 s75, s75, 0x100
	s_addc_u32 s76, s76, 0
	s_cmp_gt_u32 s77, 29
	s_mov_b64 s[24:25], s[26:27]
	s_cbranch_scc0 .LBB0_656
	s_and_b64 vcc, exec, s[8:9]
	s_cbranch_vccz .LBB0_659
	s_barrier

; #define PG8_LDA(dst, b, h) do { _Pragma("unroll") for (int m = 0; m < 4; ++m) _Pragma("unroll") for (int k = 0; k < 2; ++k) dst[m][k] = *(const LAS bf16x8*)(lds + PG8_SA(b, h) + aoff + m * 2048 + k * 1024); } while (0)
; #define PG8_LDB(dst, b, h) do { _Pragma("unroll") for (int n = 0; n < 2; ++n) _Pragma("unroll") for (int k = 0; k < 2; ++k) dst[n][k] = *(const LAS bf16x8*)(lds + PG8_SB(b, h) + boff + n * 2048 + k * 1024); } while (0)
; #define PG8_MMA(ai, bj, At, Bt) do { __builtin_amdgcn_s_setprio(1); _Pragma("unroll") for (int m = 0; m < 4; ++m) _Pragma("unroll") for (int n = 0; n < 2; ++n) _Pragma("unroll") for (int k = 0; k < 2; ++k) \
;         acc[ai][bj][m][n] = __builtin_amdgcn_mfma_f32_16x16x32_bf16(Bt[n][k], At[m][k], acc[ai][bj][m][n], 0, 0, 0); __builtin_amdgcn_s_setprio(0); } while (0)
; #define PG8_WAIT_V(n) asm volatile("s_waitcnt vmcnt(" #n ")" ::: "memory")
; #define PG8_WAIT_L(n) asm volatile("s_waitcnt lgkmcnt(" #n ")" ::: "memory")
; #define PG8_BAR __builtin_amdgcn_s_barrier()
; template <class Epi, class Addr, bool ALIGN_EPI = true, class Order = StaticOrder>
; __device__ __forceinline__ void gemm_phase(LAS unsigned char* lds, const Gemm g, const Order& S, const Epi& E, const int wid) {
;     ...
;         for (int t = 0; t < nt; t += 2) {
;             const bool last = (t == nt - 2);
;             const char* a1 = cA + (size_t)(t + 1) * kstep;
;             const char* a2 = last ? nA : cA + (size_t)(t + 2) * kstep; const char* b2 = last ? nB : cB + (size_t)(t + 2) * kstep;
;             const char* a3 = a2 + kstep; const char* b3 = b2 + kstep;
;             PG8_LDB(B0, 0, 0); PG8_LDB(B1, 0, 1); PG8_SCHED; PG8_LDA(At, 0, 0); PG8_STAGE(PG8_SA(1, 1), a1 + hstepA, voffA);
;             PG8_WAIT_V(8); PG8_WAIT_L(0); PG8_BAR; PG8_MMA(0, 0, At, B0); PG8_MMA(0, 1, At, B1); PG8_BAR; PG8_SCHED;
;             PG8_LDA(At, 0, 1); PG8_STAGE(PG8_SB(0, 0), b2, voffB); PG8_STAGE(PG8_SB(0, 1), b2 + hstepB, voffB); PG8_STAGE(PG8_SA(0, 0), a2, voffA);
;             PG8_WAIT_V(8); PG8_WAIT_L(0); PG8_BAR; PG8_MMA(1, 0, At, B0); PG8_MMA(1, 1, At, B1); PG8_BAR; PG8_SCHED;
;             PG8_LDB(B0, 1, 0); PG8_LDB(B1, 1, 1); PG8_SCHED; PG8_LDA(At, 1, 0); PG8_STAGE(PG8_SA(0, 1), a2 + hstepA, voffA);
;             PG8_WAIT_V(8); PG8_WAIT_L(0); PG8_BAR; PG8_MMA(0, 0, At, B0); PG8_MMA(0, 1, At, B1); PG8_BAR; PG8_SCHED;
.LBB0_733:
	ds_read_b128 v[68:71], v164
	ds_read_b128 v[72:75], v164 offset:1024
	ds_read_b128 v[76:79], v164 offset:2048
	ds_read_b128 v[84:87], v164 offset:3072
	ds_read_b128 v[156:159], v165
	ds_read_b128 v[170:173], v165 offset:1024
	ds_read_b128 v[174:177], v165 offset:2048
	ds_read_b128 v[178:181], v165 offset:3072
	s_add_u32 s46, s44, 0x100
	s_addc_u32 s47, s45, 0
	s_cmp_eq_u32 s80, 60
	s_cselect_b32 s52, s25, s46
	s_cselect_b32 s53, s17, s47
	s_cselect_b32 s50, s27, s78
	s_cselect_b32 s51, s15, s79
	s_add_u32 s48, s52, 0x80
	s_addc_u32 s49, s53, 0
	ds_read_b128 v[182:185], v166
	ds_read_b128 v[186:189], v166 offset:1024
	ds_read_b128 v[190:193], v166 offset:2048
	ds_read_b128 v[194:197], v166 offset:3072
	ds_read_b128 v[198:201], v166 offset:4096
	ds_read_b128 v[202:205], v166 offset:5120
	ds_read_b128 v[206:209], v166 offset:6144
	ds_read_b128 v[210:213], v166 offset:7168
	s_add_u32 s18, s44, 0x100080
	s_addc_u32 s19, s45, 0
	s_mov_b32 s36, m0
	s_mov_b32 m0, s68
	s_nop 0
	global_load_lds_dwordx4 v160, s[18:19]
	s_mov_b32 m0, s69
	s_nop 0
	global_load_lds_dwordx4 v162, s[18:19]
	s_mov_b32 m0, s36
	s_waitcnt vmcnt(8)
	s_waitcnt lgkmcnt(0)
	s_setprio 1
	s_barrier
	v_mfma_f32_16x16x32_bf16 v[140:143], v[68:71], v[182:185], v[140:143]
	v_mfma_f32_16x16x32_bf16 v[136:139], v[76:79], v[182:185], v[136:139]
	v_mfma_f32_16x16x32_bf16 v[124:127], v[68:71], v[190:193], v[124:127]
	v_mfma_f32_16x16x32_bf16 v[120:123], v[76:79], v[190:193], v[120:123]
	v_mfma_f32_16x16x32_bf16 v[108:111], v[68:71], v[198:201], v[108:111]
	v_mfma_f32_16x16x32_bf16 v[104:107], v[76:79], v[198:201], v[104:107]
	v_mfma_f32_16x16x32_bf16 v[92:95], v[68:71], v[206:209], v[92:95]
	v_mfma_f32_16x16x32_bf16 v[88:91], v[76:79], v[206:209], v[88:91]
	v_mfma_f32_16x16x32_bf16 v[140:143], v[72:75], v[186:189], v[140:143]
	v_mfma_f32_16x16x32_bf16 v[136:139], v[84:87], v[186:189], v[136:139]
	v_mfma_f32_16x16x32_bf16 v[124:127], v[72:75], v[194:197], v[124:127]
	v_mfma_f32_16x16x32_bf16 v[120:123], v[84:87], v[194:197], v[120:123]
	v_mfma_f32_16x16x32_bf16 v[108:111], v[72:75], v[202:205], v[108:111]
	v_mfma_f32_16x16x32_bf16 v[104:107], v[84:87], v[202:205], v[104:107]
	v_mfma_f32_16x16x32_bf16 v[92:95], v[72:75], v[210:213], v[92:95]
	v_mfma_f32_16x16x32_bf16 v[88:91], v[84:87], v[210:213], v[88:91]
	v_mfma_f32_16x16x32_bf16 v[132:135], v[156:159], v[182:185], v[132:135]
	v_mfma_f32_16x16x32_bf16 v[128:131], v[174:177], v[182:185], v[128:131]
	v_mfma_f32_16x16x32_bf16 v[116:119], v[156:159], v[190:193], v[116:119]
	v_mfma_f32_16x16x32_bf16 v[112:115], v[174:177], v[190:193], v[112:115]
	v_mfma_f32_16x16x32_bf16 v[100:103], v[156:159], v[198:201], v[100:103]
	v_mfma_f32_16x16x32_bf16 v[96:99], v[174:177], v[198:201], v[96:99]
	v_mfma_f32_16x16x32_bf16 v[80:83], v[156:159], v[206:209], v[80:83]
	v_mfma_f32_16x16x32_bf16 v[64:67], v[174:177], v[206:209], v[64:67]
	v_mfma_f32_16x16x32_bf16 v[132:135], v[170:173], v[186:189], v[132:135]
	v_mfma_f32_16x16x32_bf16 v[128:131], v[178:181], v[186:189], v[128:131]
	v_mfma_f32_16x16x32_bf16 v[116:119], v[170:173], v[194:197], v[116:119]
	v_mfma_f32_16x16x32_bf16 v[112:115], v[178:181], v[194:197], v[112:115]
	v_mfma_f32_16x16x32_bf16 v[100:103], v[170:173], v[202:205], v[100:103]
	v_mfma_f32_16x16x32_bf16 v[96:99], v[178:181], v[202:205], v[96:99]
	v_mfma_f32_16x16x32_bf16 v[80:83], v[170:173], v[210:213], v[80:83]
	v_mfma_f32_16x16x32_bf16 v[64:67], v[178:181], v[210:213], v[64:67]
	s_barrier
	s_setprio 0
	ds_read_b128 v[182:185], v166 offset:16384
	ds_read_b128 v[186:189], v166 offset:17408
	ds_read_b128 v[190:193], v166 offset:18432
	ds_read_b128 v[194:197], v166 offset:19456
	ds_read_b128 v[198:201], v166 offset:20480
	ds_read_b128 v[202:205], v166 offset:21504
	ds_read_b128 v[206:209], v166 offset:22528
	ds_read_b128 v[210:213], v166 offset:23552
	s_mov_b32 s18, m0
	s_mov_b32 m0, s43
	s_nop 0
	global_load_lds_dwordx4 v161, s[50:51]
	s_mov_b32 m0, s54
	s_nop 0
	global_load_lds_dwordx4 v163, s[50:51]
	s_mov_b32 m0, s18
	s_add_u32 s18, s50, 0x100000
	s_addc_u32 s19, s51, 0
	s_mov_b32 s36, m0
	s_mov_b32 m0, s55
	s_nop 0
	global_load_lds_dwordx4 v161, s[18:19]
	s_mov_b32 m0, s56
	s_nop 0
	global_load_lds_dwordx4 v163, s[18:19]
	s_mov_b32 m0, s36
	s_mov_b32 s18, m0
	s_mov_b32 m0, s41
	s_nop 0
	global_load_lds_dwordx4 v160, s[52:53]
	s_mov_b32 m0, s57
	s_nop 0
	global_load_lds_dwordx4 v162, s[52:53]
	s_mov_b32 m0, s18
	s_waitcnt vmcnt(8)
	s_waitcnt lgkmcnt(0)
	s_setprio 1
	s_barrier
	v_mfma_f32_16x16x32_bf16 v[60:63], v[68:71], v[182:185], v[60:63]
	v_mfma_f32_16x16x32_bf16 v[56:59], v[76:79], v[182:185], v[56:59]
	v_mfma_f32_16x16x32_bf16 v[44:47], v[68:71], v[190:193], v[44:47]
	v_mfma_f32_16x16x32_bf16 v[40:43], v[76:79], v[190:193], v[40:43]
	v_mfma_f32_16x16x32_bf16 v[28:31], v[68:71], v[198:201], v[28:31]
	v_mfma_f32_16x16x32_bf16 v[24:27], v[76:79], v[198:201], v[24:27]
	v_mfma_f32_16x16x32_bf16 v[12:15], v[68:71], v[206:209], v[12:15]
	v_mfma_f32_16x16x32_bf16 v[8:11], v[76:79], v[206:209], v[8:11]
	v_mfma_f32_16x16x32_bf16 v[60:63], v[72:75], v[186:189], v[60:63]
	v_mfma_f32_16x16x32_bf16 v[56:59], v[84:87], v[186:189], v[56:59]
	v_mfma_f32_16x16x32_bf16 v[44:47], v[72:75], v[194:197], v[44:47]
	v_mfma_f32_16x16x32_bf16 v[40:43], v[84:87], v[194:197], v[40:43]
	v_mfma_f32_16x16x32_bf16 v[28:31], v[72:75], v[202:205], v[28:31]
	v_mfma_f32_16x16x32_bf16 v[24:27], v[84:87], v[202:205], v[24:27]
	v_mfma_f32_16x16x32_bf16 v[12:15], v[72:75], v[210:213], v[12:15]
	v_mfma_f32_16x16x32_bf16 v[8:11], v[84:87], v[210:213], v[8:11]
	v_mfma_f32_16x16x32_bf16 v[52:55], v[156:159], v[182:185], v[52:55]
	v_mfma_f32_16x16x32_bf16 v[48:51], v[174:177], v[182:185], v[48:51]
	v_mfma_f32_16x16x32_bf16 v[36:39], v[156:159], v[190:193], v[36:39]
	v_mfma_f32_16x16x32_bf16 v[32:35], v[174:177], v[190:193], v[32:35]
	v_mfma_f32_16x16x32_bf16 v[20:23], v[156:159], v[198:201], v[20:23]
	v_mfma_f32_16x16x32_bf16 v[16:19], v[174:177], v[198:201], v[16:19]
	v_mfma_f32_16x16x32_bf16 v[4:7], v[156:159], v[206:209], v[4:7]
	v_mfma_f32_16x16x32_bf16 v[0:3], v[174:177], v[206:209], v[0:3]
	v_mfma_f32_16x16x32_bf16 v[52:55], v[170:173], v[186:189], v[52:55]
	v_mfma_f32_16x16x32_bf16 v[48:51], v[178:181], v[186:189], v[48:51]
	v_mfma_f32_16x16x32_bf16 v[36:39], v[170:173], v[194:197], v[36:39]
	v_mfma_f32_16x16x32_bf16 v[32:35], v[178:181], v[194:197], v[32:35]
	v_mfma_f32_16x16x32_bf16 v[20:23], v[170:173], v[202:205], v[20:23]
	v_mfma_f32_16x16x32_bf16 v[16:19], v[178:181], v[202:205], v[16:19]
	v_mfma_f32_16x16x32_bf16 v[4:7], v[170:173], v[210:213], v[4:7]
	v_mfma_f32_16x16x32_bf16 v[0:3], v[178:181], v[210:213], v[0:3]
	s_barrier
; #define PG8_LDA(dst, b, h) do { _Pragma("unroll") for (int m = 0; m < 4; ++m) _Pragma("unroll") for (int k = 0; k < 2; ++k) dst[m][k] = *(const LAS bf16x8*)(lds + PG8_SA(b, h) + aoff + m * 2048 + k * 1024); } while (0)
; #define PG8_LDB(dst, b, h) do { _Pragma("unroll") for (int n = 0; n < 2; ++n) _Pragma("unroll") for (int k = 0; k < 2; ++k) dst[n][k] = *(const LAS bf16x8*)(lds + PG8_SB(b, h) + boff + n * 2048 + k * 1024); } while (0)
; #define PG8_MMA(ai, bj, At, Bt) do { __builtin_amdgcn_s_setprio(1); _Pragma("unroll") for (int m = 0; m < 4; ++m) _Pragma("unroll") for (int n = 0; n < 2; ++n) _Pragma("unroll") for (int k = 0; k < 2; ++k) \
;         acc[ai][bj][m][n] = __builtin_amdgcn_mfma_f32_16x16x32_bf16(Bt[n][k], At[m][k], acc[ai][bj][m][n], 0, 0, 0); __builtin_amdgcn_s_setprio(0); } while (0)
; #define PG8_WAIT_V(n) asm volatile("s_waitcnt vmcnt(" #n ")" ::: "memory")
; #define PG8_WAIT_L(n) asm volatile("s_waitcnt lgkmcnt(" #n ")" ::: "memory")
; #define PG8_BAR __builtin_amdgcn_s_barrier()
; #define PG8_SCHED __builtin_amdgcn_sched_barrier(0)
; template <class Epi, class Addr, bool ALIGN_EPI = true, class Order = StaticOrder>
; __device__ __forceinline__ void gemm_phase(LAS unsigned char* lds, const Gemm g, const Order& S, const Epi& E, const int wid) {
;     ...
;             PG8_LDB(B0, 1, 0); PG8_LDB(B1, 1, 1); PG8_SCHED; PG8_LDA(At, 1, 0); PG8_STAGE(PG8_SA(0, 1), a2 + hstepA, voffA);
;             PG8_WAIT_V(8); PG8_WAIT_L(0); PG8_BAR; PG8_MMA(0, 0, At, B0); PG8_MMA(0, 1, At, B1); PG8_BAR; PG8_SCHED;
;             PG8_LDA(At, 1, 1); PG8_STAGE(PG8_SB(1, 0), b3, voffB); PG8_STAGE(PG8_SB(1, 1), b3 + hstepB, voffB); PG8_STAGE(PG8_SA(1, 0), a3, voffA);
;             PG8_WAIT_V(8); PG8_WAIT_L(0); PG8_BAR; PG8_MMA(1, 0, At, B0); PG8_MMA(1, 1, At, B1); PG8_BAR; PG8_SCHED;
;         }
	s_setprio 0
	ds_read_b128 v[68:71], v167
	ds_read_b128 v[72:75], v167 offset:1024
	ds_read_b128 v[76:79], v167 offset:2048
	ds_read_b128 v[84:87], v167 offset:3072
	ds_read_b128 v[156:159], v168
	ds_read_b128 v[170:173], v168 offset:1024
	ds_read_b128 v[174:177], v168 offset:2048
	ds_read_b128 v[178:181], v168 offset:3072
	ds_read_b128 v[182:185], v166 offset:32768
	ds_read_b128 v[186:189], v166 offset:33792
	ds_read_b128 v[190:193], v166 offset:34816
	ds_read_b128 v[194:197], v166 offset:35840
	ds_read_b128 v[198:201], v166 offset:36864
	ds_read_b128 v[202:205], v166 offset:37888
	ds_read_b128 v[206:209], v166 offset:38912
	ds_read_b128 v[210:213], v166 offset:39936
	s_add_u32 s18, s52, 0x100000
	s_addc_u32 s19, s53, 0
	s_mov_b32 s36, m0
	s_mov_b32 m0, s59
	s_nop 0
	global_load_lds_dwordx4 v160, s[18:19]
	s_mov_b32 m0, s60
	s_nop 0
	global_load_lds_dwordx4 v162, s[18:19]
	s_mov_b32 m0, s36
	s_waitcnt vmcnt(8)
	s_waitcnt lgkmcnt(0)
	s_setprio 1
	s_barrier
	v_mfma_f32_16x16x32_bf16 v[140:143], v[68:71], v[182:185], v[140:143]
	v_mfma_f32_16x16x32_bf16 v[136:139], v[76:79], v[182:185], v[136:139]
	v_mfma_f32_16x16x32_bf16 v[124:127], v[68:71], v[190:193], v[124:127]
	v_mfma_f32_16x16x32_bf16 v[120:123], v[76:79], v[190:193], v[120:123]
	v_mfma_f32_16x16x32_bf16 v[108:111], v[68:71], v[198:201], v[108:111]
	v_mfma_f32_16x16x32_bf16 v[104:107], v[76:79], v[198:201], v[104:107]
	v_mfma_f32_16x16x32_bf16 v[92:95], v[68:71], v[206:209], v[92:95]
	v_mfma_f32_16x16x32_bf16 v[88:91], v[76:79], v[206:209], v[88:91]
	v_mfma_f32_16x16x32_bf16 v[140:143], v[72:75], v[186:189], v[140:143]
	v_mfma_f32_16x16x32_bf16 v[136:139], v[84:87], v[186:189], v[136:139]
	v_mfma_f32_16x16x32_bf16 v[124:127], v[72:75], v[194:197], v[124:127]
	v_mfma_f32_16x16x32_bf16 v[120:123], v[84:87], v[194:197], v[120:123]
	v_mfma_f32_16x16x32_bf16 v[108:111], v[72:75], v[202:205], v[108:111]
	v_mfma_f32_16x16x32_bf16 v[104:107], v[84:87], v[202:205], v[104:107]
	v_mfma_f32_16x16x32_bf16 v[92:95], v[72:75], v[210:213], v[92:95]
	v_mfma_f32_16x16x32_bf16 v[88:91], v[84:87], v[210:213], v[88:91]
	v_mfma_f32_16x16x32_bf16 v[132:135], v[156:159], v[182:185], v[132:135]
	v_mfma_f32_16x16x32_bf16 v[128:131], v[174:177], v[182:185], v[128:131]
	v_mfma_f32_16x16x32_bf16 v[116:119], v[156:159], v[190:193], v[116:119]
	v_mfma_f32_16x16x32_bf16 v[112:115], v[174:177], v[190:193], v[112:115]
	v_mfma_f32_16x16x32_bf16 v[100:103], v[156:159], v[198:201], v[100:103]
	v_mfma_f32_16x16x32_bf16 v[96:99], v[174:177], v[198:201], v[96:99]
	v_mfma_f32_16x16x32_bf16 v[80:83], v[156:159], v[206:209], v[80:83]
	v_mfma_f32_16x16x32_bf16 v[64:67], v[174:177], v[206:209], v[64:67]
	v_mfma_f32_16x16x32_bf16 v[132:135], v[170:173], v[186:189], v[132:135]
	v_mfma_f32_16x16x32_bf16 v[128:131], v[178:181], v[186:189], v[128:131]
	v_mfma_f32_16x16x32_bf16 v[116:119], v[170:173], v[194:197], v[116:119]
	v_mfma_f32_16x16x32_bf16 v[112:115], v[178:181], v[194:197], v[112:115]
	v_mfma_f32_16x16x32_bf16 v[100:103], v[170:173], v[202:205], v[100:103]
	v_mfma_f32_16x16x32_bf16 v[96:99], v[178:181], v[202:205], v[96:99]
	v_mfma_f32_16x16x32_bf16 v[80:83], v[170:173], v[210:213], v[80:83]
	v_mfma_f32_16x16x32_bf16 v[64:67], v[178:181], v[210:213], v[64:67]
	s_barrier
	s_setprio 0
	ds_read_b128 v[182:185], v166 offset:49152
	ds_read_b128 v[186:189], v166 offset:50176
	ds_read_b128 v[190:193], v166 offset:51200
	ds_read_b128 v[194:197], v166 offset:52224
	ds_read_b128 v[198:201], v166 offset:53248
	ds_read_b128 v[202:205], v166 offset:54272
	ds_read_b128 v[206:209], v166 offset:55296
	ds_read_b128 v[210:213], v166 offset:56320
	s_add_u32 s18, s50, 0x80
	s_addc_u32 s19, s51, 0
	s_mov_b32 s36, m0
	s_mov_b32 m0, s62
	s_nop 0
	global_load_lds_dwordx4 v161, s[18:19]
	s_mov_b32 m0, s63
	s_nop 0
	global_load_lds_dwordx4 v163, s[18:19]
	s_mov_b32 m0, s36
	s_add_u32 s18, s50, 0x100080
	s_addc_u32 s19, s51, 0
	s_mov_b32 s36, m0
	s_mov_b32 m0, s66
	s_nop 0
	global_load_lds_dwordx4 v161, s[18:19]
	s_mov_b32 m0, s67
	s_nop 0
	global_load_lds_dwordx4 v163, s[18:19]
	s_mov_b32 m0, s36
	s_mov_b32 s18, m0
	s_mov_b32 m0, s64
	s_nop 0
	global_load_lds_dwordx4 v160, s[48:49]
	s_mov_b32 m0, s65
	s_nop 0
	global_load_lds_dwordx4 v162, s[48:49]
	s_mov_b32 m0, s18
	s_waitcnt vmcnt(8)
	s_waitcnt lgkmcnt(0)
	s_setprio 1
	s_barrier
	v_mfma_f32_16x16x32_bf16 v[60:63], v[68:71], v[182:185], v[60:63]
	v_mfma_f32_16x16x32_bf16 v[56:59], v[76:79], v[182:185], v[56:59]
	v_mfma_f32_16x16x32_bf16 v[44:47], v[68:71], v[190:193], v[44:47]
	v_mfma_f32_16x16x32_bf16 v[40:43], v[76:79], v[190:193], v[40:43]
	v_mfma_f32_16x16x32_bf16 v[28:31], v[68:71], v[198:201], v[28:31]
	v_mfma_f32_16x16x32_bf16 v[24:27], v[76:79], v[198:201], v[24:27]
	v_mfma_f32_16x16x32_bf16 v[12:15], v[68:71], v[206:209], v[12:15]
	v_mfma_f32_16x16x32_bf16 v[8:11], v[76:79], v[206:209], v[8:11]
	v_mfma_f32_16x16x32_bf16 v[60:63], v[72:75], v[186:189], v[60:63]
	v_mfma_f32_16x16x32_bf16 v[56:59], v[84:87], v[186:189], v[56:59]
	v_mfma_f32_16x16x32_bf16 v[44:47], v[72:75], v[194:197], v[44:47]
	v_mfma_f32_16x16x32_bf16 v[40:43], v[84:87], v[194:197], v[40:43]
	v_mfma_f32_16x16x32_bf16 v[28:31], v[72:75], v[202:205], v[28:31]
	v_mfma_f32_16x16x32_bf16 v[24:27], v[84:87], v[202:205], v[24:27]
	v_mfma_f32_16x16x32_bf16 v[12:15], v[72:75], v[210:213], v[12:15]
	v_mfma_f32_16x16x32_bf16 v[8:11], v[84:87], v[210:213], v[8:11]
	v_mfma_f32_16x16x32_bf16 v[52:55], v[156:159], v[182:185], v[52:55]
	v_mfma_f32_16x16x32_bf16 v[48:51], v[174:177], v[182:185], v[48:51]
	v_mfma_f32_16x16x32_bf16 v[36:39], v[156:159], v[190:193], v[36:39]
	v_mfma_f32_16x16x32_bf16 v[32:35], v[174:177], v[190:193], v[32:35]
	v_mfma_f32_16x16x32_bf16 v[20:23], v[156:159], v[198:201], v[20:23]
	v_mfma_f32_16x16x32_bf16 v[16:19], v[174:177], v[198:201], v[16:19]
	v_mfma_f32_16x16x32_bf16 v[4:7], v[156:159], v[206:209], v[4:7]
	v_mfma_f32_16x16x32_bf16 v[0:3], v[174:177], v[206:209], v[0:3]
	v_mfma_f32_16x16x32_bf16 v[52:55], v[170:173], v[186:189], v[52:55]
	v_mfma_f32_16x16x32_bf16 v[48:51], v[178:181], v[186:189], v[48:51]
	v_mfma_f32_16x16x32_bf16 v[36:39], v[170:173], v[194:197], v[36:39]
	v_mfma_f32_16x16x32_bf16 v[32:35], v[178:181], v[194:197], v[32:35]
	v_mfma_f32_16x16x32_bf16 v[20:23], v[170:173], v[202:205], v[20:23]
	v_mfma_f32_16x16x32_bf16 v[16:19], v[178:181], v[202:205], v[16:19]
	v_mfma_f32_16x16x32_bf16 v[4:7], v[170:173], v[210:213], v[4:7]
	v_mfma_f32_16x16x32_bf16 v[0:3], v[178:181], v[210:213], v[0:3]
	s_barrier
	s_setprio 0
	s_add_i32 s80, s80, 2
	s_add_u32 s78, s78, 0x100
	s_addc_u32 s79, s79, 0
	s_cmp_gt_u32 s80, 61
	s_mov_b64 s[44:45], s[46:47]
	s_cbranch_scc0 .LBB0_733
	s_and_b64 vcc, exec, s[10:11]
	s_cbranch_vccz .LBB0_736
	s_barrier

; #define PG8_LDA(dst, b, h) do { _Pragma("unroll") for (int m = 0; m < 4; ++m) _Pragma("unroll") for (int k = 0; k < 2; ++k) dst[m][k] = *(const LAS bf16x8*)(lds + PG8_SA(b, h) + aoff + m * 2048 + k * 1024); } while (0)
; #define PG8_LDB(dst, b, h) do { _Pragma("unroll") for (int n = 0; n < 2; ++n) _Pragma("unroll") for (int k = 0; k < 2; ++k) dst[n][k] = *(const LAS bf16x8*)(lds + PG8_SB(b, h) + boff + n * 2048 + k * 1024); } while (0)
; #define PG8_MMA(ai, bj, At, Bt) do { __builtin_amdgcn_s_setprio(1); _Pragma("unroll") for (int m = 0; m < 4; ++m) _Pragma("unroll") for (int n = 0; n < 2; ++n) _Pragma("unroll") for (int k = 0; k < 2; ++k) \
;         acc[ai][bj][m][n] = __builtin_amdgcn_mfma_f32_16x16x32_bf16(Bt[n][k], At[m][k], acc[ai][bj][m][n], 0, 0, 0); __builtin_amdgcn_s_setprio(0); } while (0)
; #define PG8_WAIT_V(n) asm volatile("s_waitcnt vmcnt(" #n ")" ::: "memory")
; #define PG8_WAIT_L(n) asm volatile("s_waitcnt lgkmcnt(" #n ")" ::: "memory")
; #define PG8_BAR __builtin_amdgcn_s_barrier()
; template <class Epi, class Addr, bool ALIGN_EPI = true, class Order = StaticOrder>
; __device__ __forceinline__ void gemm_phase(LAS unsigned char* lds, const Gemm g, const Order& S, const Epi& E, const int wid) {
;     ...
;         for (int t = 0; t < nt; t += 2) {
;             const bool last = (t == nt - 2);
;             const char* a1 = cA + (size_t)(t + 1) * kstep;
;             const char* a2 = last ? nA : cA + (size_t)(t + 2) * kstep; const char* b2 = last ? nB : cB + (size_t)(t + 2) * kstep;
;             const char* a3 = a2 + kstep; const char* b3 = b2 + kstep;
;             PG8_LDB(B0, 0, 0); PG8_LDB(B1, 0, 1); PG8_SCHED; PG8_LDA(At, 0, 0); PG8_STAGE(PG8_SA(1, 1), a1 + hstepA, voffA);
;             PG8_WAIT_V(8); PG8_WAIT_L(0); PG8_BAR; PG8_MMA(0, 0, At, B0); PG8_MMA(0, 1, At, B1); PG8_BAR; PG8_SCHED;
;             PG8_LDA(At, 0, 1); PG8_STAGE(PG8_SB(0, 0), b2, voffB); PG8_STAGE(PG8_SB(0, 1), b2 + hstepB, voffB); PG8_STAGE(PG8_SA(0, 0), a2, voffA);
;             PG8_WAIT_V(8); PG8_WAIT_L(0); PG8_BAR; PG8_MMA(1, 0, At, B0); PG8_MMA(1, 1, At, B1); PG8_BAR; PG8_SCHED;
;             PG8_LDB(B0, 1, 0); PG8_LDB(B1, 1, 1); PG8_SCHED; PG8_LDA(At, 1, 0); PG8_STAGE(PG8_SA(0, 1), a2 + hstepA, voffA);
;             PG8_WAIT_V(8); PG8_WAIT_L(0); PG8_BAR; PG8_MMA(0, 0, At, B0); PG8_MMA(0, 1, At, B1); PG8_BAR; PG8_SCHED;
.LBB0_814:
	ds_read_b128 v[134:137], v160
	ds_read_b128 v[138:141], v160 offset:1024
	ds_read_b128 v[142:145], v160 offset:2048
	ds_read_b128 v[146:149], v160 offset:3072
	ds_read_b128 v[150:153], v161
	ds_read_b128 v[166:169], v161 offset:1024
	ds_read_b128 v[170:173], v161 offset:2048
	ds_read_b128 v[174:177], v161 offset:3072
	s_add_u32 s50, s48, 0x100
	s_addc_u32 s51, s49, 0
	s_cmp_eq_u32 s77, 60
	s_cselect_b32 s56, s45, s50
	s_cselect_b32 s57, s23, s51
	s_cselect_b32 s54, s47, s75
	s_cselect_b32 s55, s21, s76
	s_add_u32 s52, s56, 0x80
	s_addc_u32 s53, s57, 0
	ds_read_b128 v[178:181], v162
	ds_read_b128 v[182:185], v162 offset:1024
	ds_read_b128 v[186:189], v162 offset:2048
	ds_read_b128 v[190:193], v162 offset:3072
	ds_read_b128 v[194:197], v162 offset:4096
	ds_read_b128 v[198:201], v162 offset:5120
	ds_read_b128 v[202:205], v162 offset:6144
	ds_read_b128 v[206:209], v162 offset:7168
	s_add_u32 s18, s48, 0x100080
	s_addc_u32 s19, s49, 0
	s_mov_b32 s36, m0
	s_mov_b32 m0, s72
	s_nop 0
	global_load_lds_dwordx4 v156, s[18:19]
	s_mov_b32 m0, s73
	s_nop 0
	global_load_lds_dwordx4 v157, s[18:19]
	s_mov_b32 m0, s36
	s_waitcnt vmcnt(8)
	s_waitcnt lgkmcnt(0)
	s_setprio 1
	s_barrier
	v_mfma_f32_16x16x32_bf16 v[124:127], v[134:137], v[178:181], v[124:127]
	v_mfma_f32_16x16x32_bf16 v[120:123], v[142:145], v[178:181], v[120:123]
	v_mfma_f32_16x16x32_bf16 v[108:111], v[134:137], v[186:189], v[108:111]
	v_mfma_f32_16x16x32_bf16 v[104:107], v[142:145], v[186:189], v[104:107]
	v_mfma_f32_16x16x32_bf16 v[92:95], v[134:137], v[194:197], v[92:95]
	v_mfma_f32_16x16x32_bf16 v[88:91], v[142:145], v[194:197], v[88:91]
	v_mfma_f32_16x16x32_bf16 v[76:79], v[134:137], v[202:205], v[76:79]
	v_mfma_f32_16x16x32_bf16 v[72:75], v[142:145], v[202:205], v[72:75]
	v_mfma_f32_16x16x32_bf16 v[124:127], v[138:141], v[182:185], v[124:127]
	v_mfma_f32_16x16x32_bf16 v[120:123], v[146:149], v[182:185], v[120:123]
	v_mfma_f32_16x16x32_bf16 v[108:111], v[138:141], v[190:193], v[108:111]
	v_mfma_f32_16x16x32_bf16 v[104:107], v[146:149], v[190:193], v[104:107]
	v_mfma_f32_16x16x32_bf16 v[92:95], v[138:141], v[198:201], v[92:95]
	v_mfma_f32_16x16x32_bf16 v[88:91], v[146:149], v[198:201], v[88:91]
	v_mfma_f32_16x16x32_bf16 v[76:79], v[138:141], v[206:209], v[76:79]
	v_mfma_f32_16x16x32_bf16 v[72:75], v[146:149], v[206:209], v[72:75]
	v_mfma_f32_16x16x32_bf16 v[116:119], v[150:153], v[178:181], v[116:119]
	v_mfma_f32_16x16x32_bf16 v[112:115], v[170:173], v[178:181], v[112:115]
	v_mfma_f32_16x16x32_bf16 v[100:103], v[150:153], v[186:189], v[100:103]
	v_mfma_f32_16x16x32_bf16 v[96:99], v[170:173], v[186:189], v[96:99]
	v_mfma_f32_16x16x32_bf16 v[84:87], v[150:153], v[194:197], v[84:87]
	v_mfma_f32_16x16x32_bf16 v[80:83], v[170:173], v[194:197], v[80:83]
	v_mfma_f32_16x16x32_bf16 v[68:71], v[150:153], v[202:205], v[68:71]
	v_mfma_f32_16x16x32_bf16 v[64:67], v[170:173], v[202:205], v[64:67]
	v_mfma_f32_16x16x32_bf16 v[116:119], v[166:169], v[182:185], v[116:119]
	v_mfma_f32_16x16x32_bf16 v[112:115], v[174:177], v[182:185], v[112:115]
	v_mfma_f32_16x16x32_bf16 v[100:103], v[166:169], v[190:193], v[100:103]
	v_mfma_f32_16x16x32_bf16 v[96:99], v[174:177], v[190:193], v[96:99]
	v_mfma_f32_16x16x32_bf16 v[84:87], v[166:169], v[198:201], v[84:87]
	v_mfma_f32_16x16x32_bf16 v[80:83], v[174:177], v[198:201], v[80:83]
	v_mfma_f32_16x16x32_bf16 v[68:71], v[166:169], v[206:209], v[68:71]
	v_mfma_f32_16x16x32_bf16 v[64:67], v[174:177], v[206:209], v[64:67]
	s_barrier
	s_setprio 0
	ds_read_b128 v[178:181], v162 offset:16384
	ds_read_b128 v[182:185], v162 offset:17408
	ds_read_b128 v[186:189], v162 offset:18432
	ds_read_b128 v[190:193], v162 offset:19456
	ds_read_b128 v[194:197], v162 offset:20480
	ds_read_b128 v[198:201], v162 offset:21504
	ds_read_b128 v[202:205], v162 offset:22528
	ds_read_b128 v[206:209], v162 offset:23552
	s_mov_b32 s18, m0
	s_mov_b32 m0, s43
	s_nop 0
	global_load_lds_dwordx4 v156, s[54:55]
	s_mov_b32 m0, s58
	s_nop 0
	global_load_lds_dwordx4 v157, s[54:55]
	s_mov_b32 m0, s18
	s_add_u32 s18, s54, 0x100000
	s_addc_u32 s19, s55, 0
	s_mov_b32 s36, m0
	s_mov_b32 m0, s59
	s_nop 0
	global_load_lds_dwordx4 v156, s[18:19]
	s_mov_b32 m0, s60
	s_nop 0
	global_load_lds_dwordx4 v157, s[18:19]
	s_mov_b32 m0, s36
	s_mov_b32 s18, m0
	s_mov_b32 m0, s41
	s_nop 0
	global_load_lds_dwordx4 v156, s[56:57]
	s_mov_b32 m0, s61
	s_nop 0
	global_load_lds_dwordx4 v157, s[56:57]
	s_mov_b32 m0, s18
	s_waitcnt vmcnt(8)
	s_waitcnt lgkmcnt(0)
	s_setprio 1
	s_barrier
	v_mfma_f32_16x16x32_bf16 v[60:63], v[134:137], v[178:181], v[60:63]
	v_mfma_f32_16x16x32_bf16 v[56:59], v[142:145], v[178:181], v[56:59]
	v_mfma_f32_16x16x32_bf16 v[44:47], v[134:137], v[186:189], v[44:47]
	v_mfma_f32_16x16x32_bf16 v[40:43], v[142:145], v[186:189], v[40:43]
	v_mfma_f32_16x16x32_bf16 v[28:31], v[134:137], v[194:197], v[28:31]
	v_mfma_f32_16x16x32_bf16 v[24:27], v[142:145], v[194:197], v[24:27]
	v_mfma_f32_16x16x32_bf16 v[12:15], v[134:137], v[202:205], v[12:15]
	v_mfma_f32_16x16x32_bf16 v[8:11], v[142:145], v[202:205], v[8:11]
	v_mfma_f32_16x16x32_bf16 v[60:63], v[138:141], v[182:185], v[60:63]
	v_mfma_f32_16x16x32_bf16 v[56:59], v[146:149], v[182:185], v[56:59]
	v_mfma_f32_16x16x32_bf16 v[44:47], v[138:141], v[190:193], v[44:47]
	v_mfma_f32_16x16x32_bf16 v[40:43], v[146:149], v[190:193], v[40:43]
	v_mfma_f32_16x16x32_bf16 v[28:31], v[138:141], v[198:201], v[28:31]
	v_mfma_f32_16x16x32_bf16 v[24:27], v[146:149], v[198:201], v[24:27]
	v_mfma_f32_16x16x32_bf16 v[12:15], v[138:141], v[206:209], v[12:15]
	v_mfma_f32_16x16x32_bf16 v[8:11], v[146:149], v[206:209], v[8:11]
	v_mfma_f32_16x16x32_bf16 v[52:55], v[150:153], v[178:181], v[52:55]
	v_mfma_f32_16x16x32_bf16 v[48:51], v[170:173], v[178:181], v[48:51]
	v_mfma_f32_16x16x32_bf16 v[36:39], v[150:153], v[186:189], v[36:39]
	v_mfma_f32_16x16x32_bf16 v[32:35], v[170:173], v[186:189], v[32:35]
	v_mfma_f32_16x16x32_bf16 v[20:23], v[150:153], v[194:197], v[20:23]
	v_mfma_f32_16x16x32_bf16 v[16:19], v[170:173], v[194:197], v[16:19]
	v_mfma_f32_16x16x32_bf16 v[4:7], v[150:153], v[202:205], v[4:7]
	v_mfma_f32_16x16x32_bf16 v[0:3], v[170:173], v[202:205], v[0:3]
	v_mfma_f32_16x16x32_bf16 v[52:55], v[166:169], v[182:185], v[52:55]
	v_mfma_f32_16x16x32_bf16 v[48:51], v[174:177], v[182:185], v[48:51]
	v_mfma_f32_16x16x32_bf16 v[36:39], v[166:169], v[190:193], v[36:39]
	v_mfma_f32_16x16x32_bf16 v[32:35], v[174:177], v[190:193], v[32:35]
	v_mfma_f32_16x16x32_bf16 v[20:23], v[166:169], v[198:201], v[20:23]
	v_mfma_f32_16x16x32_bf16 v[16:19], v[174:177], v[198:201], v[16:19]
	v_mfma_f32_16x16x32_bf16 v[4:7], v[166:169], v[206:209], v[4:7]
	v_mfma_f32_16x16x32_bf16 v[0:3], v[174:177], v[206:209], v[0:3]
	s_barrier
; #define PG8_LDA(dst, b, h) do { _Pragma("unroll") for (int m = 0; m < 4; ++m) _Pragma("unroll") for (int k = 0; k < 2; ++k) dst[m][k] = *(const LAS bf16x8*)(lds + PG8_SA(b, h) + aoff + m * 2048 + k * 1024); } while (0)
; #define PG8_LDB(dst, b, h) do { _Pragma("unroll") for (int n = 0; n < 2; ++n) _Pragma("unroll") for (int k = 0; k < 2; ++k) dst[n][k] = *(const LAS bf16x8*)(lds + PG8_SB(b, h) + boff + n * 2048 + k * 1024); } while (0)
; #define PG8_MMA(ai, bj, At, Bt) do { __builtin_amdgcn_s_setprio(1); _Pragma("unroll") for (int m = 0; m < 4; ++m) _Pragma("unroll") for (int n = 0; n < 2; ++n) _Pragma("unroll") for (int k = 0; k < 2; ++k) \
;         acc[ai][bj][m][n] = __builtin_amdgcn_mfma_f32_16x16x32_bf16(Bt[n][k], At[m][k], acc[ai][bj][m][n], 0, 0, 0); __builtin_amdgcn_s_setprio(0); } while (0)
; #define PG8_WAIT_V(n) asm volatile("s_waitcnt vmcnt(" #n ")" ::: "memory")
; #define PG8_WAIT_L(n) asm volatile("s_waitcnt lgkmcnt(" #n ")" ::: "memory")
; #define PG8_BAR __builtin_amdgcn_s_barrier()
; #define PG8_SCHED __builtin_amdgcn_sched_barrier(0)
; template <class Epi, class Addr, bool ALIGN_EPI = true, class Order = StaticOrder>
; __device__ __forceinline__ void gemm_phase(LAS unsigned char* lds, const Gemm g, const Order& S, const Epi& E, const int wid) {
;     ...
;             PG8_LDB(B0, 1, 0); PG8_LDB(B1, 1, 1); PG8_SCHED; PG8_LDA(At, 1, 0); PG8_STAGE(PG8_SA(0, 1), a2 + hstepA, voffA);
;             PG8_WAIT_V(8); PG8_WAIT_L(0); PG8_BAR; PG8_MMA(0, 0, At, B0); PG8_MMA(0, 1, At, B1); PG8_BAR; PG8_SCHED;
;             PG8_LDA(At, 1, 1); PG8_STAGE(PG8_SB(1, 0), b3, voffB); PG8_STAGE(PG8_SB(1, 1), b3 + hstepB, voffB); PG8_STAGE(PG8_SA(1, 0), a3, voffA);
;             PG8_WAIT_V(8); PG8_WAIT_L(0); PG8_BAR; PG8_MMA(1, 0, At, B0); PG8_MMA(1, 1, At, B1); PG8_BAR; PG8_SCHED;
;         }
	s_setprio 0
	ds_read_b128 v[134:137], v163
	ds_read_b128 v[138:141], v163 offset:1024
	ds_read_b128 v[142:145], v163 offset:2048
	ds_read_b128 v[146:149], v163 offset:3072
	ds_read_b128 v[150:153], v164
	ds_read_b128 v[166:169], v164 offset:1024
	ds_read_b128 v[170:173], v164 offset:2048
	ds_read_b128 v[174:177], v164 offset:3072
	ds_read_b128 v[178:181], v162 offset:32768
	ds_read_b128 v[182:185], v162 offset:33792
	ds_read_b128 v[186:189], v162 offset:34816
	ds_read_b128 v[190:193], v162 offset:35840
	ds_read_b128 v[194:197], v162 offset:36864
	ds_read_b128 v[198:201], v162 offset:37888
	ds_read_b128 v[202:205], v162 offset:38912
	ds_read_b128 v[206:209], v162 offset:39936
	s_add_u32 s18, s56, 0x100000
	s_addc_u32 s19, s57, 0
	s_mov_b32 s36, m0
	s_mov_b32 m0, s62
	s_nop 0
	global_load_lds_dwordx4 v156, s[18:19]
	s_mov_b32 m0, s63
	s_nop 0
	global_load_lds_dwordx4 v157, s[18:19]
	s_mov_b32 m0, s36
	s_waitcnt vmcnt(8)
	s_waitcnt lgkmcnt(0)
	s_setprio 1
	s_barrier
	v_mfma_f32_16x16x32_bf16 v[124:127], v[134:137], v[178:181], v[124:127]
	v_mfma_f32_16x16x32_bf16 v[120:123], v[142:145], v[178:181], v[120:123]
	v_mfma_f32_16x16x32_bf16 v[108:111], v[134:137], v[186:189], v[108:111]
	v_mfma_f32_16x16x32_bf16 v[104:107], v[142:145], v[186:189], v[104:107]
	v_mfma_f32_16x16x32_bf16 v[92:95], v[134:137], v[194:197], v[92:95]
	v_mfma_f32_16x16x32_bf16 v[88:91], v[142:145], v[194:197], v[88:91]
	v_mfma_f32_16x16x32_bf16 v[76:79], v[134:137], v[202:205], v[76:79]
	v_mfma_f32_16x16x32_bf16 v[72:75], v[142:145], v[202:205], v[72:75]
	v_mfma_f32_16x16x32_bf16 v[124:127], v[138:141], v[182:185], v[124:127]
	v_mfma_f32_16x16x32_bf16 v[120:123], v[146:149], v[182:185], v[120:123]
	v_mfma_f32_16x16x32_bf16 v[108:111], v[138:141], v[190:193], v[108:111]
	v_mfma_f32_16x16x32_bf16 v[104:107], v[146:149], v[190:193], v[104:107]
	v_mfma_f32_16x16x32_bf16 v[92:95], v[138:141], v[198:201], v[92:95]
	v_mfma_f32_16x16x32_bf16 v[88:91], v[146:149], v[198:201], v[88:91]
	v_mfma_f32_16x16x32_bf16 v[76:79], v[138:141], v[206:209], v[76:79]
	v_mfma_f32_16x16x32_bf16 v[72:75], v[146:149], v[206:209], v[72:75]
	v_mfma_f32_16x16x32_bf16 v[116:119], v[150:153], v[178:181], v[116:119]
	v_mfma_f32_16x16x32_bf16 v[112:115], v[170:173], v[178:181], v[112:115]
	v_mfma_f32_16x16x32_bf16 v[100:103], v[150:153], v[186:189], v[100:103]
	v_mfma_f32_16x16x32_bf16 v[96:99], v[170:173], v[186:189], v[96:99]
	v_mfma_f32_16x16x32_bf16 v[84:87], v[150:153], v[194:197], v[84:87]
	v_mfma_f32_16x16x32_bf16 v[80:83], v[170:173], v[194:197], v[80:83]
	v_mfma_f32_16x16x32_bf16 v[68:71], v[150:153], v[202:205], v[68:71]
	v_mfma_f32_16x16x32_bf16 v[64:67], v[170:173], v[202:205], v[64:67]
	v_mfma_f32_16x16x32_bf16 v[116:119], v[166:169], v[182:185], v[116:119]
	v_mfma_f32_16x16x32_bf16 v[112:115], v[174:177], v[182:185], v[112:115]
	v_mfma_f32_16x16x32_bf16 v[100:103], v[166:169], v[190:193], v[100:103]
	v_mfma_f32_16x16x32_bf16 v[96:99], v[174:177], v[190:193], v[96:99]
	v_mfma_f32_16x16x32_bf16 v[84:87], v[166:169], v[198:201], v[84:87]
	v_mfma_f32_16x16x32_bf16 v[80:83], v[174:177], v[198:201], v[80:83]
	v_mfma_f32_16x16x32_bf16 v[68:71], v[166:169], v[206:209], v[68:71]
	v_mfma_f32_16x16x32_bf16 v[64:67], v[174:177], v[206:209], v[64:67]
	s_barrier
	s_setprio 0
	ds_read_b128 v[178:181], v162 offset:49152
	ds_read_b128 v[182:185], v162 offset:50176
	ds_read_b128 v[186:189], v162 offset:51200
	ds_read_b128 v[190:193], v162 offset:52224
	ds_read_b128 v[194:197], v162 offset:53248
	ds_read_b128 v[198:201], v162 offset:54272
	ds_read_b128 v[202:205], v162 offset:55296
	ds_read_b128 v[206:209], v162 offset:56320
	s_add_u32 s18, s54, 0x80
	s_addc_u32 s19, s55, 0
	s_mov_b32 s36, m0
	s_mov_b32 m0, s66
	s_nop 0
	global_load_lds_dwordx4 v156, s[18:19]
	s_mov_b32 m0, s67
	s_nop 0
	global_load_lds_dwordx4 v157, s[18:19]
	s_mov_b32 m0, s36
	s_add_u32 s18, s54, 0x100080
	s_addc_u32 s19, s55, 0
	s_mov_b32 s36, m0
	s_mov_b32 m0, s70
	s_nop 0
	global_load_lds_dwordx4 v156, s[18:19]
	s_mov_b32 m0, s71
	s_nop 0
	global_load_lds_dwordx4 v157, s[18:19]
	s_mov_b32 m0, s36
	s_mov_b32 s18, m0
	s_mov_b32 m0, s68
	s_nop 0
	global_load_lds_dwordx4 v156, s[52:53]
	s_mov_b32 m0, s69
	s_nop 0
	global_load_lds_dwordx4 v157, s[52:53]
	s_mov_b32 m0, s18
	s_waitcnt vmcnt(8)
	s_waitcnt lgkmcnt(0)
	s_setprio 1
	s_barrier
	v_mfma_f32_16x16x32_bf16 v[60:63], v[134:137], v[178:181], v[60:63]
	v_mfma_f32_16x16x32_bf16 v[56:59], v[142:145], v[178:181], v[56:59]
	v_mfma_f32_16x16x32_bf16 v[44:47], v[134:137], v[186:189], v[44:47]
	v_mfma_f32_16x16x32_bf16 v[40:43], v[142:145], v[186:189], v[40:43]
	v_mfma_f32_16x16x32_bf16 v[28:31], v[134:137], v[194:197], v[28:31]
	v_mfma_f32_16x16x32_bf16 v[24:27], v[142:145], v[194:197], v[24:27]
	v_mfma_f32_16x16x32_bf16 v[12:15], v[134:137], v[202:205], v[12:15]
	v_mfma_f32_16x16x32_bf16 v[8:11], v[142:145], v[202:205], v[8:11]
	v_mfma_f32_16x16x32_bf16 v[60:63], v[138:141], v[182:185], v[60:63]
	v_mfma_f32_16x16x32_bf16 v[56:59], v[146:149], v[182:185], v[56:59]
	v_mfma_f32_16x16x32_bf16 v[44:47], v[138:141], v[190:193], v[44:47]
	v_mfma_f32_16x16x32_bf16 v[40:43], v[146:149], v[190:193], v[40:43]
	v_mfma_f32_16x16x32_bf16 v[28:31], v[138:141], v[198:201], v[28:31]
	v_mfma_f32_16x16x32_bf16 v[24:27], v[146:149], v[198:201], v[24:27]
	v_mfma_f32_16x16x32_bf16 v[12:15], v[138:141], v[206:209], v[12:15]
	v_mfma_f32_16x16x32_bf16 v[8:11], v[146:149], v[206:209], v[8:11]
	v_mfma_f32_16x16x32_bf16 v[52:55], v[150:153], v[178:181], v[52:55]
	v_mfma_f32_16x16x32_bf16 v[48:51], v[170:173], v[178:181], v[48:51]
	v_mfma_f32_16x16x32_bf16 v[36:39], v[150:153], v[186:189], v[36:39]
	v_mfma_f32_16x16x32_bf16 v[32:35], v[170:173], v[186:189], v[32:35]
	v_mfma_f32_16x16x32_bf16 v[20:23], v[150:153], v[194:197], v[20:23]
	v_mfma_f32_16x16x32_bf16 v[16:19], v[170:173], v[194:197], v[16:19]
	v_mfma_f32_16x16x32_bf16 v[4:7], v[150:153], v[202:205], v[4:7]
	v_mfma_f32_16x16x32_bf16 v[0:3], v[170:173], v[202:205], v[0:3]
	v_mfma_f32_16x16x32_bf16 v[52:55], v[166:169], v[182:185], v[52:55]
	v_mfma_f32_16x16x32_bf16 v[48:51], v[174:177], v[182:185], v[48:51]
	v_mfma_f32_16x16x32_bf16 v[36:39], v[166:169], v[190:193], v[36:39]
	v_mfma_f32_16x16x32_bf16 v[32:35], v[174:177], v[190:193], v[32:35]
	v_mfma_f32_16x16x32_bf16 v[20:23], v[166:169], v[198:201], v[20:23]
	v_mfma_f32_16x16x32_bf16 v[16:19], v[174:177], v[198:201], v[16:19]
	v_mfma_f32_16x16x32_bf16 v[4:7], v[166:169], v[206:209], v[4:7]
	v_mfma_f32_16x16x32_bf16 v[0:3], v[174:177], v[206:209], v[0:3]
	s_barrier
	s_setprio 0
	s_add_i32 s77, s77, 2
	s_add_u32 s75, s75, 0x100
	s_addc_u32 s76, s76, 0
	s_cmp_gt_u32 s77, 61
	s_mov_b64 s[48:49], s[50:51]
	s_cbranch_scc0 .LBB0_814
	s_and_b64 vcc, exec, s[14:15]
	s_cbranch_vccz .LBB0_817
	s_barrier

; #define PG8_LDA(dst, b, h) do { _Pragma("unroll") for (int m = 0; m < 4; ++m) _Pragma("unroll") for (int k = 0; k < 2; ++k) dst[m][k] = *(const LAS bf16x8*)(lds + PG8_SA(b, h) + aoff + m * 2048 + k * 1024); } while (0)
; #define PG8_LDB(dst, b, h) do { _Pragma("unroll") for (int n = 0; n < 2; ++n) _Pragma("unroll") for (int k = 0; k < 2; ++k) dst[n][k] = *(const LAS bf16x8*)(lds + PG8_SB(b, h) + boff + n * 2048 + k * 1024); } while (0)
; #define PG8_WAIT_V(n) asm volatile("s_waitcnt vmcnt(" #n ")" ::: "memory")
; #define PG8_WAIT_L(n) asm volatile("s_waitcnt lgkmcnt(" #n ")" ::: "memory")
; #define PG8_BAR __builtin_amdgcn_s_barrier()
; template <class Epi, class Addr, bool ALIGN_EPI = true, class Order = StaticOrder>
; __device__ __forceinline__ void gemm_phase(LAS unsigned char* lds, const Gemm g, const Order& S, const Epi& E, const int wid) {
;     ...
;         for (int t = 0; t < nt; t += 2) {
;             const bool last = (t == nt - 2);
;             const char* a1 = cA + (size_t)(t + 1) * kstep;
;             const char* a2 = last ? nA : cA + (size_t)(t + 2) * kstep; const char* b2 = last ? nB : cB + (size_t)(t + 2) * kstep;
;             const char* a3 = a2 + kstep; const char* b3 = b2 + kstep;
;             PG8_LDB(B0, 0, 0); PG8_LDB(B1, 0, 1); PG8_SCHED; PG8_LDA(At, 0, 0); PG8_STAGE(PG8_SA(1, 1), a1 + hstepA, voffA);
;             PG8_WAIT_V(8); PG8_WAIT_L(0); PG8_BAR; PG8_MMA(0, 0, At, B0); PG8_MMA(0, 1, At, B1); PG8_BAR; PG8_SCHED;
;             PG8_LDA(At, 0, 1); PG8_STAGE(PG8_SB(0, 0), b2, voffB); PG8_STAGE(PG8_SB(0, 1), b2 + hstepB, voffB); PG8_STAGE(PG8_SA(0, 0), a2, voffA);
;             PG8_WAIT_V(8); PG8_WAIT_L(0); PG8_BAR; PG8_MMA(1, 0, At, B0); PG8_MMA(1, 1, At, B1); PG8_BAR; PG8_SCHED;
;             PG8_LDB(B0, 1, 0); PG8_LDB(B1, 1, 1); PG8_SCHED; PG8_LDA(At, 1, 0); PG8_STAGE(PG8_SA(0, 1), a2 + hstepA, voffA);
;             PG8_WAIT_V(8); PG8_WAIT_L(0); PG8_BAR; PG8_MMA(0, 0, At, B0); PG8_MMA(0, 1, At, B1); PG8_BAR; PG8_SCHED;
;             PG8_LDA(At, 1, 1); PG8_STAGE(PG8_SB(1, 0), b3, voffB); PG8_STAGE(PG8_SB(1, 1), b3 + hstepB, voffB); PG8_STAGE(PG8_SA(1, 0), a3, voffA);
;             PG8_WAIT_V(8); PG8_WAIT_L(0); PG8_BAR; PG8_MMA(1, 0, At, B0); PG8_MMA(1, 1, At, B1); PG8_BAR; PG8_SCHED;
;         }
;         if constexpr (ALIGN_EPI) { if (wr == 0) PG8_BAR; }
;         E(acc, cur, wr, wc, fr, fq);
.LBB0_951:
	ds_read_b128 v[120:123], v200
	ds_read_b128 v[132:135], v200 offset:1024
	ds_read_b128 v[136:139], v200 offset:2048
	ds_read_b128 v[140:143], v200 offset:3072
	ds_read_b128 v[144:147], v201
	ds_read_b128 v[148:151], v201 offset:1024
	ds_read_b128 v[152:155], v201 offset:2048
	ds_read_b128 v[156:159], v201 offset:3072
	s_add_u32 s14, s12, 0x100
	s_addc_u32 s15, s13, 0
	s_cmp_eq_u32 s18, 60
	s_cselect_b32 s76, s67, s14
	s_cselect_b32 s77, s11, s15
	s_cselect_b32 s74, s73, vcc_lo
	s_cselect_b32 s75, s65, vcc_hi
	s_add_u32 s16, s76, 0x80
	s_addc_u32 s17, s77, 0
	ds_read_b128 v[160:163], v202
	ds_read_b128 v[164:167], v202 offset:1024
	ds_read_b128 v[168:171], v202 offset:2048
	ds_read_b128 v[172:175], v202 offset:3072
	ds_read_b128 v[186:189], v202 offset:4096
	ds_read_b128 v[208:211], v202 offset:5120
	ds_read_b128 v[212:215], v202 offset:6144
	ds_read_b128 v[216:219], v202 offset:7168
	s_add_u32 s12, s12, 0x100080
	s_addc_u32 s13, s13, 0
	s_mov_b32 s19, m0
	s_mov_b32 m0, s96
	s_nop 0
	global_load_lds_dwordx4 v190, s[12:13]
	s_mov_b32 m0, s97
	s_nop 0
	global_load_lds_dwordx4 v192, s[12:13]
	s_mov_b32 m0, s19
	s_waitcnt vmcnt(8)
	s_waitcnt lgkmcnt(0)
	s_setprio 1
	s_barrier
	v_mfma_f32_16x16x32_bf16 v[128:131], v[120:123], v[160:163], v[128:131]
	v_mfma_f32_16x16x32_bf16 v[56:59], v[136:139], v[160:163], v[56:59]
	v_mfma_f32_16x16x32_bf16 v[116:119], v[120:123], v[168:171], v[116:119]
	v_mfma_f32_16x16x32_bf16 v[40:43], v[136:139], v[168:171], v[40:43]
	v_mfma_f32_16x16x32_bf16 v[108:111], v[120:123], v[186:189], v[108:111]
	v_mfma_f32_16x16x32_bf16 v[52:55], v[136:139], v[186:189], v[52:55]
	v_mfma_f32_16x16x32_bf16 v[104:107], v[120:123], v[212:215], v[104:107]
	v_mfma_f32_16x16x32_bf16 v[32:35], v[136:139], v[212:215], v[32:35]
	v_mfma_f32_16x16x32_bf16 v[128:131], v[132:135], v[164:167], v[128:131]
	v_mfma_f32_16x16x32_bf16 v[56:59], v[140:143], v[164:167], v[56:59]
	v_mfma_f32_16x16x32_bf16 v[116:119], v[132:135], v[172:175], v[116:119]
	v_mfma_f32_16x16x32_bf16 v[40:43], v[140:143], v[172:175], v[40:43]
	v_mfma_f32_16x16x32_bf16 v[108:111], v[132:135], v[208:211], v[108:111]
	v_mfma_f32_16x16x32_bf16 v[52:55], v[140:143], v[208:211], v[52:55]
	v_mfma_f32_16x16x32_bf16 v[104:107], v[132:135], v[216:219], v[104:107]
	v_mfma_f32_16x16x32_bf16 v[32:35], v[140:143], v[216:219], v[32:35]
	v_mfma_f32_16x16x32_bf16 v[124:127], v[144:147], v[160:163], v[124:127]
	v_mfma_f32_16x16x32_bf16 v[60:63], v[152:155], v[160:163], v[60:63]
	v_mfma_f32_16x16x32_bf16 v[112:115], v[144:147], v[168:171], v[112:115]
	v_mfma_f32_16x16x32_bf16 v[44:47], v[152:155], v[168:171], v[44:47]
	v_mfma_f32_16x16x32_bf16 v[100:103], v[144:147], v[186:189], v[100:103]
	v_mfma_f32_16x16x32_bf16 v[48:51], v[152:155], v[186:189], v[48:51]
	v_mfma_f32_16x16x32_bf16 v[96:99], v[144:147], v[212:215], v[96:99]
	v_mfma_f32_16x16x32_bf16 v[36:39], v[152:155], v[212:215], v[36:39]
	v_mfma_f32_16x16x32_bf16 v[124:127], v[148:151], v[164:167], v[124:127]
	v_mfma_f32_16x16x32_bf16 v[60:63], v[156:159], v[164:167], v[60:63]
	v_mfma_f32_16x16x32_bf16 v[112:115], v[148:151], v[172:175], v[112:115]
	v_mfma_f32_16x16x32_bf16 v[44:47], v[156:159], v[172:175], v[44:47]
	v_mfma_f32_16x16x32_bf16 v[100:103], v[148:151], v[208:211], v[100:103]
	v_mfma_f32_16x16x32_bf16 v[48:51], v[156:159], v[208:211], v[48:51]
	v_mfma_f32_16x16x32_bf16 v[96:99], v[148:151], v[216:219], v[96:99]
	v_mfma_f32_16x16x32_bf16 v[36:39], v[156:159], v[216:219], v[36:39]
	s_barrier
	s_setprio 0
	ds_read_b128 v[160:163], v202 offset:16384
	ds_read_b128 v[164:167], v202 offset:17408
	ds_read_b128 v[168:171], v202 offset:18432
	ds_read_b128 v[172:175], v202 offset:19456
	ds_read_b128 v[186:189], v202 offset:20480
	ds_read_b128 v[208:211], v202 offset:21504
	ds_read_b128 v[212:215], v202 offset:22528
	ds_read_b128 v[216:219], v202 offset:23552
	s_mov_b32 s12, m0
	s_mov_b32 m0, s80
	s_nop 0
	global_load_lds_dwordx4 v191, s[74:75]
	s_mov_b32 m0, s81
	s_nop 0
	global_load_lds_dwordx4 v193, s[74:75]
	s_mov_b32 m0, s12
	s_add_u32 s12, s74, 0x100000
	s_addc_u32 s13, s75, 0
	s_mov_b32 s19, m0
	s_mov_b32 m0, s82
	s_nop 0
	global_load_lds_dwordx4 v191, s[12:13]
	s_mov_b32 m0, s83
	s_nop 0
	global_load_lds_dwordx4 v193, s[12:13]
	s_mov_b32 m0, s19
	s_mov_b32 s12, m0
	s_mov_b32 m0, s79
	s_nop 0
	global_load_lds_dwordx4 v190, s[76:77]
	s_mov_b32 m0, s84
	s_nop 0
	global_load_lds_dwordx4 v192, s[76:77]
	s_mov_b32 m0, s12
	s_waitcnt vmcnt(8)
	s_waitcnt lgkmcnt(0)
	s_setprio 1
	s_barrier
	v_mfma_f32_16x16x32_bf16 v[92:95], v[120:123], v[160:163], v[92:95]
	v_mfma_f32_16x16x32_bf16 v[24:27], v[136:139], v[160:163], v[24:27]
	v_mfma_f32_16x16x32_bf16 v[84:87], v[120:123], v[168:171], v[84:87]
	v_mfma_f32_16x16x32_bf16 v[20:23], v[136:139], v[168:171], v[20:23]
	v_mfma_f32_16x16x32_bf16 v[76:79], v[120:123], v[186:189], v[76:79]
	v_mfma_f32_16x16x32_bf16 v[0:3], v[136:139], v[186:189], v[0:3]
	v_mfma_f32_16x16x32_bf16 v[72:75], v[120:123], v[212:215], v[72:75]
	v_mfma_f32_16x16x32_bf16 v[8:11], v[136:139], v[212:215], v[8:11]
	v_mfma_f32_16x16x32_bf16 v[92:95], v[132:135], v[164:167], v[92:95]
	v_mfma_f32_16x16x32_bf16 v[24:27], v[140:143], v[164:167], v[24:27]
	v_mfma_f32_16x16x32_bf16 v[84:87], v[132:135], v[172:175], v[84:87]
	v_mfma_f32_16x16x32_bf16 v[20:23], v[140:143], v[172:175], v[20:23]
	v_mfma_f32_16x16x32_bf16 v[76:79], v[132:135], v[208:211], v[76:79]
	v_mfma_f32_16x16x32_bf16 v[0:3], v[140:143], v[208:211], v[0:3]
	v_mfma_f32_16x16x32_bf16 v[72:75], v[132:135], v[216:219], v[72:75]
	v_mfma_f32_16x16x32_bf16 v[8:11], v[140:143], v[216:219], v[8:11]
	v_mfma_f32_16x16x32_bf16 v[88:91], v[144:147], v[160:163], v[88:91]
	v_mfma_f32_16x16x32_bf16 v[28:31], v[152:155], v[160:163], v[28:31]
	v_mfma_f32_16x16x32_bf16 v[80:83], v[144:147], v[168:171], v[80:83]
	v_mfma_f32_16x16x32_bf16 v[16:19], v[152:155], v[168:171], v[16:19]
	v_mfma_f32_16x16x32_bf16 v[68:71], v[144:147], v[186:189], v[68:71]
	v_mfma_f32_16x16x32_bf16 v[4:7], v[152:155], v[186:189], v[4:7]
	v_mfma_f32_16x16x32_bf16 v[64:67], v[144:147], v[212:215], v[64:67]
	v_mfma_f32_16x16x32_bf16 v[12:15], v[152:155], v[212:215], v[12:15]
	v_mfma_f32_16x16x32_bf16 v[88:91], v[148:151], v[164:167], v[88:91]
	v_mfma_f32_16x16x32_bf16 v[28:31], v[156:159], v[164:167], v[28:31]
	v_mfma_f32_16x16x32_bf16 v[80:83], v[148:151], v[172:175], v[80:83]
	v_mfma_f32_16x16x32_bf16 v[16:19], v[156:159], v[172:175], v[16:19]
	v_mfma_f32_16x16x32_bf16 v[68:71], v[148:151], v[208:211], v[68:71]
	v_mfma_f32_16x16x32_bf16 v[4:7], v[156:159], v[208:211], v[4:7]
	v_mfma_f32_16x16x32_bf16 v[64:67], v[148:151], v[216:219], v[64:67]
	v_mfma_f32_16x16x32_bf16 v[12:15], v[156:159], v[216:219], v[12:15]
	s_barrier
; #define PG8_LDA(dst, b, h) do { _Pragma("unroll") for (int m = 0; m < 4; ++m) _Pragma("unroll") for (int k = 0; k < 2; ++k) dst[m][k] = *(const LAS bf16x8*)(lds + PG8_SA(b, h) + aoff + m * 2048 + k * 1024); } while (0)
; #define PG8_LDB(dst, b, h) do { _Pragma("unroll") for (int n = 0; n < 2; ++n) _Pragma("unroll") for (int k = 0; k < 2; ++k) dst[n][k] = *(const LAS bf16x8*)(lds + PG8_SB(b, h) + boff + n * 2048 + k * 1024); } while (0)
; #define PG8_MMA(ai, bj, At, Bt) do { __builtin_amdgcn_s_setprio(1); _Pragma("unroll") for (int m = 0; m < 4; ++m) _Pragma("unroll") for (int n = 0; n < 2; ++n) _Pragma("unroll") for (int k = 0; k < 2; ++k) \
;         acc[ai][bj][m][n] = __builtin_amdgcn_mfma_f32_16x16x32_bf16(Bt[n][k], At[m][k], acc[ai][bj][m][n], 0, 0, 0); __builtin_amdgcn_s_setprio(0); } while (0)
; #define PG8_WAIT_V(n) asm volatile("s_waitcnt vmcnt(" #n ")" ::: "memory")
; #define PG8_WAIT_L(n) asm volatile("s_waitcnt lgkmcnt(" #n ")" ::: "memory")
; #define PG8_BAR __builtin_amdgcn_s_barrier()
; #define PG8_SCHED __builtin_amdgcn_sched_barrier(0)
; template <class Epi, class Addr, bool ALIGN_EPI = true, class Order = StaticOrder>
; __device__ __forceinline__ void gemm_phase(LAS unsigned char* lds, const Gemm g, const Order& S, const Epi& E, const int wid) {
;     ...
;             PG8_LDB(B0, 1, 0); PG8_LDB(B1, 1, 1); PG8_SCHED; PG8_LDA(At, 1, 0); PG8_STAGE(PG8_SA(0, 1), a2 + hstepA, voffA);
;             PG8_WAIT_V(8); PG8_WAIT_L(0); PG8_BAR; PG8_MMA(0, 0, At, B0); PG8_MMA(0, 1, At, B1); PG8_BAR; PG8_SCHED;
;             PG8_LDA(At, 1, 1); PG8_STAGE(PG8_SB(1, 0), b3, voffB); PG8_STAGE(PG8_SB(1, 1), b3 + hstepB, voffB); PG8_STAGE(PG8_SA(1, 0), a3, voffA);
;             PG8_WAIT_V(8); PG8_WAIT_L(0); PG8_BAR; PG8_MMA(1, 0, At, B0); PG8_MMA(1, 1, At, B1); PG8_BAR; PG8_SCHED;
;         }
	s_setprio 0
	ds_read_b128 v[120:123], v203
	ds_read_b128 v[132:135], v203 offset:1024
	ds_read_b128 v[136:139], v203 offset:2048
	ds_read_b128 v[140:143], v203 offset:3072
	ds_read_b128 v[144:147], v204
	ds_read_b128 v[148:151], v204 offset:1024
	ds_read_b128 v[152:155], v204 offset:2048
	ds_read_b128 v[156:159], v204 offset:3072
	ds_read_b128 v[160:163], v202 offset:32768
	ds_read_b128 v[164:167], v202 offset:33792
	ds_read_b128 v[168:171], v202 offset:34816
	ds_read_b128 v[172:175], v202 offset:35840
	ds_read_b128 v[186:189], v202 offset:36864
	ds_read_b128 v[208:211], v202 offset:37888
	ds_read_b128 v[212:215], v202 offset:38912
	ds_read_b128 v[216:219], v202 offset:39936
	s_add_u32 s12, s76, 0x100000
	s_addc_u32 s13, s77, 0
	s_mov_b32 s19, m0
	s_mov_b32 m0, s85
	s_nop 0
	global_load_lds_dwordx4 v190, s[12:13]
	s_mov_b32 m0, s86
	s_nop 0
	global_load_lds_dwordx4 v192, s[12:13]
	s_mov_b32 m0, s19
	s_waitcnt vmcnt(8)
	s_waitcnt lgkmcnt(0)
	s_setprio 1
	s_barrier
	v_mfma_f32_16x16x32_bf16 v[128:131], v[120:123], v[160:163], v[128:131]
	v_mfma_f32_16x16x32_bf16 v[56:59], v[136:139], v[160:163], v[56:59]
	v_mfma_f32_16x16x32_bf16 v[116:119], v[120:123], v[168:171], v[116:119]
	v_mfma_f32_16x16x32_bf16 v[40:43], v[136:139], v[168:171], v[40:43]
	v_mfma_f32_16x16x32_bf16 v[108:111], v[120:123], v[186:189], v[108:111]
	v_mfma_f32_16x16x32_bf16 v[52:55], v[136:139], v[186:189], v[52:55]
	v_mfma_f32_16x16x32_bf16 v[104:107], v[120:123], v[212:215], v[104:107]
	v_mfma_f32_16x16x32_bf16 v[32:35], v[136:139], v[212:215], v[32:35]
	v_mfma_f32_16x16x32_bf16 v[128:131], v[132:135], v[164:167], v[128:131]
	v_mfma_f32_16x16x32_bf16 v[56:59], v[140:143], v[164:167], v[56:59]
	v_mfma_f32_16x16x32_bf16 v[116:119], v[132:135], v[172:175], v[116:119]
	v_mfma_f32_16x16x32_bf16 v[40:43], v[140:143], v[172:175], v[40:43]
	v_mfma_f32_16x16x32_bf16 v[108:111], v[132:135], v[208:211], v[108:111]
	v_mfma_f32_16x16x32_bf16 v[52:55], v[140:143], v[208:211], v[52:55]
	v_mfma_f32_16x16x32_bf16 v[104:107], v[132:135], v[216:219], v[104:107]
	v_mfma_f32_16x16x32_bf16 v[32:35], v[140:143], v[216:219], v[32:35]
	v_mfma_f32_16x16x32_bf16 v[124:127], v[144:147], v[160:163], v[124:127]
	v_mfma_f32_16x16x32_bf16 v[60:63], v[152:155], v[160:163], v[60:63]
	v_mfma_f32_16x16x32_bf16 v[112:115], v[144:147], v[168:171], v[112:115]
	v_mfma_f32_16x16x32_bf16 v[44:47], v[152:155], v[168:171], v[44:47]
	v_mfma_f32_16x16x32_bf16 v[100:103], v[144:147], v[186:189], v[100:103]
	v_mfma_f32_16x16x32_bf16 v[48:51], v[152:155], v[186:189], v[48:51]
	v_mfma_f32_16x16x32_bf16 v[96:99], v[144:147], v[212:215], v[96:99]
	v_mfma_f32_16x16x32_bf16 v[36:39], v[152:155], v[212:215], v[36:39]
	v_mfma_f32_16x16x32_bf16 v[124:127], v[148:151], v[164:167], v[124:127]
	v_mfma_f32_16x16x32_bf16 v[60:63], v[156:159], v[164:167], v[60:63]
	v_mfma_f32_16x16x32_bf16 v[112:115], v[148:151], v[172:175], v[112:115]
	v_mfma_f32_16x16x32_bf16 v[44:47], v[156:159], v[172:175], v[44:47]
	v_mfma_f32_16x16x32_bf16 v[100:103], v[148:151], v[208:211], v[100:103]
	v_mfma_f32_16x16x32_bf16 v[48:51], v[156:159], v[208:211], v[48:51]
	v_mfma_f32_16x16x32_bf16 v[96:99], v[148:151], v[216:219], v[96:99]
	v_mfma_f32_16x16x32_bf16 v[36:39], v[156:159], v[216:219], v[36:39]
	s_barrier
	s_setprio 0
	ds_read_b128 v[160:163], v202 offset:49152
	ds_read_b128 v[164:167], v202 offset:50176
	ds_read_b128 v[168:171], v202 offset:51200
	ds_read_b128 v[172:175], v202 offset:52224
	ds_read_b128 v[186:189], v202 offset:53248
	ds_read_b128 v[208:211], v202 offset:54272
	ds_read_b128 v[212:215], v202 offset:55296
	ds_read_b128 v[216:219], v202 offset:56320
	s_add_u32 s12, s74, 0x80
	s_addc_u32 s13, s75, 0
	s_mov_b32 s19, m0
	s_mov_b32 m0, s89
	s_nop 0
	global_load_lds_dwordx4 v191, s[12:13]
	s_mov_b32 m0, s90
	s_nop 0
	global_load_lds_dwordx4 v193, s[12:13]
	s_mov_b32 m0, s19
	s_add_u32 s12, s74, 0x100080
	s_addc_u32 s13, s75, 0
	s_mov_b32 s19, m0
	s_mov_b32 m0, s94
	s_nop 0
	global_load_lds_dwordx4 v191, s[12:13]
	s_mov_b32 m0, s95
	s_nop 0
	global_load_lds_dwordx4 v193, s[12:13]
	s_mov_b32 m0, s19
	s_mov_b32 s12, m0
	s_mov_b32 m0, s91
	s_nop 0
	global_load_lds_dwordx4 v190, s[16:17]
	s_mov_b32 m0, s93
	s_nop 0
	global_load_lds_dwordx4 v192, s[16:17]
	s_mov_b32 m0, s12
	s_waitcnt vmcnt(8)
	s_waitcnt lgkmcnt(0)
	s_setprio 1
	s_barrier
	v_mfma_f32_16x16x32_bf16 v[92:95], v[120:123], v[160:163], v[92:95]
	v_mfma_f32_16x16x32_bf16 v[24:27], v[136:139], v[160:163], v[24:27]
	v_mfma_f32_16x16x32_bf16 v[84:87], v[120:123], v[168:171], v[84:87]
	v_mfma_f32_16x16x32_bf16 v[20:23], v[136:139], v[168:171], v[20:23]
	v_mfma_f32_16x16x32_bf16 v[76:79], v[120:123], v[186:189], v[76:79]
	v_mfma_f32_16x16x32_bf16 v[0:3], v[136:139], v[186:189], v[0:3]
	v_mfma_f32_16x16x32_bf16 v[72:75], v[120:123], v[212:215], v[72:75]
	v_mfma_f32_16x16x32_bf16 v[8:11], v[136:139], v[212:215], v[8:11]
	v_mfma_f32_16x16x32_bf16 v[92:95], v[132:135], v[164:167], v[92:95]
	v_mfma_f32_16x16x32_bf16 v[24:27], v[140:143], v[164:167], v[24:27]
	v_mfma_f32_16x16x32_bf16 v[84:87], v[132:135], v[172:175], v[84:87]
	v_mfma_f32_16x16x32_bf16 v[20:23], v[140:143], v[172:175], v[20:23]
	v_mfma_f32_16x16x32_bf16 v[76:79], v[132:135], v[208:211], v[76:79]
	v_mfma_f32_16x16x32_bf16 v[0:3], v[140:143], v[208:211], v[0:3]
	v_mfma_f32_16x16x32_bf16 v[72:75], v[132:135], v[216:219], v[72:75]
	v_mfma_f32_16x16x32_bf16 v[8:11], v[140:143], v[216:219], v[8:11]
	v_mfma_f32_16x16x32_bf16 v[88:91], v[144:147], v[160:163], v[88:91]
	v_mfma_f32_16x16x32_bf16 v[28:31], v[152:155], v[160:163], v[28:31]
	v_mfma_f32_16x16x32_bf16 v[80:83], v[144:147], v[168:171], v[80:83]
	v_mfma_f32_16x16x32_bf16 v[16:19], v[152:155], v[168:171], v[16:19]
	v_mfma_f32_16x16x32_bf16 v[68:71], v[144:147], v[186:189], v[68:71]
	v_mfma_f32_16x16x32_bf16 v[4:7], v[152:155], v[186:189], v[4:7]
	v_mfma_f32_16x16x32_bf16 v[64:67], v[144:147], v[212:215], v[64:67]
	v_mfma_f32_16x16x32_bf16 v[12:15], v[152:155], v[212:215], v[12:15]
	v_mfma_f32_16x16x32_bf16 v[88:91], v[148:151], v[164:167], v[88:91]
	v_mfma_f32_16x16x32_bf16 v[28:31], v[156:159], v[164:167], v[28:31]
	v_mfma_f32_16x16x32_bf16 v[80:83], v[148:151], v[172:175], v[80:83]
	v_mfma_f32_16x16x32_bf16 v[16:19], v[156:159], v[172:175], v[16:19]
	v_mfma_f32_16x16x32_bf16 v[68:71], v[148:151], v[208:211], v[68:71]
	v_mfma_f32_16x16x32_bf16 v[4:7], v[156:159], v[208:211], v[4:7]
	v_mfma_f32_16x16x32_bf16 v[64:67], v[148:151], v[216:219], v[64:67]
	v_mfma_f32_16x16x32_bf16 v[12:15], v[156:159], v[216:219], v[12:15]
	s_barrier
	s_setprio 0
	s_add_i32 s18, s18, 2
	s_add_u32 vcc_lo, vcc_lo, 0x100
	s_addc_u32 vcc_hi, vcc_hi, 0
	s_cmp_gt_u32 s18, 61
	s_mov_b64 s[12:13], s[14:15]
	s_cbranch_scc0 .LBB0_951
	s_and_b64 vcc, exec, s[4:5]
	s_cbranch_vccz .LBB0_995
	s_barrier
	v_cmp_gt_i32_e32 vcc, 15, v194
	s_mov_b64 s[14:15], -1
	s_and_saveexec_b64 s[12:13], vcc
	s_cbranch_execnz .LBB0_996

; #define PG8_LDA(dst, b, h) do { _Pragma("unroll") for (int m = 0; m < 4; ++m) _Pragma("unroll") for (int k = 0; k < 2; ++k) dst[m][k] = *(const LAS bf16x8*)(lds + PG8_SA(b, h) + aoff + m * 2048 + k * 1024); } while (0)
; #define PG8_LDB(dst, b, h) do { _Pragma("unroll") for (int n = 0; n < 2; ++n) _Pragma("unroll") for (int k = 0; k < 2; ++k) dst[n][k] = *(const LAS bf16x8*)(lds + PG8_SB(b, h) + boff + n * 2048 + k * 1024); } while (0)
; #define PG8_MMA(ai, bj, At, Bt) do { __builtin_amdgcn_s_setprio(1); _Pragma("unroll") for (int m = 0; m < 4; ++m) _Pragma("unroll") for (int n = 0; n < 2; ++n) _Pragma("unroll") for (int k = 0; k < 2; ++k) \
;         acc[ai][bj][m][n] = __builtin_amdgcn_mfma_f32_16x16x32_bf16(Bt[n][k], At[m][k], acc[ai][bj][m][n], 0, 0, 0); __builtin_amdgcn_s_setprio(0); } while (0)
; #define PG8_WAIT_V(n) asm volatile("s_waitcnt vmcnt(" #n ")" ::: "memory")
; #define PG8_WAIT_L(n) asm volatile("s_waitcnt lgkmcnt(" #n ")" ::: "memory")
; #define PG8_BAR __builtin_amdgcn_s_barrier()
; template <class Epi, class Addr, bool ALIGN_EPI = true, class Order = StaticOrder>
; __device__ __forceinline__ void gemm_phase(LAS unsigned char* lds, const Gemm g, const Order& S, const Epi& E, const int wid) {
;     ...
;         for (int t = 0; t < nt; t += 2) {
;             const bool last = (t == nt - 2);
;             const char* a1 = cA + (size_t)(t + 1) * kstep;
;             const char* a2 = last ? nA : cA + (size_t)(t + 2) * kstep; const char* b2 = last ? nB : cB + (size_t)(t + 2) * kstep;
;             const char* a3 = a2 + kstep; const char* b3 = b2 + kstep;
;             PG8_LDB(B0, 0, 0); PG8_LDB(B1, 0, 1); PG8_SCHED; PG8_LDA(At, 0, 0); PG8_STAGE(PG8_SA(1, 1), a1 + hstepA, voffA);
;             PG8_WAIT_V(8); PG8_WAIT_L(0); PG8_BAR; PG8_MMA(0, 0, At, B0); PG8_MMA(0, 1, At, B1); PG8_BAR; PG8_SCHED;
;             PG8_LDA(At, 0, 1); PG8_STAGE(PG8_SB(0, 0), b2, voffB); PG8_STAGE(PG8_SB(0, 1), b2 + hstepB, voffB); PG8_STAGE(PG8_SA(0, 0), a2, voffA);
;             PG8_WAIT_V(8); PG8_WAIT_L(0); PG8_BAR; PG8_MMA(1, 0, At, B0); PG8_MMA(1, 1, At, B1); PG8_BAR; PG8_SCHED;
;             PG8_LDB(B0, 1, 0); PG8_LDB(B1, 1, 1); PG8_SCHED; PG8_LDA(At, 1, 0); PG8_STAGE(PG8_SA(0, 1), a2 + hstepA, voffA);
;             PG8_WAIT_V(8); PG8_WAIT_L(0); PG8_BAR; PG8_MMA(0, 0, At, B0); PG8_MMA(0, 1, At, B1); PG8_BAR; PG8_SCHED;
.LBB0_1144:
	ds_read_b128 v[134:137], v160
	ds_read_b128 v[138:141], v160 offset:1024
	ds_read_b128 v[142:145], v160 offset:2048
	ds_read_b128 v[146:149], v160 offset:3072
	ds_read_b128 v[150:153], v161
	ds_read_b128 v[166:169], v161 offset:1024
	ds_read_b128 v[170:173], v161 offset:2048
	ds_read_b128 v[174:177], v161 offset:3072
	s_add_u32 s42, s24, 0x100
	s_addc_u32 s43, s25, 0
	s_cmpk_eq_i32 s18, 0xa8
	s_cselect_b32 s48, s6, s42
	s_cselect_b32 s49, s7, s43
	s_cselect_b32 s46, s20, s23
	s_cselect_b32 s47, s21, s27
	s_add_u32 s44, s48, 0x80
	s_addc_u32 s45, s49, 0
	ds_read_b128 v[178:181], v162
	ds_read_b128 v[182:185], v162 offset:1024
	ds_read_b128 v[186:189], v162 offset:2048
	ds_read_b128 v[190:193], v162 offset:3072
	ds_read_b128 v[194:197], v162 offset:4096
	ds_read_b128 v[198:201], v162 offset:5120
	ds_read_b128 v[202:205], v162 offset:6144
	ds_read_b128 v[206:209], v162 offset:7168
	s_add_u32 s24, s24, 0x2b0080
	s_addc_u32 s25, s25, 0
	s_mov_b32 s19, m0
	s_mov_b32 m0, s67
	s_nop 0
	global_load_lds_dwordx4 v156, s[24:25]
	s_mov_b32 m0, s68
	s_nop 0
	global_load_lds_dwordx4 v157, s[24:25]
	s_mov_b32 m0, s19
	s_waitcnt vmcnt(8)
	s_waitcnt lgkmcnt(0)
	s_setprio 1
	s_barrier
	v_mfma_f32_16x16x32_bf16 v[124:127], v[134:137], v[178:181], v[124:127]
	v_mfma_f32_16x16x32_bf16 v[120:123], v[142:145], v[178:181], v[120:123]
	v_mfma_f32_16x16x32_bf16 v[108:111], v[134:137], v[186:189], v[108:111]
	v_mfma_f32_16x16x32_bf16 v[104:107], v[142:145], v[186:189], v[104:107]
	v_mfma_f32_16x16x32_bf16 v[92:95], v[134:137], v[194:197], v[92:95]
	v_mfma_f32_16x16x32_bf16 v[88:91], v[142:145], v[194:197], v[88:91]
	v_mfma_f32_16x16x32_bf16 v[76:79], v[134:137], v[202:205], v[76:79]
	v_mfma_f32_16x16x32_bf16 v[72:75], v[142:145], v[202:205], v[72:75]
	v_mfma_f32_16x16x32_bf16 v[124:127], v[138:141], v[182:185], v[124:127]
	v_mfma_f32_16x16x32_bf16 v[120:123], v[146:149], v[182:185], v[120:123]
	v_mfma_f32_16x16x32_bf16 v[108:111], v[138:141], v[190:193], v[108:111]
	v_mfma_f32_16x16x32_bf16 v[104:107], v[146:149], v[190:193], v[104:107]
	v_mfma_f32_16x16x32_bf16 v[92:95], v[138:141], v[198:201], v[92:95]
	v_mfma_f32_16x16x32_bf16 v[88:91], v[146:149], v[198:201], v[88:91]
	v_mfma_f32_16x16x32_bf16 v[76:79], v[138:141], v[206:209], v[76:79]
	v_mfma_f32_16x16x32_bf16 v[72:75], v[146:149], v[206:209], v[72:75]
	v_mfma_f32_16x16x32_bf16 v[116:119], v[150:153], v[178:181], v[116:119]
	v_mfma_f32_16x16x32_bf16 v[112:115], v[170:173], v[178:181], v[112:115]
	v_mfma_f32_16x16x32_bf16 v[100:103], v[150:153], v[186:189], v[100:103]
	v_mfma_f32_16x16x32_bf16 v[96:99], v[170:173], v[186:189], v[96:99]
	v_mfma_f32_16x16x32_bf16 v[84:87], v[150:153], v[194:197], v[84:87]
	v_mfma_f32_16x16x32_bf16 v[80:83], v[170:173], v[194:197], v[80:83]
	v_mfma_f32_16x16x32_bf16 v[68:71], v[150:153], v[202:205], v[68:71]
	v_mfma_f32_16x16x32_bf16 v[64:67], v[170:173], v[202:205], v[64:67]
	v_mfma_f32_16x16x32_bf16 v[116:119], v[166:169], v[182:185], v[116:119]
	v_mfma_f32_16x16x32_bf16 v[112:115], v[174:177], v[182:185], v[112:115]
	v_mfma_f32_16x16x32_bf16 v[100:103], v[166:169], v[190:193], v[100:103]
	v_mfma_f32_16x16x32_bf16 v[96:99], v[174:177], v[190:193], v[96:99]
	v_mfma_f32_16x16x32_bf16 v[84:87], v[166:169], v[198:201], v[84:87]
	v_mfma_f32_16x16x32_bf16 v[80:83], v[174:177], v[198:201], v[80:83]
	v_mfma_f32_16x16x32_bf16 v[68:71], v[166:169], v[206:209], v[68:71]
	v_mfma_f32_16x16x32_bf16 v[64:67], v[174:177], v[206:209], v[64:67]
	s_barrier
	s_setprio 0
	ds_read_b128 v[178:181], v162 offset:16384
	ds_read_b128 v[182:185], v162 offset:17408
	ds_read_b128 v[186:189], v162 offset:18432
	ds_read_b128 v[190:193], v162 offset:19456
	ds_read_b128 v[194:197], v162 offset:20480
	ds_read_b128 v[198:201], v162 offset:21504
	ds_read_b128 v[202:205], v162 offset:22528
	ds_read_b128 v[206:209], v162 offset:23552
	s_mov_b32 s19, m0
	s_mov_b32 m0, s40
	s_nop 0
	global_load_lds_dwordx4 v156, s[46:47]
	s_mov_b32 m0, s41
	s_nop 0
	global_load_lds_dwordx4 v157, s[46:47]
	s_mov_b32 m0, s19
	s_add_u32 s24, s46, 0x2b0000
	s_addc_u32 s25, s47, 0
	s_mov_b32 s19, m0
	s_mov_b32 m0, s50
	s_nop 0
	global_load_lds_dwordx4 v156, s[24:25]
	s_mov_b32 m0, s51
	s_nop 0
	global_load_lds_dwordx4 v157, s[24:25]
	s_mov_b32 m0, s19
	s_nop 0
	s_mov_b32 s19, m0
	s_mov_b32 m0, s39
	s_nop 0
	global_load_lds_dwordx4 v156, s[48:49]
	s_mov_b32 m0, s52
	s_nop 0
	global_load_lds_dwordx4 v157, s[48:49]
	s_mov_b32 m0, s19
	s_waitcnt vmcnt(8)
	s_waitcnt lgkmcnt(0)
	s_setprio 1
	s_barrier
	v_mfma_f32_16x16x32_bf16 v[60:63], v[134:137], v[178:181], v[60:63]
	v_mfma_f32_16x16x32_bf16 v[56:59], v[142:145], v[178:181], v[56:59]
	v_mfma_f32_16x16x32_bf16 v[44:47], v[134:137], v[186:189], v[44:47]
	v_mfma_f32_16x16x32_bf16 v[40:43], v[142:145], v[186:189], v[40:43]
	v_mfma_f32_16x16x32_bf16 v[28:31], v[134:137], v[194:197], v[28:31]
	v_mfma_f32_16x16x32_bf16 v[24:27], v[142:145], v[194:197], v[24:27]
	v_mfma_f32_16x16x32_bf16 v[12:15], v[134:137], v[202:205], v[12:15]
	v_mfma_f32_16x16x32_bf16 v[8:11], v[142:145], v[202:205], v[8:11]
	v_mfma_f32_16x16x32_bf16 v[60:63], v[138:141], v[182:185], v[60:63]
	v_mfma_f32_16x16x32_bf16 v[56:59], v[146:149], v[182:185], v[56:59]
	v_mfma_f32_16x16x32_bf16 v[44:47], v[138:141], v[190:193], v[44:47]
	v_mfma_f32_16x16x32_bf16 v[40:43], v[146:149], v[190:193], v[40:43]
	v_mfma_f32_16x16x32_bf16 v[28:31], v[138:141], v[198:201], v[28:31]
	v_mfma_f32_16x16x32_bf16 v[24:27], v[146:149], v[198:201], v[24:27]
	v_mfma_f32_16x16x32_bf16 v[12:15], v[138:141], v[206:209], v[12:15]
	v_mfma_f32_16x16x32_bf16 v[8:11], v[146:149], v[206:209], v[8:11]
	v_mfma_f32_16x16x32_bf16 v[52:55], v[150:153], v[178:181], v[52:55]
	v_mfma_f32_16x16x32_bf16 v[48:51], v[170:173], v[178:181], v[48:51]
	v_mfma_f32_16x16x32_bf16 v[36:39], v[150:153], v[186:189], v[36:39]
	v_mfma_f32_16x16x32_bf16 v[32:35], v[170:173], v[186:189], v[32:35]
	v_mfma_f32_16x16x32_bf16 v[20:23], v[150:153], v[194:197], v[20:23]
	v_mfma_f32_16x16x32_bf16 v[16:19], v[170:173], v[194:197], v[16:19]
	v_mfma_f32_16x16x32_bf16 v[4:7], v[150:153], v[202:205], v[4:7]
	v_mfma_f32_16x16x32_bf16 v[0:3], v[170:173], v[202:205], v[0:3]
	v_mfma_f32_16x16x32_bf16 v[52:55], v[166:169], v[182:185], v[52:55]
	v_mfma_f32_16x16x32_bf16 v[48:51], v[174:177], v[182:185], v[48:51]
	v_mfma_f32_16x16x32_bf16 v[36:39], v[166:169], v[190:193], v[36:39]
	v_mfma_f32_16x16x32_bf16 v[32:35], v[174:177], v[190:193], v[32:35]
	v_mfma_f32_16x16x32_bf16 v[20:23], v[166:169], v[198:201], v[20:23]
	v_mfma_f32_16x16x32_bf16 v[16:19], v[174:177], v[198:201], v[16:19]
	v_mfma_f32_16x16x32_bf16 v[4:7], v[166:169], v[206:209], v[4:7]
	v_mfma_f32_16x16x32_bf16 v[0:3], v[174:177], v[206:209], v[0:3]
	s_barrier
; #define PG8_LDA(dst, b, h) do { _Pragma("unroll") for (int m = 0; m < 4; ++m) _Pragma("unroll") for (int k = 0; k < 2; ++k) dst[m][k] = *(const LAS bf16x8*)(lds + PG8_SA(b, h) + aoff + m * 2048 + k * 1024); } while (0)
; #define PG8_LDB(dst, b, h) do { _Pragma("unroll") for (int n = 0; n < 2; ++n) _Pragma("unroll") for (int k = 0; k < 2; ++k) dst[n][k] = *(const LAS bf16x8*)(lds + PG8_SB(b, h) + boff + n * 2048 + k * 1024); } while (0)
; #define PG8_MMA(ai, bj, At, Bt) do { __builtin_amdgcn_s_setprio(1); _Pragma("unroll") for (int m = 0; m < 4; ++m) _Pragma("unroll") for (int n = 0; n < 2; ++n) _Pragma("unroll") for (int k = 0; k < 2; ++k) \
;         acc[ai][bj][m][n] = __builtin_amdgcn_mfma_f32_16x16x32_bf16(Bt[n][k], At[m][k], acc[ai][bj][m][n], 0, 0, 0); __builtin_amdgcn_s_setprio(0); } while (0)
; #define PG8_WAIT_V(n) asm volatile("s_waitcnt vmcnt(" #n ")" ::: "memory")
; #define PG8_WAIT_L(n) asm volatile("s_waitcnt lgkmcnt(" #n ")" ::: "memory")
; #define PG8_BAR __builtin_amdgcn_s_barrier()
; #define PG8_SCHED __builtin_amdgcn_sched_barrier(0)
; template <class Epi, class Addr, bool ALIGN_EPI = true, class Order = StaticOrder>
; __device__ __forceinline__ void gemm_phase(LAS unsigned char* lds, const Gemm g, const Order& S, const Epi& E, const int wid) {
;     ...
;             PG8_LDB(B0, 0, 0); PG8_LDB(B1, 0, 1); PG8_SCHED; PG8_LDA(At, 0, 0); PG8_STAGE(PG8_SA(1, 1), a1 + hstepA, voffA);
;             PG8_WAIT_V(8); PG8_WAIT_L(0); PG8_BAR; PG8_MMA(0, 0, At, B0); PG8_MMA(0, 1, At, B1); PG8_BAR; PG8_SCHED;
;             PG8_LDA(At, 0, 1); PG8_STAGE(PG8_SB(0, 0), b2, voffB); PG8_STAGE(PG8_SB(0, 1), b2 + hstepB, voffB); PG8_STAGE(PG8_SA(0, 0), a2, voffA);
;             PG8_WAIT_V(8); PG8_WAIT_L(0); PG8_BAR; PG8_MMA(1, 0, At, B0); PG8_MMA(1, 1, At, B1); PG8_BAR; PG8_SCHED;
;             PG8_LDB(B0, 1, 0); PG8_LDB(B1, 1, 1); PG8_SCHED; PG8_LDA(At, 1, 0); PG8_STAGE(PG8_SA(0, 1), a2 + hstepA, voffA);
;             PG8_WAIT_V(8); PG8_WAIT_L(0); PG8_BAR; PG8_MMA(0, 0, At, B0); PG8_MMA(0, 1, At, B1); PG8_BAR; PG8_SCHED;
;             PG8_LDA(At, 1, 1); PG8_STAGE(PG8_SB(1, 0), b3, voffB); PG8_STAGE(PG8_SB(1, 1), b3 + hstepB, voffB); PG8_STAGE(PG8_SA(1, 0), a3, voffA);
;             PG8_WAIT_V(8); PG8_WAIT_L(0); PG8_BAR; PG8_MMA(1, 0, At, B0); PG8_MMA(1, 1, At, B1); PG8_BAR; PG8_SCHED;
;         }
	s_setprio 0
	ds_read_b128 v[134:137], v163
	ds_read_b128 v[138:141], v163 offset:1024
	ds_read_b128 v[142:145], v163 offset:2048
	ds_read_b128 v[146:149], v163 offset:3072
	ds_read_b128 v[150:153], v164
	ds_read_b128 v[166:169], v164 offset:1024
	ds_read_b128 v[170:173], v164 offset:2048
	ds_read_b128 v[174:177], v164 offset:3072
	ds_read_b128 v[178:181], v162 offset:32768
	ds_read_b128 v[182:185], v162 offset:33792
	ds_read_b128 v[186:189], v162 offset:34816
	ds_read_b128 v[190:193], v162 offset:35840
	ds_read_b128 v[194:197], v162 offset:36864
	ds_read_b128 v[198:201], v162 offset:37888
	ds_read_b128 v[202:205], v162 offset:38912
	ds_read_b128 v[206:209], v162 offset:39936
	s_add_u32 s24, s48, 0x2b0000
	s_addc_u32 s25, s49, 0
	s_mov_b32 s19, m0
	s_mov_b32 m0, s53
	s_nop 0
	global_load_lds_dwordx4 v156, s[24:25]
	s_mov_b32 m0, s54
	s_nop 0
	global_load_lds_dwordx4 v157, s[24:25]
	s_mov_b32 m0, s19
	s_waitcnt vmcnt(8)
	s_waitcnt lgkmcnt(0)
	s_setprio 1
	s_barrier
	v_mfma_f32_16x16x32_bf16 v[124:127], v[134:137], v[178:181], v[124:127]
	v_mfma_f32_16x16x32_bf16 v[120:123], v[142:145], v[178:181], v[120:123]
	v_mfma_f32_16x16x32_bf16 v[108:111], v[134:137], v[186:189], v[108:111]
	v_mfma_f32_16x16x32_bf16 v[104:107], v[142:145], v[186:189], v[104:107]
	v_mfma_f32_16x16x32_bf16 v[92:95], v[134:137], v[194:197], v[92:95]
	v_mfma_f32_16x16x32_bf16 v[88:91], v[142:145], v[194:197], v[88:91]
	v_mfma_f32_16x16x32_bf16 v[76:79], v[134:137], v[202:205], v[76:79]
	v_mfma_f32_16x16x32_bf16 v[72:75], v[142:145], v[202:205], v[72:75]
	v_mfma_f32_16x16x32_bf16 v[124:127], v[138:141], v[182:185], v[124:127]
	v_mfma_f32_16x16x32_bf16 v[120:123], v[146:149], v[182:185], v[120:123]
	v_mfma_f32_16x16x32_bf16 v[108:111], v[138:141], v[190:193], v[108:111]
	v_mfma_f32_16x16x32_bf16 v[104:107], v[146:149], v[190:193], v[104:107]
	v_mfma_f32_16x16x32_bf16 v[92:95], v[138:141], v[198:201], v[92:95]
	v_mfma_f32_16x16x32_bf16 v[88:91], v[146:149], v[198:201], v[88:91]
	v_mfma_f32_16x16x32_bf16 v[76:79], v[138:141], v[206:209], v[76:79]
	v_mfma_f32_16x16x32_bf16 v[72:75], v[146:149], v[206:209], v[72:75]
	v_mfma_f32_16x16x32_bf16 v[116:119], v[150:153], v[178:181], v[116:119]
	v_mfma_f32_16x16x32_bf16 v[112:115], v[170:173], v[178:181], v[112:115]
	v_mfma_f32_16x16x32_bf16 v[100:103], v[150:153], v[186:189], v[100:103]
	v_mfma_f32_16x16x32_bf16 v[96:99], v[170:173], v[186:189], v[96:99]
	v_mfma_f32_16x16x32_bf16 v[84:87], v[150:153], v[194:197], v[84:87]
	v_mfma_f32_16x16x32_bf16 v[80:83], v[170:173], v[194:197], v[80:83]
	v_mfma_f32_16x16x32_bf16 v[68:71], v[150:153], v[202:205], v[68:71]
	v_mfma_f32_16x16x32_bf16 v[64:67], v[170:173], v[202:205], v[64:67]
	v_mfma_f32_16x16x32_bf16 v[116:119], v[166:169], v[182:185], v[116:119]
	v_mfma_f32_16x16x32_bf16 v[112:115], v[174:177], v[182:185], v[112:115]
	v_mfma_f32_16x16x32_bf16 v[100:103], v[166:169], v[190:193], v[100:103]
	v_mfma_f32_16x16x32_bf16 v[96:99], v[174:177], v[190:193], v[96:99]
	v_mfma_f32_16x16x32_bf16 v[84:87], v[166:169], v[198:201], v[84:87]
	v_mfma_f32_16x16x32_bf16 v[80:83], v[174:177], v[198:201], v[80:83]
	v_mfma_f32_16x16x32_bf16 v[68:71], v[166:169], v[206:209], v[68:71]
	v_mfma_f32_16x16x32_bf16 v[64:67], v[174:177], v[206:209], v[64:67]
	s_barrier
	s_setprio 0
	ds_read_b128 v[178:181], v162 offset:49152
	ds_read_b128 v[182:185], v162 offset:50176
	ds_read_b128 v[186:189], v162 offset:51200
	ds_read_b128 v[190:193], v162 offset:52224
	ds_read_b128 v[194:197], v162 offset:53248
	ds_read_b128 v[198:201], v162 offset:54272
	ds_read_b128 v[202:205], v162 offset:55296
	ds_read_b128 v[206:209], v162 offset:56320
	s_add_u32 s24, s46, 0x80
	s_addc_u32 s25, s47, 0
	s_mov_b32 s19, m0
	s_mov_b32 m0, s59
	s_nop 0
	global_load_lds_dwordx4 v156, s[24:25]
	s_mov_b32 m0, s62
	s_nop 0
	global_load_lds_dwordx4 v157, s[24:25]
	s_mov_b32 m0, s19
	s_add_u32 s24, s46, 0x2b0080
	s_addc_u32 s25, s47, 0
	s_mov_b32 s19, m0
	s_mov_b32 m0, s65
	s_nop 0
	global_load_lds_dwordx4 v156, s[24:25]
	s_mov_b32 m0, s66
	s_nop 0
	global_load_lds_dwordx4 v157, s[24:25]
	s_mov_b32 m0, s19
	s_nop 0
	s_mov_b32 s19, m0
	s_mov_b32 m0, s63
	s_nop 0
	global_load_lds_dwordx4 v156, s[44:45]
	s_mov_b32 m0, s64
	s_nop 0
	global_load_lds_dwordx4 v157, s[44:45]
	s_mov_b32 m0, s19
	s_waitcnt vmcnt(8)
	s_waitcnt lgkmcnt(0)
	s_setprio 1
	s_barrier
	v_mfma_f32_16x16x32_bf16 v[60:63], v[134:137], v[178:181], v[60:63]
	v_mfma_f32_16x16x32_bf16 v[56:59], v[142:145], v[178:181], v[56:59]
	v_mfma_f32_16x16x32_bf16 v[44:47], v[134:137], v[186:189], v[44:47]
	v_mfma_f32_16x16x32_bf16 v[40:43], v[142:145], v[186:189], v[40:43]
	v_mfma_f32_16x16x32_bf16 v[28:31], v[134:137], v[194:197], v[28:31]
	v_mfma_f32_16x16x32_bf16 v[24:27], v[142:145], v[194:197], v[24:27]
	v_mfma_f32_16x16x32_bf16 v[12:15], v[134:137], v[202:205], v[12:15]
	v_mfma_f32_16x16x32_bf16 v[8:11], v[142:145], v[202:205], v[8:11]
	v_mfma_f32_16x16x32_bf16 v[60:63], v[138:141], v[182:185], v[60:63]
	v_mfma_f32_16x16x32_bf16 v[56:59], v[146:149], v[182:185], v[56:59]
	v_mfma_f32_16x16x32_bf16 v[44:47], v[138:141], v[190:193], v[44:47]
	v_mfma_f32_16x16x32_bf16 v[40:43], v[146:149], v[190:193], v[40:43]
	v_mfma_f32_16x16x32_bf16 v[28:31], v[138:141], v[198:201], v[28:31]
	v_mfma_f32_16x16x32_bf16 v[24:27], v[146:149], v[198:201], v[24:27]
	v_mfma_f32_16x16x32_bf16 v[12:15], v[138:141], v[206:209], v[12:15]
	v_mfma_f32_16x16x32_bf16 v[8:11], v[146:149], v[206:209], v[8:11]
	v_mfma_f32_16x16x32_bf16 v[52:55], v[150:153], v[178:181], v[52:55]
	v_mfma_f32_16x16x32_bf16 v[48:51], v[170:173], v[178:181], v[48:51]
	v_mfma_f32_16x16x32_bf16 v[36:39], v[150:153], v[186:189], v[36:39]
	v_mfma_f32_16x16x32_bf16 v[32:35], v[170:173], v[186:189], v[32:35]
	v_mfma_f32_16x16x32_bf16 v[20:23], v[150:153], v[194:197], v[20:23]
	v_mfma_f32_16x16x32_bf16 v[16:19], v[170:173], v[194:197], v[16:19]
	v_mfma_f32_16x16x32_bf16 v[4:7], v[150:153], v[202:205], v[4:7]
	v_mfma_f32_16x16x32_bf16 v[0:3], v[170:173], v[202:205], v[0:3]
	v_mfma_f32_16x16x32_bf16 v[52:55], v[166:169], v[182:185], v[52:55]
	v_mfma_f32_16x16x32_bf16 v[48:51], v[174:177], v[182:185], v[48:51]
	v_mfma_f32_16x16x32_bf16 v[36:39], v[166:169], v[190:193], v[36:39]
	v_mfma_f32_16x16x32_bf16 v[32:35], v[174:177], v[190:193], v[32:35]
	v_mfma_f32_16x16x32_bf16 v[20:23], v[166:169], v[198:201], v[20:23]
	v_mfma_f32_16x16x32_bf16 v[16:19], v[174:177], v[198:201], v[16:19]
	v_mfma_f32_16x16x32_bf16 v[4:7], v[166:169], v[206:209], v[4:7]
	v_mfma_f32_16x16x32_bf16 v[0:3], v[174:177], v[206:209], v[0:3]
	s_barrier
	s_setprio 0
	s_add_i32 s18, s18, 2
	s_add_u32 s23, s23, 0x100
	s_addc_u32 s27, s27, 0
	s_cmpk_gt_u32 s18, 0xa9
	s_mov_b64 s[24:25], s[42:43]
	s_cbranch_scc0 .LBB0_1144
	s_and_b64 vcc, exec, s[14:15]
	s_cbranch_vccz .LBB0_1147
	s_barrier

; #define PG8_LDA(dst, b, h) do { _Pragma("unroll") for (int m = 0; m < 4; ++m) _Pragma("unroll") for (int k = 0; k < 2; ++k) dst[m][k] = *(const LAS bf16x8*)(lds + PG8_SA(b, h) + aoff + m * 2048 + k * 1024); } while (0)
; #define PG8_LDB(dst, b, h) do { _Pragma("unroll") for (int n = 0; n < 2; ++n) _Pragma("unroll") for (int k = 0; k < 2; ++k) dst[n][k] = *(const LAS bf16x8*)(lds + PG8_SB(b, h) + boff + n * 2048 + k * 1024); } while (0)
; #define PG8_MMA(ai, bj, At, Bt) do { __builtin_amdgcn_s_setprio(1); _Pragma("unroll") for (int m = 0; m < 4; ++m) _Pragma("unroll") for (int n = 0; n < 2; ++n) _Pragma("unroll") for (int k = 0; k < 2; ++k) \
;         acc[ai][bj][m][n] = __builtin_amdgcn_mfma_f32_16x16x32_bf16(Bt[n][k], At[m][k], acc[ai][bj][m][n], 0, 0, 0); __builtin_amdgcn_s_setprio(0); } while (0)
; #define PG8_WAIT_V(n) asm volatile("s_waitcnt vmcnt(" #n ")" ::: "memory")
; #define PG8_WAIT_L(n) asm volatile("s_waitcnt lgkmcnt(" #n ")" ::: "memory")
; #define PG8_BAR __builtin_amdgcn_s_barrier()
; #define PG8_SCHED __builtin_amdgcn_sched_barrier(0)
; template <class Epi, class Addr, bool ALIGN_EPI = true, class Order = StaticOrder>
; __device__ __forceinline__ void gemm_phase(LAS unsigned char* lds, const Gemm g, const Order& S, const Epi& E, const int wid) {
;     ...
;             PG8_LDB(B0, 0, 0); PG8_LDB(B1, 0, 1); PG8_SCHED; PG8_LDA(At, 0, 0); PG8_STAGE(PG8_SA(1, 1), a1 + hstepA, voffA);
;             PG8_WAIT_V(8); PG8_WAIT_L(0); PG8_BAR; PG8_MMA(0, 0, At, B0); PG8_MMA(0, 1, At, B1); PG8_BAR; PG8_SCHED;
;             PG8_LDA(At, 0, 1); PG8_STAGE(PG8_SB(0, 0), b2, voffB); PG8_STAGE(PG8_SB(0, 1), b2 + hstepB, voffB); PG8_STAGE(PG8_SA(0, 0), a2, voffA);
;             PG8_WAIT_V(8); PG8_WAIT_L(0); PG8_BAR; PG8_MMA(1, 0, At, B0); PG8_MMA(1, 1, At, B1); PG8_BAR; PG8_SCHED;
.LBB0_1232:
	ds_read_b128 v[132:135], v236
	ds_read_b128 v[136:139], v236 offset:1024
	ds_read_b128 v[140:143], v236 offset:2048
	ds_read_b128 v[144:147], v236 offset:3072
	ds_read_b128 v[148:151], v237
	ds_read_b128 v[152:155], v237 offset:1024
	ds_read_b128 v[156:159], v237 offset:2048
	ds_read_b128 v[160:163], v237 offset:3072
	s_add_u32 s6, s40, 0x100
	s_addc_u32 s7, s41, 0
	s_cmpk_eq_i32 s18, 0xa8
	s_cselect_b32 s46, s24, s6
	s_cselect_b32 s47, s25, s7
	s_cselect_b32 s44, s26, s9
	s_cselect_b32 s45, s27, s39
	s_add_u32 s42, s46, 0x80
	s_addc_u32 s43, s47, 0
	ds_read_b128 v[164:167], v238
	ds_read_b128 v[168:171], v238 offset:1024
	ds_read_b128 v[172:175], v238 offset:2048
	ds_read_b128 v[176:179], v238 offset:3072
	ds_read_b128 v[180:183], v238 offset:4096
	ds_read_b128 v[184:187], v238 offset:5120
	ds_read_b128 v[188:191], v238 offset:6144
	ds_read_b128 v[192:195], v238 offset:7168
	s_add_u32 s36, s40, 0x2b0080
	s_addc_u32 s37, s41, 0
	s_mov_b32 s19, m0
	s_mov_b32 m0, s64
	s_nop 0
	global_load_lds_dwordx4 v234, s[36:37]
	s_mov_b32 m0, s65
	s_nop 0
	global_load_lds_dwordx4 v235, s[36:37]
	s_mov_b32 m0, s19
	s_waitcnt vmcnt(8)
	s_waitcnt lgkmcnt(0)
	s_setprio 1
	s_barrier
	v_mfma_f32_16x16x32_bf16 v[124:127], v[132:135], v[164:167], v[124:127]
	v_mfma_f32_16x16x32_bf16 v[120:123], v[140:143], v[164:167], v[120:123]
	v_mfma_f32_16x16x32_bf16 v[108:111], v[132:135], v[172:175], v[108:111]
	v_mfma_f32_16x16x32_bf16 v[104:107], v[140:143], v[172:175], v[104:107]
	v_mfma_f32_16x16x32_bf16 v[92:95], v[132:135], v[180:183], v[92:95]
	v_mfma_f32_16x16x32_bf16 v[88:91], v[140:143], v[180:183], v[88:91]
	v_mfma_f32_16x16x32_bf16 v[76:79], v[132:135], v[188:191], v[76:79]
	v_mfma_f32_16x16x32_bf16 v[72:75], v[140:143], v[188:191], v[72:75]
	v_mfma_f32_16x16x32_bf16 v[124:127], v[136:139], v[168:171], v[124:127]
	v_mfma_f32_16x16x32_bf16 v[120:123], v[144:147], v[168:171], v[120:123]
	v_mfma_f32_16x16x32_bf16 v[108:111], v[136:139], v[176:179], v[108:111]
	v_mfma_f32_16x16x32_bf16 v[104:107], v[144:147], v[176:179], v[104:107]
	v_mfma_f32_16x16x32_bf16 v[92:95], v[136:139], v[184:187], v[92:95]
	v_mfma_f32_16x16x32_bf16 v[88:91], v[144:147], v[184:187], v[88:91]
	v_mfma_f32_16x16x32_bf16 v[76:79], v[136:139], v[192:195], v[76:79]
	v_mfma_f32_16x16x32_bf16 v[72:75], v[144:147], v[192:195], v[72:75]
	v_mfma_f32_16x16x32_bf16 v[116:119], v[148:151], v[164:167], v[116:119]
	v_mfma_f32_16x16x32_bf16 v[112:115], v[156:159], v[164:167], v[112:115]
	v_mfma_f32_16x16x32_bf16 v[100:103], v[148:151], v[172:175], v[100:103]
	v_mfma_f32_16x16x32_bf16 v[96:99], v[156:159], v[172:175], v[96:99]
	v_mfma_f32_16x16x32_bf16 v[84:87], v[148:151], v[180:183], v[84:87]
	v_mfma_f32_16x16x32_bf16 v[80:83], v[156:159], v[180:183], v[80:83]
	v_mfma_f32_16x16x32_bf16 v[68:71], v[148:151], v[188:191], v[68:71]
	v_mfma_f32_16x16x32_bf16 v[64:67], v[156:159], v[188:191], v[64:67]
	v_mfma_f32_16x16x32_bf16 v[116:119], v[152:155], v[168:171], v[116:119]
	v_mfma_f32_16x16x32_bf16 v[112:115], v[160:163], v[168:171], v[112:115]
	v_mfma_f32_16x16x32_bf16 v[100:103], v[152:155], v[176:179], v[100:103]
	v_mfma_f32_16x16x32_bf16 v[96:99], v[160:163], v[176:179], v[96:99]
	v_mfma_f32_16x16x32_bf16 v[84:87], v[152:155], v[184:187], v[84:87]
	v_mfma_f32_16x16x32_bf16 v[80:83], v[160:163], v[184:187], v[80:83]
	v_mfma_f32_16x16x32_bf16 v[68:71], v[152:155], v[192:195], v[68:71]
	v_mfma_f32_16x16x32_bf16 v[64:67], v[160:163], v[192:195], v[64:67]
	s_barrier
	s_setprio 0
	ds_read_b128 v[164:167], v238 offset:16384
	ds_read_b128 v[168:171], v238 offset:17408
	ds_read_b128 v[172:175], v238 offset:18432
	ds_read_b128 v[176:179], v238 offset:19456
	ds_read_b128 v[180:183], v238 offset:20480
	ds_read_b128 v[184:187], v238 offset:21504
	ds_read_b128 v[188:191], v238 offset:22528
	ds_read_b128 v[192:195], v238 offset:23552
	s_mov_b32 s19, m0
	s_mov_b32 m0, s48
	s_nop 0
	global_load_lds_dwordx4 v234, s[44:45]
	s_mov_b32 m0, s49
	s_nop 0
	global_load_lds_dwordx4 v235, s[44:45]
	s_mov_b32 m0, s19
	s_add_u32 s36, s44, 0x2b0000
	s_addc_u32 s37, s45, 0
	s_mov_b32 s19, m0
	s_mov_b32 m0, s50
	s_nop 0
	global_load_lds_dwordx4 v234, s[36:37]
	s_mov_b32 m0, s51
	s_nop 0
	global_load_lds_dwordx4 v235, s[36:37]
	s_mov_b32 m0, s19
	s_nop 0
	s_mov_b32 s19, m0
	s_mov_b32 m0, s23
	s_nop 0
	global_load_lds_dwordx4 v234, s[46:47]
	s_mov_b32 m0, s52
	s_nop 0
	global_load_lds_dwordx4 v235, s[46:47]
	s_mov_b32 m0, s19
	s_waitcnt vmcnt(8)
	s_waitcnt lgkmcnt(0)
	s_setprio 1
	s_barrier
	v_mfma_f32_16x16x32_bf16 v[60:63], v[132:135], v[164:167], v[60:63]
	v_mfma_f32_16x16x32_bf16 v[56:59], v[140:143], v[164:167], v[56:59]
	v_mfma_f32_16x16x32_bf16 v[44:47], v[132:135], v[172:175], v[44:47]
	v_mfma_f32_16x16x32_bf16 v[40:43], v[140:143], v[172:175], v[40:43]
	v_mfma_f32_16x16x32_bf16 v[28:31], v[132:135], v[180:183], v[28:31]
	v_mfma_f32_16x16x32_bf16 v[24:27], v[140:143], v[180:183], v[24:27]
	v_mfma_f32_16x16x32_bf16 v[12:15], v[132:135], v[188:191], v[12:15]
	v_mfma_f32_16x16x32_bf16 v[8:11], v[140:143], v[188:191], v[8:11]
	v_mfma_f32_16x16x32_bf16 v[60:63], v[136:139], v[168:171], v[60:63]
	v_mfma_f32_16x16x32_bf16 v[56:59], v[144:147], v[168:171], v[56:59]
	v_mfma_f32_16x16x32_bf16 v[44:47], v[136:139], v[176:179], v[44:47]
	v_mfma_f32_16x16x32_bf16 v[40:43], v[144:147], v[176:179], v[40:43]
	v_mfma_f32_16x16x32_bf16 v[28:31], v[136:139], v[184:187], v[28:31]
	v_mfma_f32_16x16x32_bf16 v[24:27], v[144:147], v[184:187], v[24:27]
	v_mfma_f32_16x16x32_bf16 v[12:15], v[136:139], v[192:195], v[12:15]
	v_mfma_f32_16x16x32_bf16 v[8:11], v[144:147], v[192:195], v[8:11]
	v_mfma_f32_16x16x32_bf16 v[52:55], v[148:151], v[164:167], v[52:55]
	v_mfma_f32_16x16x32_bf16 v[48:51], v[156:159], v[164:167], v[48:51]
	v_mfma_f32_16x16x32_bf16 v[36:39], v[148:151], v[172:175], v[36:39]
	v_mfma_f32_16x16x32_bf16 v[32:35], v[156:159], v[172:175], v[32:35]
	v_mfma_f32_16x16x32_bf16 v[20:23], v[148:151], v[180:183], v[20:23]
	v_mfma_f32_16x16x32_bf16 v[16:19], v[156:159], v[180:183], v[16:19]
	v_mfma_f32_16x16x32_bf16 v[4:7], v[148:151], v[188:191], v[4:7]
	v_mfma_f32_16x16x32_bf16 v[0:3], v[156:159], v[188:191], v[0:3]
	v_mfma_f32_16x16x32_bf16 v[52:55], v[152:155], v[168:171], v[52:55]
	v_mfma_f32_16x16x32_bf16 v[48:51], v[160:163], v[168:171], v[48:51]
	v_mfma_f32_16x16x32_bf16 v[36:39], v[152:155], v[176:179], v[36:39]
	v_mfma_f32_16x16x32_bf16 v[32:35], v[160:163], v[176:179], v[32:35]
	v_mfma_f32_16x16x32_bf16 v[20:23], v[152:155], v[184:187], v[20:23]
	v_mfma_f32_16x16x32_bf16 v[16:19], v[160:163], v[184:187], v[16:19]
	v_mfma_f32_16x16x32_bf16 v[4:7], v[152:155], v[192:195], v[4:7]
	v_mfma_f32_16x16x32_bf16 v[0:3], v[160:163], v[192:195], v[0:3]
	s_barrier
; #define PG8_LDA(dst, b, h) do { _Pragma("unroll") for (int m = 0; m < 4; ++m) _Pragma("unroll") for (int k = 0; k < 2; ++k) dst[m][k] = *(const LAS bf16x8*)(lds + PG8_SA(b, h) + aoff + m * 2048 + k * 1024); } while (0)
; #define PG8_LDB(dst, b, h) do { _Pragma("unroll") for (int n = 0; n < 2; ++n) _Pragma("unroll") for (int k = 0; k < 2; ++k) dst[n][k] = *(const LAS bf16x8*)(lds + PG8_SB(b, h) + boff + n * 2048 + k * 1024); } while (0)
; #define PG8_MMA(ai, bj, At, Bt) do { __builtin_amdgcn_s_setprio(1); _Pragma("unroll") for (int m = 0; m < 4; ++m) _Pragma("unroll") for (int n = 0; n < 2; ++n) _Pragma("unroll") for (int k = 0; k < 2; ++k) \
;         acc[ai][bj][m][n] = __builtin_amdgcn_mfma_f32_16x16x32_bf16(Bt[n][k], At[m][k], acc[ai][bj][m][n], 0, 0, 0); __builtin_amdgcn_s_setprio(0); } while (0)
; #define PG8_WAIT_V(n) asm volatile("s_waitcnt vmcnt(" #n ")" ::: "memory")
; #define PG8_WAIT_L(n) asm volatile("s_waitcnt lgkmcnt(" #n ")" ::: "memory")
; #define PG8_BAR __builtin_amdgcn_s_barrier()
; #define PG8_SCHED __builtin_amdgcn_sched_barrier(0)
; template <class Epi, class Addr, bool ALIGN_EPI = true, class Order = StaticOrder>
; __device__ __forceinline__ void gemm_phase(LAS unsigned char* lds, const Gemm g, const Order& S, const Epi& E, const int wid) {
;     ...
;             PG8_LDB(B0, 1, 0); PG8_LDB(B1, 1, 1); PG8_SCHED; PG8_LDA(At, 1, 0); PG8_STAGE(PG8_SA(0, 1), a2 + hstepA, voffA);
;             PG8_WAIT_V(8); PG8_WAIT_L(0); PG8_BAR; PG8_MMA(0, 0, At, B0); PG8_MMA(0, 1, At, B1); PG8_BAR; PG8_SCHED;
;             PG8_LDA(At, 1, 1); PG8_STAGE(PG8_SB(1, 0), b3, voffB); PG8_STAGE(PG8_SB(1, 1), b3 + hstepB, voffB); PG8_STAGE(PG8_SA(1, 0), a3, voffA);
;             PG8_WAIT_V(8); PG8_WAIT_L(0); PG8_BAR; PG8_MMA(1, 0, At, B0); PG8_MMA(1, 1, At, B1); PG8_BAR; PG8_SCHED;
	s_setprio 0
	ds_read_b128 v[132:135], v239
	ds_read_b128 v[136:139], v239 offset:1024
	ds_read_b128 v[140:143], v239 offset:2048
	ds_read_b128 v[144:147], v239 offset:3072
	ds_read_b128 v[148:151], v240
	ds_read_b128 v[152:155], v240 offset:1024
	ds_read_b128 v[156:159], v240 offset:2048
	ds_read_b128 v[160:163], v240 offset:3072
	ds_read_b128 v[164:167], v238 offset:32768
	ds_read_b128 v[168:171], v238 offset:33792
	ds_read_b128 v[172:175], v238 offset:34816
	ds_read_b128 v[176:179], v238 offset:35840
	ds_read_b128 v[180:183], v238 offset:36864
	ds_read_b128 v[184:187], v238 offset:37888
	ds_read_b128 v[188:191], v238 offset:38912
	ds_read_b128 v[192:195], v238 offset:39936
	s_add_u32 s36, s46, 0x2b0000
	s_addc_u32 s37, s47, 0
	s_mov_b32 s19, m0
	s_mov_b32 m0, s53
	s_nop 0
	global_load_lds_dwordx4 v234, s[36:37]
	s_mov_b32 m0, s54
	s_nop 0
	global_load_lds_dwordx4 v235, s[36:37]
	s_mov_b32 m0, s19
	s_waitcnt vmcnt(8)
	s_waitcnt lgkmcnt(0)
	s_setprio 1
	s_barrier
	v_mfma_f32_16x16x32_bf16 v[124:127], v[132:135], v[164:167], v[124:127]
	v_mfma_f32_16x16x32_bf16 v[120:123], v[140:143], v[164:167], v[120:123]
	v_mfma_f32_16x16x32_bf16 v[108:111], v[132:135], v[172:175], v[108:111]
	v_mfma_f32_16x16x32_bf16 v[104:107], v[140:143], v[172:175], v[104:107]
	v_mfma_f32_16x16x32_bf16 v[92:95], v[132:135], v[180:183], v[92:95]
	v_mfma_f32_16x16x32_bf16 v[88:91], v[140:143], v[180:183], v[88:91]
	v_mfma_f32_16x16x32_bf16 v[76:79], v[132:135], v[188:191], v[76:79]
	v_mfma_f32_16x16x32_bf16 v[72:75], v[140:143], v[188:191], v[72:75]
	v_mfma_f32_16x16x32_bf16 v[124:127], v[136:139], v[168:171], v[124:127]
	v_mfma_f32_16x16x32_bf16 v[120:123], v[144:147], v[168:171], v[120:123]
	v_mfma_f32_16x16x32_bf16 v[108:111], v[136:139], v[176:179], v[108:111]
	v_mfma_f32_16x16x32_bf16 v[104:107], v[144:147], v[176:179], v[104:107]
	v_mfma_f32_16x16x32_bf16 v[92:95], v[136:139], v[184:187], v[92:95]
	v_mfma_f32_16x16x32_bf16 v[88:91], v[144:147], v[184:187], v[88:91]
	v_mfma_f32_16x16x32_bf16 v[76:79], v[136:139], v[192:195], v[76:79]
	v_mfma_f32_16x16x32_bf16 v[72:75], v[144:147], v[192:195], v[72:75]
	v_mfma_f32_16x16x32_bf16 v[116:119], v[148:151], v[164:167], v[116:119]
	v_mfma_f32_16x16x32_bf16 v[112:115], v[156:159], v[164:167], v[112:115]
	v_mfma_f32_16x16x32_bf16 v[100:103], v[148:151], v[172:175], v[100:103]
	v_mfma_f32_16x16x32_bf16 v[96:99], v[156:159], v[172:175], v[96:99]
	v_mfma_f32_16x16x32_bf16 v[84:87], v[148:151], v[180:183], v[84:87]
	v_mfma_f32_16x16x32_bf16 v[80:83], v[156:159], v[180:183], v[80:83]
	v_mfma_f32_16x16x32_bf16 v[68:71], v[148:151], v[188:191], v[68:71]
	v_mfma_f32_16x16x32_bf16 v[64:67], v[156:159], v[188:191], v[64:67]
	v_mfma_f32_16x16x32_bf16 v[116:119], v[152:155], v[168:171], v[116:119]
	v_mfma_f32_16x16x32_bf16 v[112:115], v[160:163], v[168:171], v[112:115]
	v_mfma_f32_16x16x32_bf16 v[100:103], v[152:155], v[176:179], v[100:103]
	v_mfma_f32_16x16x32_bf16 v[96:99], v[160:163], v[176:179], v[96:99]
	v_mfma_f32_16x16x32_bf16 v[84:87], v[152:155], v[184:187], v[84:87]
	v_mfma_f32_16x16x32_bf16 v[80:83], v[160:163], v[184:187], v[80:83]
	v_mfma_f32_16x16x32_bf16 v[68:71], v[152:155], v[192:195], v[68:71]
	v_mfma_f32_16x16x32_bf16 v[64:67], v[160:163], v[192:195], v[64:67]
	s_barrier
	s_setprio 0
	ds_read_b128 v[164:167], v238 offset:49152
	ds_read_b128 v[168:171], v238 offset:50176
	ds_read_b128 v[172:175], v238 offset:51200
	ds_read_b128 v[176:179], v238 offset:52224
	ds_read_b128 v[180:183], v238 offset:53248
	ds_read_b128 v[184:187], v238 offset:54272
	ds_read_b128 v[188:191], v238 offset:55296
	ds_read_b128 v[192:195], v238 offset:56320
	s_add_u32 s36, s44, 0x80
	s_addc_u32 s37, s45, 0
	s_mov_b32 s19, m0
	s_mov_b32 m0, s56
	s_nop 0
	global_load_lds_dwordx4 v234, s[36:37]
	s_mov_b32 m0, s57
	s_nop 0
	global_load_lds_dwordx4 v235, s[36:37]
	s_mov_b32 m0, s19
	s_add_u32 s36, s44, 0x2b0080
	s_addc_u32 s37, s45, 0
	s_mov_b32 s19, m0
	s_mov_b32 m0, s62
	s_nop 0
	global_load_lds_dwordx4 v234, s[36:37]
	s_mov_b32 m0, s63
	s_nop 0
	global_load_lds_dwordx4 v235, s[36:37]
	s_mov_b32 m0, s19
	s_nop 0
	s_mov_b32 s19, m0
	s_mov_b32 m0, s58
	s_nop 0
	global_load_lds_dwordx4 v234, s[42:43]
	s_mov_b32 m0, s59
	s_nop 0
	global_load_lds_dwordx4 v235, s[42:43]
	s_mov_b32 m0, s19
	s_waitcnt vmcnt(8)
	s_waitcnt lgkmcnt(0)
	s_setprio 1
	s_barrier
	v_mfma_f32_16x16x32_bf16 v[60:63], v[132:135], v[164:167], v[60:63]
	v_mfma_f32_16x16x32_bf16 v[56:59], v[140:143], v[164:167], v[56:59]
	v_mfma_f32_16x16x32_bf16 v[44:47], v[132:135], v[172:175], v[44:47]
	v_mfma_f32_16x16x32_bf16 v[40:43], v[140:143], v[172:175], v[40:43]
	v_mfma_f32_16x16x32_bf16 v[28:31], v[132:135], v[180:183], v[28:31]
	v_mfma_f32_16x16x32_bf16 v[24:27], v[140:143], v[180:183], v[24:27]
	v_mfma_f32_16x16x32_bf16 v[12:15], v[132:135], v[188:191], v[12:15]
	v_mfma_f32_16x16x32_bf16 v[8:11], v[140:143], v[188:191], v[8:11]
	v_mfma_f32_16x16x32_bf16 v[60:63], v[136:139], v[168:171], v[60:63]
	v_mfma_f32_16x16x32_bf16 v[56:59], v[144:147], v[168:171], v[56:59]
	v_mfma_f32_16x16x32_bf16 v[44:47], v[136:139], v[176:179], v[44:47]
	v_mfma_f32_16x16x32_bf16 v[40:43], v[144:147], v[176:179], v[40:43]
	v_mfma_f32_16x16x32_bf16 v[28:31], v[136:139], v[184:187], v[28:31]
	v_mfma_f32_16x16x32_bf16 v[24:27], v[144:147], v[184:187], v[24:27]
	v_mfma_f32_16x16x32_bf16 v[12:15], v[136:139], v[192:195], v[12:15]
	v_mfma_f32_16x16x32_bf16 v[8:11], v[144:147], v[192:195], v[8:11]
	v_mfma_f32_16x16x32_bf16 v[52:55], v[148:151], v[164:167], v[52:55]
	v_mfma_f32_16x16x32_bf16 v[48:51], v[156:159], v[164:167], v[48:51]
	v_mfma_f32_16x16x32_bf16 v[36:39], v[148:151], v[172:175], v[36:39]
	v_mfma_f32_16x16x32_bf16 v[32:35], v[156:159], v[172:175], v[32:35]
	v_mfma_f32_16x16x32_bf16 v[20:23], v[148:151], v[180:183], v[20:23]
	v_mfma_f32_16x16x32_bf16 v[16:19], v[156:159], v[180:183], v[16:19]
	v_mfma_f32_16x16x32_bf16 v[4:7], v[148:151], v[188:191], v[4:7]
	v_mfma_f32_16x16x32_bf16 v[0:3], v[156:159], v[188:191], v[0:3]
	v_mfma_f32_16x16x32_bf16 v[52:55], v[152:155], v[168:171], v[52:55]
	v_mfma_f32_16x16x32_bf16 v[48:51], v[160:163], v[168:171], v[48:51]
	v_mfma_f32_16x16x32_bf16 v[36:39], v[152:155], v[176:179], v[36:39]
	v_mfma_f32_16x16x32_bf16 v[32:35], v[160:163], v[176:179], v[32:35]
	v_mfma_f32_16x16x32_bf16 v[20:23], v[152:155], v[184:187], v[20:23]
	v_mfma_f32_16x16x32_bf16 v[16:19], v[160:163], v[184:187], v[16:19]
	v_mfma_f32_16x16x32_bf16 v[4:7], v[152:155], v[192:195], v[4:7]
	v_mfma_f32_16x16x32_bf16 v[0:3], v[160:163], v[192:195], v[0:3]
	s_barrier
	s_setprio 0
	s_add_i32 s18, s18, 2
	s_add_u32 s9, s9, 0x100
	s_addc_u32 s39, s39, 0
	s_cmpk_gt_u32 s18, 0xa9
	s_mov_b64 s[40:41], s[6:7]
	s_cbranch_scc0 .LBB0_1232
	s_and_b64 vcc, exec, s[16:17]
	s_cbranch_vccz .LBB0_1235
	s_barrier
